# adds LoRA gemm K-slice skip (zero blocks of WL not multiplied) and EpiLn bf16 stores widened; on top of sscan load hoist + EpiB16 dwordx4 stores
# speedup vs baseline: 1.0325x; 1.0127x over previous
; __device__ __forceinline__ unsigned cvt_pk_bf16(float lo, float hi) { unsigned r; asm volatile("v_cvt_pk_bf16_f32 %0, %1, %2" : "=v"(r) : "v"(lo), "v"(hi)); return r; }
;     __device__ __forceinline__ void fused(f32x4 (&acc)[2][2][4][2], const Unit& u, int wr, int wc, int fr, int fq, PG8_LAS unsigned char* lds, int wid, int lane) const {
;     ...
;         const float qnan = __builtin_nanf("");
; #pragma unroll
;         for (int bj = 0; bj < 2; ++bj)
; #pragma unroll
;             for (int n = 0; n < 2; ++n) { const f32x4 gv = *(const f32x4*)(g + col0 + bj * HALF + n * 16), bv = *(const f32x4*)(b + col0 + bj * HALF + n * 16);
; #pragma unroll
;                 for (int ai = 0; ai < 2; ++ai)
; #pragma unroll
;                     for (int m = 0; m < 4; ++m) { const int r = ai * HALF + wr * 64 + m * 16 + fr; const f32x2v sr = S[r]; const size_t o = (size_t)(rowoff + u.pm * BM + r) * ldc + col0 + bj * HALF + n * 16;
;                         f32x4 v = (acc[ai][bj][m][n] - sr.x) * sr.y * gv + bv; if (bad) v = (f32x4){qnan, qnan, qnan, qnan};
;                         if (outf) *(f32x4*)(outf + o) = v; else { u32x2 w; w.x = cvt_pk_bf16(v[0], v[1]); w.y = cvt_pk_bf16(v[2], v[3]); *(u32x2*)(outb + o) = w; } } }
.LBB0_299:
	s_or_b64 exec, exec, s[6:7]
	v_and_b32_e32 v252, 16, v186
	v_lshrrev_b32_e32 v253, 1, v252
	v_add_u32_e32 v252, v252, v253
	v_add_u32_e32 v138, v138, v252
	v_lshlrev_b64 v[134:135], 2, v[130:131]
	s_waitcnt lgkmcnt(0)
	s_barrier
	v_lshl_add_u64 v[140:141], s[16:17], 0, v[134:135]
	v_lshl_add_u64 v[142:143], s[14:15], 0, v[134:135]
	global_load_dwordx4 v[130:133], v[140:141], off
	global_load_dwordx4 v[134:137], v[142:143], off
	v_lshl_add_u32 v148, v1, 3, 0
	ds_read_b64 v[150:151], v148 offset:8192
	v_add_u32_e32 v146, s28, v1
	v_mov_b32_e32 v1, 0x7fc00000
	s_waitcnt lgkmcnt(1)
	v_cmp_eq_u32_e32 vcc, 0, v144
	v_ashrrev_i32_e32 v147, 31, v146
	s_waitcnt lgkmcnt(0)
	v_sub_f32_e32 v107, v107, v150
	v_sub_f32_e32 v106, v106, v150
	v_sub_f32_e32 v109, v109, v150
	v_sub_f32_e32 v108, v108, v150
	v_pk_mul_f32 v[108:109], v[150:151], v[108:109] op_sel:[1,0]
	v_pk_mul_f32 v[106:107], v[150:151], v[106:107] op_sel:[1,0]
	v_readlane_b32 s4, v254, 13
	v_lshlrev_b64 v[162:163], 11, v[146:147]
	v_readlane_b32 s5, v254, 14
	v_add_u32_e32 v152, 16, v146
	v_ashrrev_i32_e32 v153, 31, v152
	v_lshl_add_u64 v[144:145], s[4:5], 0, v[162:163]
	v_lshl_add_u64 v[144:145], v[144:145], 0, v[138:139]
	v_add_u32_e32 v154, 32, v146
	v_ashrrev_i32_e32 v155, 31, v154
	v_add_u32_e32 v156, 48, v146
	v_ashrrev_i32_e32 v157, 31, v156
	v_add_u32_e32 v158, 0x80, v146
	v_ashrrev_i32_e32 v159, 31, v158
	v_add_u32_e32 v160, 0x90, v146
	v_ashrrev_i32_e32 v161, 31, v160
	s_waitcnt vmcnt(0)
	v_pk_fma_f32 v[106:107], v[130:131], v[106:107], v[134:135]
	v_pk_fma_f32 v[108:109], v[132:133], v[108:109], v[136:137]
	v_cndmask_b32_e32 v106, v1, v106, vcc
	v_cndmask_b32_e32 v108, v1, v108, vcc
	v_cndmask_b32_e32 v109, v1, v109, vcc
	v_cndmask_b32_e32 v107, v1, v107, vcc
	v_cvt_pk_bf16_f32 v226, v106, v107
	v_cvt_pk_bf16_f32 v227, v108, v109
	ds_read_b64 v[108:109], v148 offset:8320
	s_waitcnt lgkmcnt(0)
	v_sub_f32_e32 v107, v115, v108
	v_sub_f32_e32 v106, v114, v108
	v_sub_f32_e32 v115, v117, v108
	v_sub_f32_e32 v114, v116, v108
	v_pk_mul_f32 v[114:115], v[108:109], v[114:115] op_sel:[1,0]
	v_pk_mul_f32 v[106:107], v[108:109], v[106:107] op_sel:[1,0]
	v_pk_fma_f32 v[108:109], v[132:133], v[114:115], v[136:137]
	v_pk_fma_f32 v[106:107], v[130:131], v[106:107], v[134:135]
	v_cndmask_b32_e32 v108, v1, v108, vcc
	v_cndmask_b32_e32 v109, v1, v109, vcc
	v_cndmask_b32_e32 v106, v1, v106, vcc
	v_cndmask_b32_e32 v107, v1, v107, vcc
	v_cvt_pk_bf16_f32 v228, v106, v107
	v_cvt_pk_bf16_f32 v229, v108, v109
	ds_read_b64 v[108:109], v148 offset:8448
	v_lshlrev_b64 v[114:115], 11, v[152:153]
	v_lshl_add_u64 v[114:115], s[4:5], 0, v[114:115]
	v_lshl_add_u64 v[114:115], v[114:115], 0, v[138:139]
	s_waitcnt lgkmcnt(0)
	v_sub_f32_e32 v107, v127, v108
	v_sub_f32_e32 v106, v126, v108
	v_sub_f32_e32 v117, v129, v108
	v_sub_f32_e32 v116, v128, v108
	v_pk_mul_f32 v[106:107], v[108:109], v[106:107] op_sel:[1,0]
	v_pk_mul_f32 v[116:117], v[108:109], v[116:117] op_sel:[1,0]
	v_pk_fma_f32 v[106:107], v[130:131], v[106:107], v[134:135]
	v_pk_fma_f32 v[108:109], v[132:133], v[116:117], v[136:137]
	v_cndmask_b32_e32 v106, v1, v106, vcc
	v_cndmask_b32_e32 v107, v1, v107, vcc
	v_cndmask_b32_e32 v108, v1, v108, vcc
	v_cndmask_b32_e32 v109, v1, v109, vcc
	v_cvt_pk_bf16_f32 v230, v106, v107
	v_cvt_pk_bf16_f32 v231, v108, v109
	ds_read_b64 v[116:117], v148 offset:8576
	v_lshlrev_b64 v[108:109], 11, v[154:155]
	v_lshl_add_u64 v[108:109], s[4:5], 0, v[108:109]
	v_lshl_add_u64 v[108:109], v[108:109], 0, v[138:139]
	s_waitcnt lgkmcnt(0)
	v_sub_f32_e32 v107, v123, v116
	v_sub_f32_e32 v106, v122, v116
	v_sub_f32_e32 v123, v125, v116
	v_sub_f32_e32 v122, v124, v116
	v_pk_mul_f32 v[122:123], v[116:117], v[122:123] op_sel:[1,0]
	v_pk_mul_f32 v[106:107], v[116:117], v[106:107] op_sel:[1,0]
	v_pk_fma_f32 v[116:117], v[132:133], v[122:123], v[136:137]
	v_pk_fma_f32 v[106:107], v[130:131], v[106:107], v[134:135]
	v_cndmask_b32_e32 v122, v1, v116, vcc
	v_cndmask_b32_e32 v117, v1, v117, vcc
	v_cndmask_b32_e32 v106, v1, v106, vcc
	v_cndmask_b32_e32 v107, v1, v107, vcc
	v_cvt_pk_bf16_f32 v232, v106, v107
	v_cvt_pk_bf16_f32 v233, v122, v117
	ds_read_b64 v[122:123], v148 offset:9216
	v_lshlrev_b64 v[106:107], 11, v[156:157]
	v_lshl_add_u64 v[106:107], s[4:5], 0, v[106:107]
	v_lshl_add_u64 v[106:107], v[106:107], 0, v[138:139]
	s_waitcnt lgkmcnt(0)
	v_sub_f32_e32 v105, v105, v122
	v_sub_f32_e32 v104, v104, v122
	v_sub_f32_e32 v103, v103, v122
	v_sub_f32_e32 v102, v102, v122
	v_pk_mul_f32 v[104:105], v[122:123], v[104:105] op_sel:[1,0]
	v_pk_mul_f32 v[102:103], v[122:123], v[102:103] op_sel:[1,0]
	v_pk_fma_f32 v[104:105], v[132:133], v[104:105], v[136:137]
	v_pk_fma_f32 v[102:103], v[130:131], v[102:103], v[134:135]
	v_cndmask_b32_e32 v116, v1, v104, vcc
	v_cndmask_b32_e32 v105, v1, v105, vcc
	v_cndmask_b32_e32 v102, v1, v102, vcc
	v_cndmask_b32_e32 v103, v1, v103, vcc
	v_cvt_pk_bf16_f32 v234, v102, v103
	v_cvt_pk_bf16_f32 v235, v116, v105
	ds_read_b64 v[116:117], v148 offset:9344
	v_lshlrev_b64 v[102:103], 11, v[158:159]
	v_lshl_add_u64 v[102:103], s[4:5], 0, v[102:103]
	v_lshl_add_u64 v[102:103], v[102:103], 0, v[138:139]
	s_waitcnt lgkmcnt(0)
	v_sub_f32_e32 v81, v81, v116
	v_sub_f32_e32 v80, v80, v116
	v_sub_f32_e32 v79, v79, v116
	v_sub_f32_e32 v78, v78, v116
	v_pk_mul_f32 v[80:81], v[116:117], v[80:81] op_sel:[1,0]
	v_pk_mul_f32 v[78:79], v[116:117], v[78:79] op_sel:[1,0]
	v_pk_fma_f32 v[80:81], v[132:133], v[80:81], v[136:137]
	v_pk_fma_f32 v[78:79], v[130:131], v[78:79], v[134:135]
	v_cndmask_b32_e32 v104, v1, v80, vcc
	v_cndmask_b32_e32 v81, v1, v81, vcc
	v_cndmask_b32_e32 v78, v1, v78, vcc
	v_cndmask_b32_e32 v79, v1, v79, vcc
	v_cvt_pk_bf16_f32 v236, v78, v79
	v_cvt_pk_bf16_f32 v237, v104, v81
	ds_read_b64 v[104:105], v148 offset:9472
	v_lshlrev_b64 v[78:79], 11, v[160:161]
	v_lshl_add_u64 v[78:79], s[4:5], 0, v[78:79]
	v_lshl_add_u64 v[78:79], v[78:79], 0, v[138:139]
	s_waitcnt lgkmcnt(0)
; __device__ __forceinline__ unsigned cvt_pk_bf16(float lo, float hi) { unsigned r; asm volatile("v_cvt_pk_bf16_f32 %0, %1, %2" : "=v"(r) : "v"(lo), "v"(hi)); return r; }
;     __device__ __forceinline__ void fused(f32x4 (&acc)[2][2][4][2], const Unit& u, int wr, int wc, int fr, int fq, PG8_LAS unsigned char* lds, int wid, int lane) const {
;     ...
;         const float qnan = __builtin_nanf("");
; #pragma unroll
;         for (int bj = 0; bj < 2; ++bj)
; #pragma unroll
;             for (int n = 0; n < 2; ++n) { const f32x4 gv = *(const f32x4*)(g + col0 + bj * HALF + n * 16), bv = *(const f32x4*)(b + col0 + bj * HALF + n * 16);
; #pragma unroll
;                 for (int ai = 0; ai < 2; ++ai)
; #pragma unroll
;                     for (int m = 0; m < 4; ++m) { const int r = ai * HALF + wr * 64 + m * 16 + fr; const f32x2v sr = S[r]; const size_t o = (size_t)(rowoff + u.pm * BM + r) * ldc + col0 + bj * HALF + n * 16;
;                         f32x4 v = (acc[ai][bj][m][n] - sr.x) * sr.y * gv + bv; if (bad) v = (f32x4){qnan, qnan, qnan, qnan};
;                         if (outf) *(f32x4*)(outf + o) = v; else { u32x2 w; w.x = cvt_pk_bf16(v[0], v[1]); w.y = cvt_pk_bf16(v[2], v[3]); *(u32x2*)(outb + o) = w; } } }
	v_sub_f32_e32 v39, v39, v104
	v_sub_f32_e32 v38, v38, v104
	v_sub_f32_e32 v41, v41, v104
	v_sub_f32_e32 v40, v40, v104
	v_pk_mul_f32 v[40:41], v[104:105], v[40:41] op_sel:[1,0]
	v_pk_mul_f32 v[38:39], v[104:105], v[38:39] op_sel:[1,0]
	v_add_u32_e32 v80, 0xa0, v146
	v_pk_fma_f32 v[38:39], v[130:131], v[38:39], v[134:135]
	v_pk_fma_f32 v[40:41], v[132:133], v[40:41], v[136:137]
	v_ashrrev_i32_e32 v81, 31, v80
	v_cndmask_b32_e32 v41, v1, v41, vcc
	v_cndmask_b32_e32 v38, v1, v38, vcc
	v_cndmask_b32_e32 v39, v1, v39, vcc
	v_cndmask_b32_e32 v104, v1, v40, vcc
	v_cvt_pk_bf16_f32 v238, v38, v39
	v_cvt_pk_bf16_f32 v239, v104, v41
	v_lshlrev_b64 v[38:39], 11, v[80:81]
	ds_read_b64 v[80:81], v148 offset:9600
	v_lshl_add_u64 v[38:39], s[4:5], 0, v[38:39]
	v_lshl_add_u64 v[38:39], v[38:39], 0, v[138:139]
	v_add_u32_e32 v40, 0xb0, v146
	s_waitcnt lgkmcnt(0)
	v_sub_f32_e32 v15, v15, v80
	v_sub_f32_e32 v14, v14, v80
	v_sub_f32_e32 v17, v17, v80
	v_sub_f32_e32 v16, v16, v80
	v_pk_mul_f32 v[14:15], v[80:81], v[14:15] op_sel:[1,0]
	v_pk_mul_f32 v[16:17], v[80:81], v[16:17] op_sel:[1,0]
	v_pk_fma_f32 v[14:15], v[130:131], v[14:15], v[134:135]
	v_ashrrev_i32_e32 v41, 31, v40
	v_pk_fma_f32 v[16:17], v[132:133], v[16:17], v[136:137]
	v_cndmask_b32_e32 v14, v1, v14, vcc
	v_cndmask_b32_e32 v15, v1, v15, vcc
	v_cndmask_b32_e32 v80, v1, v16, vcc
	v_cvt_pk_bf16_f32 v240, v14, v15
	v_lshlrev_b64 v[14:15], 11, v[40:41]
	v_lshl_add_u64 v[14:15], s[4:5], 0, v[14:15]
	v_cndmask_b32_e32 v17, v1, v17, vcc
	v_lshl_add_u64 v[14:15], v[14:15], 0, v[138:139]
	v_cvt_pk_bf16_f32 v241, v80, v17
	global_load_dwordx4 v[122:125], v[140:141], off offset:64
	global_load_dwordx4 v[126:129], v[142:143], off offset:64
	ds_read_b64 v[16:17], v148 offset:8192
	s_waitcnt lgkmcnt(0)
	v_sub_f32_e32 v41, v67, v16
	v_sub_f32_e32 v40, v66, v16
	v_sub_f32_e32 v67, v69, v16
	v_sub_f32_e32 v66, v68, v16
	v_pk_mul_f32 v[66:67], v[16:17], v[66:67] op_sel:[1,0]
	v_pk_mul_f32 v[16:17], v[16:17], v[40:41] op_sel:[1,0]
	s_waitcnt vmcnt(0)
	v_pk_fma_f32 v[40:41], v[124:125], v[66:67], v[128:129]
	v_pk_fma_f32 v[16:17], v[122:123], v[16:17], v[126:127]
	v_cndmask_b32_e32 v40, v1, v40, vcc
	v_cndmask_b32_e32 v41, v1, v41, vcc
	v_cndmask_b32_e32 v16, v1, v16, vcc
	v_cndmask_b32_e32 v17, v1, v17, vcc
	v_cvt_pk_bf16_f32 v246, v16, v17
	v_cvt_pk_bf16_f32 v247, v40, v41
	ds_read_b64 v[40:41], v148 offset:8320
	v_mov_b32_e32 v244, v226
	v_mov_b32_e32 v245, v227
	s_nop 1
	v_permlane16_swap_b32_e32 v244, v246
	v_permlane16_swap_b32_e32 v245, v247
	global_store_dwordx4 v[144:145], v[244:247], off
	s_waitcnt lgkmcnt(0)
	v_sub_f32_e32 v17, v87, v40
	v_sub_f32_e32 v16, v86, v40
	v_sub_f32_e32 v67, v89, v40
	v_sub_f32_e32 v66, v88, v40
	v_pk_mul_f32 v[66:67], v[40:41], v[66:67] op_sel:[1,0]
	v_pk_mul_f32 v[16:17], v[40:41], v[16:17] op_sel:[1,0]
	v_pk_fma_f32 v[40:41], v[124:125], v[66:67], v[128:129]
	v_pk_fma_f32 v[16:17], v[122:123], v[16:17], v[126:127]
	v_cndmask_b32_e32 v40, v1, v40, vcc
	v_cndmask_b32_e32 v41, v1, v41, vcc
	v_cndmask_b32_e32 v16, v1, v16, vcc
	v_cndmask_b32_e32 v17, v1, v17, vcc
	v_cvt_pk_bf16_f32 v250, v16, v17
	v_cvt_pk_bf16_f32 v251, v40, v41
	ds_read_b64 v[40:41], v148 offset:8448
	v_mov_b32_e32 v248, v228
	v_mov_b32_e32 v249, v229
	s_nop 1
	v_permlane16_swap_b32_e32 v248, v250
	v_permlane16_swap_b32_e32 v249, v251
	global_store_dwordx4 v[114:115], v[248:251], off
	s_waitcnt lgkmcnt(0)
	v_sub_f32_e32 v17, v111, v40
	v_sub_f32_e32 v16, v110, v40
	v_sub_f32_e32 v67, v113, v40
	v_sub_f32_e32 v66, v112, v40
	v_pk_mul_f32 v[66:67], v[40:41], v[66:67] op_sel:[1,0]
	v_pk_mul_f32 v[16:17], v[40:41], v[16:17] op_sel:[1,0]
	v_pk_fma_f32 v[40:41], v[124:125], v[66:67], v[128:129]
	v_pk_fma_f32 v[16:17], v[122:123], v[16:17], v[126:127]
	v_cndmask_b32_e32 v40, v1, v40, vcc
	v_cndmask_b32_e32 v41, v1, v41, vcc
	v_cndmask_b32_e32 v16, v1, v16, vcc
	v_cndmask_b32_e32 v17, v1, v17, vcc
	v_cvt_pk_bf16_f32 v246, v16, v17
	v_cvt_pk_bf16_f32 v247, v40, v41
	ds_read_b64 v[40:41], v148 offset:8576
	v_mov_b32_e32 v244, v230
	v_mov_b32_e32 v245, v231
	s_nop 1
	v_permlane16_swap_b32_e32 v244, v246
	v_permlane16_swap_b32_e32 v245, v247
	global_store_dwordx4 v[108:109], v[244:247], off
	s_waitcnt lgkmcnt(0)
	v_sub_f32_e32 v17, v119, v40
	v_sub_f32_e32 v16, v118, v40
	v_sub_f32_e32 v67, v121, v40
	v_sub_f32_e32 v66, v120, v40
	v_pk_mul_f32 v[66:67], v[40:41], v[66:67] op_sel:[1,0]
	v_pk_mul_f32 v[16:17], v[40:41], v[16:17] op_sel:[1,0]
	v_pk_fma_f32 v[40:41], v[124:125], v[66:67], v[128:129]
	v_pk_fma_f32 v[16:17], v[122:123], v[16:17], v[126:127]
	v_cndmask_b32_e32 v40, v1, v40, vcc
	v_cndmask_b32_e32 v41, v1, v41, vcc
	v_cndmask_b32_e32 v16, v1, v16, vcc
	v_cndmask_b32_e32 v17, v1, v17, vcc
	v_cvt_pk_bf16_f32 v250, v16, v17
	v_cvt_pk_bf16_f32 v251, v40, v41
	ds_read_b64 v[40:41], v148 offset:9216
	v_mov_b32_e32 v248, v232
	v_mov_b32_e32 v249, v233
	s_nop 1
	v_permlane16_swap_b32_e32 v248, v250
	v_permlane16_swap_b32_e32 v249, v251
	global_store_dwordx4 v[106:107], v[248:251], off
	s_waitcnt lgkmcnt(0)
	v_sub_f32_e32 v17, v99, v40
	v_sub_f32_e32 v16, v98, v40
	v_sub_f32_e32 v67, v101, v40
	v_sub_f32_e32 v66, v100, v40
	v_pk_mul_f32 v[66:67], v[40:41], v[66:67] op_sel:[1,0]
	v_pk_mul_f32 v[16:17], v[40:41], v[16:17] op_sel:[1,0]
	v_pk_fma_f32 v[40:41], v[124:125], v[66:67], v[128:129]
	v_pk_fma_f32 v[16:17], v[122:123], v[16:17], v[126:127]
	v_cndmask_b32_e32 v40, v1, v40, vcc
	v_cndmask_b32_e32 v41, v1, v41, vcc
	v_cndmask_b32_e32 v16, v1, v16, vcc
	v_cndmask_b32_e32 v17, v1, v17, vcc
	v_cvt_pk_bf16_f32 v246, v16, v17
	v_cvt_pk_bf16_f32 v247, v40, v41
	ds_read_b64 v[40:41], v148 offset:9344
	v_mov_b32_e32 v244, v234
	v_mov_b32_e32 v245, v235
	s_nop 1
	v_permlane16_swap_b32_e32 v244, v246
	v_permlane16_swap_b32_e32 v245, v247
	global_store_dwordx4 v[102:103], v[244:247], off
	s_waitcnt lgkmcnt(0)
; __device__ __forceinline__ unsigned cvt_pk_bf16(float lo, float hi) { unsigned r; asm volatile("v_cvt_pk_bf16_f32 %0, %1, %2" : "=v"(r) : "v"(lo), "v"(hi)); return r; }
;     __device__ __forceinline__ void fused(f32x4 (&acc)[2][2][4][2], const Unit& u, int wr, int wc, int fr, int fq, PG8_LAS unsigned char* lds, int wid, int lane) const {
;     ...
;         const float qnan = __builtin_nanf("");
; #pragma unroll
;         for (int bj = 0; bj < 2; ++bj)
; #pragma unroll
;             for (int n = 0; n < 2; ++n) { const f32x4 gv = *(const f32x4*)(g + col0 + bj * HALF + n * 16), bv = *(const f32x4*)(b + col0 + bj * HALF + n * 16);
; #pragma unroll
;                 for (int ai = 0; ai < 2; ++ai)
; #pragma unroll
;                     for (int m = 0; m < 4; ++m) { const int r = ai * HALF + wr * 64 + m * 16 + fr; const f32x2v sr = S[r]; const size_t o = (size_t)(rowoff + u.pm * BM + r) * ldc + col0 + bj * HALF + n * 16;
;                         f32x4 v = (acc[ai][bj][m][n] - sr.x) * sr.y * gv + bv; if (bad) v = (f32x4){qnan, qnan, qnan, qnan};
;                         if (outf) *(f32x4*)(outf + o) = v; else { u32x2 w; w.x = cvt_pk_bf16(v[0], v[1]); w.y = cvt_pk_bf16(v[2], v[3]); *(u32x2*)(outb + o) = w; } } }
	v_sub_f32_e32 v17, v71, v40
	v_sub_f32_e32 v16, v70, v40
	v_sub_f32_e32 v67, v73, v40
	v_sub_f32_e32 v66, v72, v40
	v_pk_mul_f32 v[66:67], v[40:41], v[66:67] op_sel:[1,0]
	v_pk_mul_f32 v[16:17], v[40:41], v[16:17] op_sel:[1,0]
	v_pk_fma_f32 v[40:41], v[124:125], v[66:67], v[128:129]
	v_pk_fma_f32 v[16:17], v[122:123], v[16:17], v[126:127]
	v_cndmask_b32_e32 v40, v1, v40, vcc
	v_cndmask_b32_e32 v41, v1, v41, vcc
	v_cndmask_b32_e32 v16, v1, v16, vcc
	v_cndmask_b32_e32 v17, v1, v17, vcc
	v_cvt_pk_bf16_f32 v250, v16, v17
	v_cvt_pk_bf16_f32 v251, v40, v41
	ds_read_b64 v[40:41], v148 offset:9472
	v_mov_b32_e32 v248, v236
	v_mov_b32_e32 v249, v237
	s_nop 1
	v_permlane16_swap_b32_e32 v248, v250
	v_permlane16_swap_b32_e32 v249, v251
	global_store_dwordx4 v[78:79], v[248:251], off
	s_waitcnt lgkmcnt(0)
	v_sub_f32_e32 v17, v35, v40
	v_sub_f32_e32 v16, v34, v40
	v_sub_f32_e32 v35, v37, v40
	v_sub_f32_e32 v34, v36, v40
	v_pk_mul_f32 v[34:35], v[40:41], v[34:35] op_sel:[1,0]
	v_pk_mul_f32 v[16:17], v[40:41], v[16:17] op_sel:[1,0]
	v_pk_fma_f32 v[34:35], v[124:125], v[34:35], v[128:129]
	v_pk_fma_f32 v[16:17], v[122:123], v[16:17], v[126:127]
	v_cndmask_b32_e32 v34, v1, v34, vcc
	v_cndmask_b32_e32 v35, v1, v35, vcc
	v_cndmask_b32_e32 v16, v1, v16, vcc
	v_cndmask_b32_e32 v17, v1, v17, vcc
	v_cvt_pk_bf16_f32 v246, v16, v17
	v_cvt_pk_bf16_f32 v247, v34, v35
	ds_read_b64 v[34:35], v148 offset:9600
	v_mov_b32_e32 v244, v238
	v_mov_b32_e32 v245, v239
	s_nop 1
	v_permlane16_swap_b32_e32 v244, v246
	v_permlane16_swap_b32_e32 v245, v247
	global_store_dwordx4 v[38:39], v[244:247], off
	s_waitcnt lgkmcnt(0)
	v_sub_f32_e32 v11, v11, v34
	v_sub_f32_e32 v10, v10, v34
	v_sub_f32_e32 v13, v13, v34
	v_sub_f32_e32 v12, v12, v34
	v_pk_mul_f32 v[10:11], v[34:35], v[10:11] op_sel:[1,0]
	v_pk_mul_f32 v[12:13], v[34:35], v[12:13] op_sel:[1,0]
	v_pk_fma_f32 v[10:11], v[122:123], v[10:11], v[126:127]
	v_pk_fma_f32 v[12:13], v[124:125], v[12:13], v[128:129]
	v_cndmask_b32_e32 v10, v1, v10, vcc
	v_cndmask_b32_e32 v11, v1, v11, vcc
	v_cndmask_b32_e32 v12, v1, v12, vcc
	v_cndmask_b32_e32 v13, v1, v13, vcc
	v_cvt_pk_bf16_f32 v250, v10, v11
	v_cvt_pk_bf16_f32 v251, v12, v13
	v_mov_b32_e32 v248, v240
	v_mov_b32_e32 v249, v241
	s_nop 1
	v_permlane16_swap_b32_e32 v248, v250
	v_permlane16_swap_b32_e32 v249, v251
	global_store_dwordx4 v[14:15], v[248:251], off
	global_load_dwordx4 v[10:13], v[140:141], off offset:512
	s_nop 0
	global_load_dwordx4 v[34:37], v[142:143], off offset:512
	ds_read_b64 v[16:17], v148 offset:8192
	s_waitcnt lgkmcnt(0)
	v_sub_f32_e32 v41, v43, v16
	v_sub_f32_e32 v40, v42, v16
	v_sub_f32_e32 v43, v45, v16
	v_sub_f32_e32 v42, v44, v16
	v_pk_mul_f32 v[42:43], v[16:17], v[42:43] op_sel:[1,0]
	v_pk_mul_f32 v[16:17], v[16:17], v[40:41] op_sel:[1,0]
	s_waitcnt vmcnt(0)
	v_pk_fma_f32 v[40:41], v[12:13], v[42:43], v[36:37]
	v_pk_fma_f32 v[16:17], v[10:11], v[16:17], v[34:35]
	v_cndmask_b32_e32 v40, v1, v40, vcc
	v_cndmask_b32_e32 v41, v1, v41, vcc
	v_cndmask_b32_e32 v16, v1, v16, vcc
	v_cndmask_b32_e32 v17, v1, v17, vcc
	v_cvt_pk_bf16_f32 v226, v16, v17
	v_cvt_pk_bf16_f32 v227, v40, v41
	ds_read_b64 v[40:41], v148 offset:8320
	s_waitcnt lgkmcnt(0)
	v_sub_f32_e32 v17, v51, v40
	v_sub_f32_e32 v16, v50, v40
	v_sub_f32_e32 v43, v53, v40
	v_sub_f32_e32 v42, v52, v40
	v_pk_mul_f32 v[42:43], v[40:41], v[42:43] op_sel:[1,0]
	v_pk_mul_f32 v[16:17], v[40:41], v[16:17] op_sel:[1,0]
	v_pk_fma_f32 v[40:41], v[12:13], v[42:43], v[36:37]
	v_pk_fma_f32 v[16:17], v[10:11], v[16:17], v[34:35]
	v_cndmask_b32_e32 v40, v1, v40, vcc
	v_cndmask_b32_e32 v41, v1, v41, vcc
	v_cndmask_b32_e32 v16, v1, v16, vcc
	v_cndmask_b32_e32 v17, v1, v17, vcc
	v_cvt_pk_bf16_f32 v228, v16, v17
	v_cvt_pk_bf16_f32 v229, v40, v41
	ds_read_b64 v[40:41], v148 offset:8448
	s_waitcnt lgkmcnt(0)
	v_sub_f32_e32 v17, v75, v40
	v_sub_f32_e32 v16, v74, v40
	v_sub_f32_e32 v43, v77, v40
	v_sub_f32_e32 v42, v76, v40
	v_pk_mul_f32 v[42:43], v[40:41], v[42:43] op_sel:[1,0]
	v_pk_mul_f32 v[16:17], v[40:41], v[16:17] op_sel:[1,0]
	v_pk_fma_f32 v[40:41], v[12:13], v[42:43], v[36:37]
	v_pk_fma_f32 v[16:17], v[10:11], v[16:17], v[34:35]
	v_cndmask_b32_e32 v40, v1, v40, vcc
	v_cndmask_b32_e32 v41, v1, v41, vcc
	v_cndmask_b32_e32 v16, v1, v16, vcc
	v_cndmask_b32_e32 v17, v1, v17, vcc
	v_cvt_pk_bf16_f32 v230, v16, v17
	v_cvt_pk_bf16_f32 v231, v40, v41
	ds_read_b64 v[40:41], v148 offset:8576
	s_waitcnt lgkmcnt(0)
	v_sub_f32_e32 v17, v95, v40
	v_sub_f32_e32 v16, v94, v40
	v_sub_f32_e32 v43, v97, v40
	v_sub_f32_e32 v42, v96, v40
	v_pk_mul_f32 v[42:43], v[40:41], v[42:43] op_sel:[1,0]
	v_pk_mul_f32 v[16:17], v[40:41], v[16:17] op_sel:[1,0]
	v_pk_fma_f32 v[40:41], v[12:13], v[42:43], v[36:37]
	v_pk_fma_f32 v[16:17], v[10:11], v[16:17], v[34:35]
	v_cndmask_b32_e32 v40, v1, v40, vcc
	v_cndmask_b32_e32 v41, v1, v41, vcc
	v_cndmask_b32_e32 v16, v1, v16, vcc
	v_cndmask_b32_e32 v17, v1, v17, vcc
	v_cvt_pk_bf16_f32 v232, v16, v17
	v_cvt_pk_bf16_f32 v233, v40, v41
	ds_read_b64 v[40:41], v148 offset:9216
	s_waitcnt lgkmcnt(0)
	v_sub_f32_e32 v17, v91, v40
	v_sub_f32_e32 v16, v90, v40
	v_sub_f32_e32 v43, v93, v40
	v_sub_f32_e32 v42, v92, v40
	v_pk_mul_f32 v[42:43], v[40:41], v[42:43] op_sel:[1,0]
	v_pk_mul_f32 v[16:17], v[40:41], v[16:17] op_sel:[1,0]
	v_pk_fma_f32 v[40:41], v[12:13], v[42:43], v[36:37]
	v_pk_fma_f32 v[16:17], v[10:11], v[16:17], v[34:35]
	v_cndmask_b32_e32 v40, v1, v40, vcc
	v_cndmask_b32_e32 v41, v1, v41, vcc
	v_cndmask_b32_e32 v16, v1, v16, vcc
	v_cndmask_b32_e32 v17, v1, v17, vcc
	v_cvt_pk_bf16_f32 v234, v16, v17
	v_cvt_pk_bf16_f32 v235, v40, v41
	ds_read_b64 v[40:41], v148 offset:9344
	s_waitcnt lgkmcnt(0)
; __device__ __forceinline__ unsigned cvt_pk_bf16(float lo, float hi) { unsigned r; asm volatile("v_cvt_pk_bf16_f32 %0, %1, %2" : "=v"(r) : "v"(lo), "v"(hi)); return r; }
;     __device__ __forceinline__ void fused(f32x4 (&acc)[2][2][4][2], const Unit& u, int wr, int wc, int fr, int fq, PG8_LAS unsigned char* lds, int wid, int lane) const {
;     ...
;         const float qnan = __builtin_nanf("");
; #pragma unroll
;         for (int bj = 0; bj < 2; ++bj)
; #pragma unroll
;             for (int n = 0; n < 2; ++n) { const f32x4 gv = *(const f32x4*)(g + col0 + bj * HALF + n * 16), bv = *(const f32x4*)(b + col0 + bj * HALF + n * 16);
; #pragma unroll
;                 for (int ai = 0; ai < 2; ++ai)
; #pragma unroll
;                     for (int m = 0; m < 4; ++m) { const int r = ai * HALF + wr * 64 + m * 16 + fr; const f32x2v sr = S[r]; const size_t o = (size_t)(rowoff + u.pm * BM + r) * ldc + col0 + bj * HALF + n * 16;
;                         f32x4 v = (acc[ai][bj][m][n] - sr.x) * sr.y * gv + bv; if (bad) v = (f32x4){qnan, qnan, qnan, qnan};
;                         if (outf) *(f32x4*)(outf + o) = v; else { u32x2 w; w.x = cvt_pk_bf16(v[0], v[1]); w.y = cvt_pk_bf16(v[2], v[3]); *(u32x2*)(outb + o) = w; } } }
	v_sub_f32_e32 v17, v63, v40
	v_sub_f32_e32 v16, v62, v40
	v_sub_f32_e32 v43, v65, v40
	v_sub_f32_e32 v42, v64, v40
	v_pk_mul_f32 v[42:43], v[40:41], v[42:43] op_sel:[1,0]
	v_pk_mul_f32 v[16:17], v[40:41], v[16:17] op_sel:[1,0]
	v_pk_fma_f32 v[40:41], v[12:13], v[42:43], v[36:37]
	v_pk_fma_f32 v[16:17], v[10:11], v[16:17], v[34:35]
	v_cndmask_b32_e32 v40, v1, v40, vcc
	v_cndmask_b32_e32 v41, v1, v41, vcc
	v_cndmask_b32_e32 v16, v1, v16, vcc
	v_cndmask_b32_e32 v17, v1, v17, vcc
	v_cvt_pk_bf16_f32 v236, v16, v17
	v_cvt_pk_bf16_f32 v237, v40, v41
	ds_read_b64 v[40:41], v148 offset:9472
	s_waitcnt lgkmcnt(0)
	v_sub_f32_e32 v17, v27, v40
	v_sub_f32_e32 v16, v26, v40
	v_sub_f32_e32 v27, v29, v40
	v_sub_f32_e32 v26, v28, v40
	v_pk_mul_f32 v[26:27], v[40:41], v[26:27] op_sel:[1,0]
	v_pk_mul_f32 v[16:17], v[40:41], v[16:17] op_sel:[1,0]
	v_pk_fma_f32 v[26:27], v[12:13], v[26:27], v[36:37]
	v_pk_fma_f32 v[16:17], v[10:11], v[16:17], v[34:35]
	v_cndmask_b32_e32 v26, v1, v26, vcc
	v_cndmask_b32_e32 v27, v1, v27, vcc
	v_cndmask_b32_e32 v16, v1, v16, vcc
	v_cndmask_b32_e32 v17, v1, v17, vcc
	v_cvt_pk_bf16_f32 v238, v16, v17
	v_cvt_pk_bf16_f32 v239, v26, v27
	ds_read_b64 v[26:27], v148 offset:9600
	s_waitcnt lgkmcnt(0)
	v_sub_f32_e32 v7, v7, v26
	v_sub_f32_e32 v6, v6, v26
	v_sub_f32_e32 v9, v9, v26
	v_sub_f32_e32 v8, v8, v26
	v_pk_mul_f32 v[6:7], v[26:27], v[6:7] op_sel:[1,0]
	v_pk_mul_f32 v[8:9], v[26:27], v[8:9] op_sel:[1,0]
	v_pk_fma_f32 v[6:7], v[10:11], v[6:7], v[34:35]
	v_pk_fma_f32 v[8:9], v[12:13], v[8:9], v[36:37]
	v_cndmask_b32_e32 v6, v1, v6, vcc
	v_cndmask_b32_e32 v7, v1, v7, vcc
	v_cndmask_b32_e32 v8, v1, v8, vcc
	v_cndmask_b32_e32 v9, v1, v9, vcc
	v_cvt_pk_bf16_f32 v240, v6, v7
	v_cvt_pk_bf16_f32 v241, v8, v9
	global_load_dwordx4 v[6:9], v[140:141], off offset:576
	s_nop 0
	global_load_dwordx4 v[10:13], v[142:143], off offset:576
	ds_read_b64 v[16:17], v148 offset:8192
	s_waitcnt lgkmcnt(0)
	v_sub_f32_e32 v19, v19, v16
	v_sub_f32_e32 v18, v18, v16
	v_sub_f32_e32 v21, v21, v16
	v_sub_f32_e32 v20, v20, v16
	v_pk_mul_f32 v[20:21], v[16:17], v[20:21] op_sel:[1,0]
	v_pk_mul_f32 v[16:17], v[16:17], v[18:19] op_sel:[1,0]
	s_waitcnt vmcnt(0)
	v_pk_fma_f32 v[18:19], v[8:9], v[20:21], v[12:13]
	v_pk_fma_f32 v[16:17], v[6:7], v[16:17], v[10:11]
	v_cndmask_b32_e32 v18, v1, v18, vcc
	v_cndmask_b32_e32 v19, v1, v19, vcc
	v_cndmask_b32_e32 v16, v1, v16, vcc
	v_cndmask_b32_e32 v17, v1, v17, vcc
	v_cvt_pk_bf16_f32 v246, v16, v17
	v_cvt_pk_bf16_f32 v247, v18, v19
	ds_read_b64 v[18:19], v148 offset:8320
	v_mov_b32_e32 v244, v226
	v_mov_b32_e32 v245, v227
	s_nop 1
	v_permlane16_swap_b32_e32 v244, v246
	v_permlane16_swap_b32_e32 v245, v247
	global_store_dwordx4 v[144:145], v[244:247], off offset:256
	s_waitcnt lgkmcnt(0)
	v_sub_f32_e32 v17, v31, v18
	v_sub_f32_e32 v16, v30, v18
	v_sub_f32_e32 v21, v33, v18
	v_sub_f32_e32 v20, v32, v18
	v_pk_mul_f32 v[20:21], v[18:19], v[20:21] op_sel:[1,0]
	v_pk_mul_f32 v[16:17], v[18:19], v[16:17] op_sel:[1,0]
	v_pk_fma_f32 v[18:19], v[8:9], v[20:21], v[12:13]
	v_pk_fma_f32 v[16:17], v[6:7], v[16:17], v[10:11]
	v_cndmask_b32_e32 v18, v1, v18, vcc
	v_cndmask_b32_e32 v19, v1, v19, vcc
	v_cndmask_b32_e32 v16, v1, v16, vcc
	v_cndmask_b32_e32 v17, v1, v17, vcc
	v_cvt_pk_bf16_f32 v250, v16, v17
	v_cvt_pk_bf16_f32 v251, v18, v19
	ds_read_b64 v[18:19], v148 offset:8448
	v_mov_b32_e32 v248, v228
	v_mov_b32_e32 v249, v229
	s_nop 1
	v_permlane16_swap_b32_e32 v248, v250
	v_permlane16_swap_b32_e32 v249, v251
	global_store_dwordx4 v[114:115], v[248:251], off offset:256
	s_waitcnt lgkmcnt(0)
	v_sub_f32_e32 v17, v47, v18
	v_sub_f32_e32 v16, v46, v18
	v_sub_f32_e32 v21, v49, v18
	v_sub_f32_e32 v20, v48, v18
	v_pk_mul_f32 v[20:21], v[18:19], v[20:21] op_sel:[1,0]
	v_pk_mul_f32 v[16:17], v[18:19], v[16:17] op_sel:[1,0]
	v_pk_fma_f32 v[18:19], v[8:9], v[20:21], v[12:13]
	v_pk_fma_f32 v[16:17], v[6:7], v[16:17], v[10:11]
	v_cndmask_b32_e32 v18, v1, v18, vcc
	v_cndmask_b32_e32 v19, v1, v19, vcc
	v_cndmask_b32_e32 v16, v1, v16, vcc
	v_cndmask_b32_e32 v17, v1, v17, vcc
	v_cvt_pk_bf16_f32 v246, v16, v17
	v_cvt_pk_bf16_f32 v247, v18, v19
	ds_read_b64 v[18:19], v148 offset:8576
	v_mov_b32_e32 v244, v230
	v_mov_b32_e32 v245, v231
	s_nop 1
	v_permlane16_swap_b32_e32 v244, v246
	v_permlane16_swap_b32_e32 v245, v247
	global_store_dwordx4 v[108:109], v[244:247], off offset:256
	s_waitcnt lgkmcnt(0)
; __device__ __forceinline__ unsigned cvt_pk_bf16(float lo, float hi) { unsigned r; asm volatile("v_cvt_pk_bf16_f32 %0, %1, %2" : "=v"(r) : "v"(lo), "v"(hi)); return r; }
;     __device__ __forceinline__ void fused(f32x4 (&acc)[2][2][4][2], const Unit& u, int wr, int wc, int fr, int fq, PG8_LAS unsigned char* lds, int wid, int lane) const {
;     ...
;         const float qnan = __builtin_nanf("");
; #pragma unroll
;         for (int bj = 0; bj < 2; ++bj)
; #pragma unroll
;             for (int n = 0; n < 2; ++n) { const f32x4 gv = *(const f32x4*)(g + col0 + bj * HALF + n * 16), bv = *(const f32x4*)(b + col0 + bj * HALF + n * 16);
; #pragma unroll
;                 for (int ai = 0; ai < 2; ++ai)
; #pragma unroll
;                     for (int m = 0; m < 4; ++m) { const int r = ai * HALF + wr * 64 + m * 16 + fr; const f32x2v sr = S[r]; const size_t o = (size_t)(rowoff + u.pm * BM + r) * ldc + col0 + bj * HALF + n * 16;
;                         f32x4 v = (acc[ai][bj][m][n] - sr.x) * sr.y * gv + bv; if (bad) v = (f32x4){qnan, qnan, qnan, qnan};
;                         if (outf) *(f32x4*)(outf + o) = v; else { u32x2 w; w.x = cvt_pk_bf16(v[0], v[1]); w.y = cvt_pk_bf16(v[2], v[3]); *(u32x2*)(outb + o) = w; } } }
	v_sub_f32_e32 v17, v55, v18
	v_sub_f32_e32 v16, v54, v18
	v_sub_f32_e32 v21, v57, v18
	v_sub_f32_e32 v20, v56, v18
	v_pk_mul_f32 v[20:21], v[18:19], v[20:21] op_sel:[1,0]
	v_pk_mul_f32 v[16:17], v[18:19], v[16:17] op_sel:[1,0]
	v_pk_fma_f32 v[18:19], v[8:9], v[20:21], v[12:13]
	v_pk_fma_f32 v[16:17], v[6:7], v[16:17], v[10:11]
	v_cndmask_b32_e32 v18, v1, v18, vcc
	v_cndmask_b32_e32 v19, v1, v19, vcc
	v_cndmask_b32_e32 v16, v1, v16, vcc
	v_cndmask_b32_e32 v17, v1, v17, vcc
	v_cvt_pk_bf16_f32 v250, v16, v17
	v_cvt_pk_bf16_f32 v251, v18, v19
	ds_read_b64 v[18:19], v148 offset:9216
	v_mov_b32_e32 v248, v232
	v_mov_b32_e32 v249, v233
	s_nop 1
	v_permlane16_swap_b32_e32 v248, v250
	v_permlane16_swap_b32_e32 v249, v251
	global_store_dwordx4 v[106:107], v[248:251], off offset:256
	s_waitcnt lgkmcnt(0)
	v_sub_f32_e32 v17, v83, v18
	v_sub_f32_e32 v16, v82, v18
	v_sub_f32_e32 v21, v85, v18
	v_sub_f32_e32 v20, v84, v18
	v_pk_mul_f32 v[20:21], v[18:19], v[20:21] op_sel:[1,0]
	v_pk_mul_f32 v[16:17], v[18:19], v[16:17] op_sel:[1,0]
	v_pk_fma_f32 v[18:19], v[8:9], v[20:21], v[12:13]
	v_pk_fma_f32 v[16:17], v[6:7], v[16:17], v[10:11]
	v_cndmask_b32_e32 v18, v1, v18, vcc
	v_cndmask_b32_e32 v19, v1, v19, vcc
	v_cndmask_b32_e32 v16, v1, v16, vcc
	v_cndmask_b32_e32 v17, v1, v17, vcc
	v_cvt_pk_bf16_f32 v246, v16, v17
	v_cvt_pk_bf16_f32 v247, v18, v19
	ds_read_b64 v[18:19], v148 offset:9344
	v_mov_b32_e32 v244, v234
	v_mov_b32_e32 v245, v235
	s_nop 1
	v_permlane16_swap_b32_e32 v244, v246
	v_permlane16_swap_b32_e32 v245, v247
	global_store_dwordx4 v[102:103], v[244:247], off offset:256
	s_waitcnt lgkmcnt(0)
	v_sub_f32_e32 v17, v59, v18
	v_sub_f32_e32 v16, v58, v18
	v_sub_f32_e32 v21, v61, v18
	v_sub_f32_e32 v20, v60, v18
	v_pk_mul_f32 v[20:21], v[18:19], v[20:21] op_sel:[1,0]
	v_pk_mul_f32 v[16:17], v[18:19], v[16:17] op_sel:[1,0]
	v_pk_fma_f32 v[18:19], v[8:9], v[20:21], v[12:13]
	v_pk_fma_f32 v[16:17], v[6:7], v[16:17], v[10:11]
	v_cndmask_b32_e32 v18, v1, v18, vcc
	v_cndmask_b32_e32 v19, v1, v19, vcc
	v_cndmask_b32_e32 v16, v1, v16, vcc
	v_cndmask_b32_e32 v17, v1, v17, vcc
	v_cvt_pk_bf16_f32 v250, v16, v17
	v_cvt_pk_bf16_f32 v251, v18, v19
	ds_read_b64 v[18:19], v148 offset:9472
	v_mov_b32_e32 v248, v236
	v_mov_b32_e32 v249, v237
	s_nop 1
	v_permlane16_swap_b32_e32 v248, v250
	v_permlane16_swap_b32_e32 v249, v251
	global_store_dwordx4 v[78:79], v[248:251], off offset:256
	s_waitcnt lgkmcnt(0)
	v_sub_f32_e32 v17, v23, v18
	v_sub_f32_e32 v16, v22, v18
	v_sub_f32_e32 v21, v25, v18
	v_sub_f32_e32 v20, v24, v18
	v_pk_mul_f32 v[20:21], v[18:19], v[20:21] op_sel:[1,0]
	v_pk_mul_f32 v[16:17], v[18:19], v[16:17] op_sel:[1,0]
	v_pk_fma_f32 v[18:19], v[8:9], v[20:21], v[12:13]
	v_pk_fma_f32 v[16:17], v[6:7], v[16:17], v[10:11]
	v_cndmask_b32_e32 v18, v1, v18, vcc
	v_cndmask_b32_e32 v19, v1, v19, vcc
	v_cndmask_b32_e32 v16, v1, v16, vcc
	v_cndmask_b32_e32 v17, v1, v17, vcc
	v_cvt_pk_bf16_f32 v246, v16, v17
	v_cvt_pk_bf16_f32 v247, v18, v19
	ds_read_b64 v[18:19], v148 offset:9600
	v_mov_b32_e32 v244, v238
	v_mov_b32_e32 v245, v239
	s_nop 1
	v_permlane16_swap_b32_e32 v244, v246
	v_permlane16_swap_b32_e32 v245, v247
	global_store_dwordx4 v[38:39], v[244:247], off offset:256
	s_waitcnt lgkmcnt(0)
	v_sub_f32_e32 v3, v3, v18
	v_sub_f32_e32 v2, v2, v18
	v_sub_f32_e32 v5, v5, v18
	v_sub_f32_e32 v4, v4, v18
	v_pk_mul_f32 v[2:3], v[18:19], v[2:3] op_sel:[1,0]
	v_pk_mul_f32 v[4:5], v[18:19], v[4:5] op_sel:[1,0]
	v_pk_fma_f32 v[2:3], v[6:7], v[2:3], v[10:11]
	v_pk_fma_f32 v[4:5], v[8:9], v[4:5], v[12:13]
	v_cndmask_b32_e32 v2, v1, v2, vcc
	v_cndmask_b32_e32 v4, v1, v4, vcc
	v_cndmask_b32_e32 v5, v1, v5, vcc
	v_cndmask_b32_e32 v1, v1, v3, vcc
	v_cvt_pk_bf16_f32 v250, v2, v1
	v_cvt_pk_bf16_f32 v251, v4, v5
	v_mov_b32_e32 v248, v240
	v_mov_b32_e32 v249, v241
	s_nop 1
	v_permlane16_swap_b32_e32 v248, v250
	v_permlane16_swap_b32_e32 v249, v251
	global_store_dwordx4 v[14:15], v[248:251], off offset:256
	v_sub_u32_e32 v138, v138, v252

; __device__ __forceinline__ unsigned cvt_pk_bf16(float lo, float hi) { unsigned r; asm volatile("v_cvt_pk_bf16_f32 %0, %1, %2" : "=v"(r) : "v"(lo), "v"(hi)); return r; }
;     __device__ __forceinline__ void fused(f32x4 (&acc)[2][2][4][2], const Unit& u, int wr, int wc, int fr, int fq, PG8_LAS unsigned char* lds, int wid, int lane) const {
;     ...
;         const float qnan = __builtin_nanf("");
; #pragma unroll
;         for (int bj = 0; bj < 2; ++bj)
; #pragma unroll
;             for (int n = 0; n < 2; ++n) { const f32x4 gv = *(const f32x4*)(g + col0 + bj * HALF + n * 16), bv = *(const f32x4*)(b + col0 + bj * HALF + n * 16);
; #pragma unroll
;                 for (int ai = 0; ai < 2; ++ai)
; #pragma unroll
;                     for (int m = 0; m < 4; ++m) { const int r = ai * HALF + wr * 64 + m * 16 + fr; const f32x2v sr = S[r]; const size_t o = (size_t)(rowoff + u.pm * BM + r) * ldc + col0 + bj * HALF + n * 16;
;                         f32x4 v = (acc[ai][bj][m][n] - sr.x) * sr.y * gv + bv; if (bad) v = (f32x4){qnan, qnan, qnan, qnan};
;                         if (outf) *(f32x4*)(outf + o) = v; else { u32x2 w; w.x = cvt_pk_bf16(v[0], v[1]); w.y = cvt_pk_bf16(v[2], v[3]); *(u32x2*)(outb + o) = w; } } }
.LBB0_366:
	s_or_b64 exec, exec, s[6:7]
	v_and_b32_e32 v252, 16, v186
	v_lshrrev_b32_e32 v253, 1, v252
	v_add_u32_e32 v252, v252, v253
	v_add_u32_e32 v138, v138, v252
	v_lshlrev_b64 v[134:135], 2, v[130:131]
	s_waitcnt lgkmcnt(0)
	s_barrier
	v_lshl_add_u64 v[140:141], s[14:15], 0, v[134:135]
	v_lshl_add_u64 v[142:143], s[12:13], 0, v[134:135]
	global_load_dwordx4 v[130:133], v[140:141], off
	global_load_dwordx4 v[134:137], v[142:143], off
	v_lshl_add_u32 v146, v1, 3, 0
	ds_read_b64 v[148:149], v146 offset:8192
	v_add_u32_e32 v147, s0, v1
	v_mov_b32_e32 v1, 0x7fc00000
	s_waitcnt lgkmcnt(1)
	v_cmp_eq_u32_e32 vcc, 0, v144
	v_add_u32_e32 v150, 0x4000, v147
	s_waitcnt lgkmcnt(0)
	v_sub_f32_e32 v107, v107, v148
	v_sub_f32_e32 v106, v106, v148
	v_sub_f32_e32 v109, v109, v148
	v_sub_f32_e32 v108, v108, v148
	v_pk_mul_f32 v[108:109], v[148:149], v[108:109] op_sel:[1,0]
	v_pk_mul_f32 v[106:107], v[148:149], v[106:107] op_sel:[1,0]
	v_ashrrev_i32_e32 v151, 31, v150
	v_readlane_b32 s0, v254, 13
	v_lshlrev_b64 v[144:145], 11, v[150:151]
	v_readlane_b32 s1, v254, 14
	v_add_u32_e32 v152, 0x4010, v147
	v_ashrrev_i32_e32 v153, 31, v152
	v_lshl_add_u64 v[144:145], s[0:1], 0, v[144:145]
	v_lshl_add_u64 v[144:145], v[144:145], 0, v[138:139]
	v_add_u32_e32 v154, 0x4020, v147
	v_ashrrev_i32_e32 v155, 31, v154
	v_add_u32_e32 v156, 0x4030, v147
	v_ashrrev_i32_e32 v157, 31, v156
	v_add_u32_e32 v158, 0x4080, v147
	v_ashrrev_i32_e32 v159, 31, v158
	v_add_u32_e32 v160, 0x4090, v147
	v_ashrrev_i32_e32 v161, 31, v160
	s_waitcnt vmcnt(0)
	v_pk_fma_f32 v[106:107], v[130:131], v[106:107], v[134:135]
	v_pk_fma_f32 v[108:109], v[132:133], v[108:109], v[136:137]
	v_cndmask_b32_e32 v106, v1, v106, vcc
	v_cndmask_b32_e32 v108, v1, v108, vcc
	v_cndmask_b32_e32 v109, v1, v109, vcc
	v_cndmask_b32_e32 v107, v1, v107, vcc
	v_cvt_pk_bf16_f32 v226, v106, v107
	v_cvt_pk_bf16_f32 v227, v108, v109
	ds_read_b64 v[108:109], v146 offset:8320
	s_waitcnt lgkmcnt(0)
	v_sub_f32_e32 v107, v115, v108
	v_sub_f32_e32 v106, v114, v108
	v_sub_f32_e32 v115, v117, v108
	v_sub_f32_e32 v114, v116, v108
	v_pk_mul_f32 v[114:115], v[108:109], v[114:115] op_sel:[1,0]
	v_pk_mul_f32 v[106:107], v[108:109], v[106:107] op_sel:[1,0]
	v_pk_fma_f32 v[108:109], v[132:133], v[114:115], v[136:137]
	v_pk_fma_f32 v[106:107], v[130:131], v[106:107], v[134:135]
	v_cndmask_b32_e32 v108, v1, v108, vcc
	v_cndmask_b32_e32 v109, v1, v109, vcc
	v_cndmask_b32_e32 v106, v1, v106, vcc
	v_cndmask_b32_e32 v107, v1, v107, vcc
	v_cvt_pk_bf16_f32 v228, v106, v107
	v_cvt_pk_bf16_f32 v229, v108, v109
	ds_read_b64 v[108:109], v146 offset:8448
	v_lshlrev_b64 v[114:115], 11, v[152:153]
	v_lshl_add_u64 v[114:115], s[0:1], 0, v[114:115]
	v_lshl_add_u64 v[114:115], v[114:115], 0, v[138:139]
	s_waitcnt lgkmcnt(0)
	v_sub_f32_e32 v107, v127, v108
	v_sub_f32_e32 v106, v126, v108
	v_sub_f32_e32 v117, v129, v108
	v_sub_f32_e32 v116, v128, v108
	v_pk_mul_f32 v[106:107], v[108:109], v[106:107] op_sel:[1,0]
	v_pk_mul_f32 v[116:117], v[108:109], v[116:117] op_sel:[1,0]
	v_pk_fma_f32 v[106:107], v[130:131], v[106:107], v[134:135]
	v_pk_fma_f32 v[108:109], v[132:133], v[116:117], v[136:137]
	v_cndmask_b32_e32 v106, v1, v106, vcc
	v_cndmask_b32_e32 v107, v1, v107, vcc
	v_cndmask_b32_e32 v108, v1, v108, vcc
	v_cndmask_b32_e32 v109, v1, v109, vcc
	v_cvt_pk_bf16_f32 v230, v106, v107
	v_cvt_pk_bf16_f32 v231, v108, v109
	ds_read_b64 v[116:117], v146 offset:8576
	v_lshlrev_b64 v[108:109], 11, v[154:155]
	v_lshl_add_u64 v[108:109], s[0:1], 0, v[108:109]
	v_lshl_add_u64 v[108:109], v[108:109], 0, v[138:139]
	s_waitcnt lgkmcnt(0)
	v_sub_f32_e32 v107, v123, v116
	v_sub_f32_e32 v106, v122, v116
	v_sub_f32_e32 v123, v125, v116
	v_sub_f32_e32 v122, v124, v116
	v_pk_mul_f32 v[122:123], v[116:117], v[122:123] op_sel:[1,0]
	v_pk_mul_f32 v[106:107], v[116:117], v[106:107] op_sel:[1,0]
	v_pk_fma_f32 v[116:117], v[132:133], v[122:123], v[136:137]
	v_pk_fma_f32 v[106:107], v[130:131], v[106:107], v[134:135]
	v_cndmask_b32_e32 v122, v1, v116, vcc
	v_cndmask_b32_e32 v117, v1, v117, vcc
	v_cndmask_b32_e32 v106, v1, v106, vcc
	v_cndmask_b32_e32 v107, v1, v107, vcc
	v_cvt_pk_bf16_f32 v232, v106, v107
	v_cvt_pk_bf16_f32 v233, v122, v117
	ds_read_b64 v[122:123], v146 offset:9216
	v_lshlrev_b64 v[106:107], 11, v[156:157]
	v_lshl_add_u64 v[106:107], s[0:1], 0, v[106:107]
	v_lshl_add_u64 v[106:107], v[106:107], 0, v[138:139]
	s_waitcnt lgkmcnt(0)
	v_sub_f32_e32 v105, v105, v122
	v_sub_f32_e32 v104, v104, v122
	v_sub_f32_e32 v103, v103, v122
	v_sub_f32_e32 v102, v102, v122
	v_pk_mul_f32 v[104:105], v[122:123], v[104:105] op_sel:[1,0]
	v_pk_mul_f32 v[102:103], v[122:123], v[102:103] op_sel:[1,0]
	v_pk_fma_f32 v[104:105], v[132:133], v[104:105], v[136:137]
	v_pk_fma_f32 v[102:103], v[130:131], v[102:103], v[134:135]
	v_cndmask_b32_e32 v116, v1, v104, vcc
	v_cndmask_b32_e32 v105, v1, v105, vcc
	v_cndmask_b32_e32 v102, v1, v102, vcc
	v_cndmask_b32_e32 v103, v1, v103, vcc
	v_cvt_pk_bf16_f32 v234, v102, v103
	v_cvt_pk_bf16_f32 v235, v116, v105
	ds_read_b64 v[116:117], v146 offset:9344
	v_lshlrev_b64 v[102:103], 11, v[158:159]
	v_lshl_add_u64 v[102:103], s[0:1], 0, v[102:103]
	v_lshl_add_u64 v[102:103], v[102:103], 0, v[138:139]
	s_waitcnt lgkmcnt(0)
	v_sub_f32_e32 v81, v81, v116
	v_sub_f32_e32 v80, v80, v116
	v_sub_f32_e32 v79, v79, v116
	v_sub_f32_e32 v78, v78, v116
	v_pk_mul_f32 v[80:81], v[116:117], v[80:81] op_sel:[1,0]
	v_pk_mul_f32 v[78:79], v[116:117], v[78:79] op_sel:[1,0]
	v_pk_fma_f32 v[80:81], v[132:133], v[80:81], v[136:137]
	v_pk_fma_f32 v[78:79], v[130:131], v[78:79], v[134:135]
	v_cndmask_b32_e32 v104, v1, v80, vcc
	v_cndmask_b32_e32 v81, v1, v81, vcc
	v_cndmask_b32_e32 v78, v1, v78, vcc
	v_cndmask_b32_e32 v79, v1, v79, vcc
	v_cvt_pk_bf16_f32 v236, v78, v79
	v_cvt_pk_bf16_f32 v237, v104, v81
	ds_read_b64 v[104:105], v146 offset:9472
	v_lshlrev_b64 v[78:79], 11, v[160:161]
	v_lshl_add_u64 v[78:79], s[0:1], 0, v[78:79]
	v_lshl_add_u64 v[78:79], v[78:79], 0, v[138:139]
	s_waitcnt lgkmcnt(0)
; __device__ __forceinline__ unsigned cvt_pk_bf16(float lo, float hi) { unsigned r; asm volatile("v_cvt_pk_bf16_f32 %0, %1, %2" : "=v"(r) : "v"(lo), "v"(hi)); return r; }
;     __device__ __forceinline__ void fused(f32x4 (&acc)[2][2][4][2], const Unit& u, int wr, int wc, int fr, int fq, PG8_LAS unsigned char* lds, int wid, int lane) const {
;     ...
;         const float qnan = __builtin_nanf("");
; #pragma unroll
;         for (int bj = 0; bj < 2; ++bj)
; #pragma unroll
;             for (int n = 0; n < 2; ++n) { const f32x4 gv = *(const f32x4*)(g + col0 + bj * HALF + n * 16), bv = *(const f32x4*)(b + col0 + bj * HALF + n * 16);
; #pragma unroll
;                 for (int ai = 0; ai < 2; ++ai)
; #pragma unroll
;                     for (int m = 0; m < 4; ++m) { const int r = ai * HALF + wr * 64 + m * 16 + fr; const f32x2v sr = S[r]; const size_t o = (size_t)(rowoff + u.pm * BM + r) * ldc + col0 + bj * HALF + n * 16;
;                         f32x4 v = (acc[ai][bj][m][n] - sr.x) * sr.y * gv + bv; if (bad) v = (f32x4){qnan, qnan, qnan, qnan};
;                         if (outf) *(f32x4*)(outf + o) = v; else { u32x2 w; w.x = cvt_pk_bf16(v[0], v[1]); w.y = cvt_pk_bf16(v[2], v[3]); *(u32x2*)(outb + o) = w; } } }
	v_sub_f32_e32 v39, v39, v104
	v_sub_f32_e32 v38, v38, v104
	v_sub_f32_e32 v41, v41, v104
	v_sub_f32_e32 v40, v40, v104
	v_pk_mul_f32 v[40:41], v[104:105], v[40:41] op_sel:[1,0]
	v_pk_mul_f32 v[38:39], v[104:105], v[38:39] op_sel:[1,0]
	v_add_u32_e32 v80, 0x40a0, v147
	v_pk_fma_f32 v[38:39], v[130:131], v[38:39], v[134:135]
	v_pk_fma_f32 v[40:41], v[132:133], v[40:41], v[136:137]
	v_ashrrev_i32_e32 v81, 31, v80
	v_cndmask_b32_e32 v41, v1, v41, vcc
	v_cndmask_b32_e32 v38, v1, v38, vcc
	v_cndmask_b32_e32 v39, v1, v39, vcc
	v_cndmask_b32_e32 v104, v1, v40, vcc
	v_cvt_pk_bf16_f32 v238, v38, v39
	v_cvt_pk_bf16_f32 v239, v104, v41
	v_lshlrev_b64 v[38:39], 11, v[80:81]
	ds_read_b64 v[80:81], v146 offset:9600
	v_lshl_add_u64 v[38:39], s[0:1], 0, v[38:39]
	v_lshl_add_u64 v[38:39], v[38:39], 0, v[138:139]
	v_add_u32_e32 v40, 0x40b0, v147
	s_waitcnt lgkmcnt(0)
	v_sub_f32_e32 v15, v15, v80
	v_sub_f32_e32 v14, v14, v80
	v_sub_f32_e32 v17, v17, v80
	v_sub_f32_e32 v16, v16, v80
	v_pk_mul_f32 v[14:15], v[80:81], v[14:15] op_sel:[1,0]
	v_pk_mul_f32 v[16:17], v[80:81], v[16:17] op_sel:[1,0]
	v_pk_fma_f32 v[14:15], v[130:131], v[14:15], v[134:135]
	v_ashrrev_i32_e32 v41, 31, v40
	v_pk_fma_f32 v[16:17], v[132:133], v[16:17], v[136:137]
	v_cndmask_b32_e32 v14, v1, v14, vcc
	v_cndmask_b32_e32 v15, v1, v15, vcc
	v_cndmask_b32_e32 v80, v1, v16, vcc
	v_cvt_pk_bf16_f32 v240, v14, v15
	v_lshlrev_b64 v[14:15], 11, v[40:41]
	v_lshl_add_u64 v[14:15], s[0:1], 0, v[14:15]
	v_cndmask_b32_e32 v17, v1, v17, vcc
	v_lshl_add_u64 v[14:15], v[14:15], 0, v[138:139]
	v_cvt_pk_bf16_f32 v241, v80, v17
	global_load_dwordx4 v[122:125], v[140:141], off offset:64
	global_load_dwordx4 v[126:129], v[142:143], off offset:64
	ds_read_b64 v[16:17], v146 offset:8192
	s_waitcnt lgkmcnt(0)
	v_sub_f32_e32 v41, v67, v16
	v_sub_f32_e32 v40, v66, v16
	v_sub_f32_e32 v67, v69, v16
	v_sub_f32_e32 v66, v68, v16
	v_pk_mul_f32 v[66:67], v[16:17], v[66:67] op_sel:[1,0]
	v_pk_mul_f32 v[16:17], v[16:17], v[40:41] op_sel:[1,0]
	s_waitcnt vmcnt(0)
	v_pk_fma_f32 v[40:41], v[124:125], v[66:67], v[128:129]
	v_pk_fma_f32 v[16:17], v[122:123], v[16:17], v[126:127]
	v_cndmask_b32_e32 v40, v1, v40, vcc
	v_cndmask_b32_e32 v41, v1, v41, vcc
	v_cndmask_b32_e32 v16, v1, v16, vcc
	v_cndmask_b32_e32 v17, v1, v17, vcc
	v_cvt_pk_bf16_f32 v246, v16, v17
	v_cvt_pk_bf16_f32 v247, v40, v41
	ds_read_b64 v[40:41], v146 offset:8320
	v_mov_b32_e32 v244, v226
	v_mov_b32_e32 v245, v227
	s_nop 1
	v_permlane16_swap_b32_e32 v244, v246
	v_permlane16_swap_b32_e32 v245, v247
	global_store_dwordx4 v[144:145], v[244:247], off
	s_waitcnt lgkmcnt(0)
	v_sub_f32_e32 v17, v87, v40
	v_sub_f32_e32 v16, v86, v40
	v_sub_f32_e32 v67, v89, v40
	v_sub_f32_e32 v66, v88, v40
	v_pk_mul_f32 v[66:67], v[40:41], v[66:67] op_sel:[1,0]
	v_pk_mul_f32 v[16:17], v[40:41], v[16:17] op_sel:[1,0]
	v_pk_fma_f32 v[40:41], v[124:125], v[66:67], v[128:129]
	v_pk_fma_f32 v[16:17], v[122:123], v[16:17], v[126:127]
	v_cndmask_b32_e32 v40, v1, v40, vcc
	v_cndmask_b32_e32 v41, v1, v41, vcc
	v_cndmask_b32_e32 v16, v1, v16, vcc
	v_cndmask_b32_e32 v17, v1, v17, vcc
	v_cvt_pk_bf16_f32 v250, v16, v17
	v_cvt_pk_bf16_f32 v251, v40, v41
	ds_read_b64 v[40:41], v146 offset:8448
	v_mov_b32_e32 v248, v228
	v_mov_b32_e32 v249, v229
	s_nop 1
	v_permlane16_swap_b32_e32 v248, v250
	v_permlane16_swap_b32_e32 v249, v251
	global_store_dwordx4 v[114:115], v[248:251], off
	s_waitcnt lgkmcnt(0)
	v_sub_f32_e32 v17, v111, v40
	v_sub_f32_e32 v16, v110, v40
	v_sub_f32_e32 v67, v113, v40
	v_sub_f32_e32 v66, v112, v40
	v_pk_mul_f32 v[66:67], v[40:41], v[66:67] op_sel:[1,0]
	v_pk_mul_f32 v[16:17], v[40:41], v[16:17] op_sel:[1,0]
	v_pk_fma_f32 v[40:41], v[124:125], v[66:67], v[128:129]
	v_pk_fma_f32 v[16:17], v[122:123], v[16:17], v[126:127]
	v_cndmask_b32_e32 v40, v1, v40, vcc
	v_cndmask_b32_e32 v41, v1, v41, vcc
	v_cndmask_b32_e32 v16, v1, v16, vcc
	v_cndmask_b32_e32 v17, v1, v17, vcc
	v_cvt_pk_bf16_f32 v246, v16, v17
	v_cvt_pk_bf16_f32 v247, v40, v41
	ds_read_b64 v[40:41], v146 offset:8576
	v_mov_b32_e32 v244, v230
	v_mov_b32_e32 v245, v231
	s_nop 1
	v_permlane16_swap_b32_e32 v244, v246
	v_permlane16_swap_b32_e32 v245, v247
	global_store_dwordx4 v[108:109], v[244:247], off
	s_waitcnt lgkmcnt(0)
	v_sub_f32_e32 v17, v119, v40
	v_sub_f32_e32 v16, v118, v40
	v_sub_f32_e32 v67, v121, v40
	v_sub_f32_e32 v66, v120, v40
	v_pk_mul_f32 v[66:67], v[40:41], v[66:67] op_sel:[1,0]
	v_pk_mul_f32 v[16:17], v[40:41], v[16:17] op_sel:[1,0]
	v_pk_fma_f32 v[40:41], v[124:125], v[66:67], v[128:129]
	v_pk_fma_f32 v[16:17], v[122:123], v[16:17], v[126:127]
	v_cndmask_b32_e32 v40, v1, v40, vcc
	v_cndmask_b32_e32 v41, v1, v41, vcc
	v_cndmask_b32_e32 v16, v1, v16, vcc
	v_cndmask_b32_e32 v17, v1, v17, vcc
	v_cvt_pk_bf16_f32 v250, v16, v17
	v_cvt_pk_bf16_f32 v251, v40, v41
	ds_read_b64 v[40:41], v146 offset:9216
	v_mov_b32_e32 v248, v232
	v_mov_b32_e32 v249, v233
	s_nop 1
	v_permlane16_swap_b32_e32 v248, v250
	v_permlane16_swap_b32_e32 v249, v251
	global_store_dwordx4 v[106:107], v[248:251], off
	s_waitcnt lgkmcnt(0)
	v_sub_f32_e32 v17, v99, v40
	v_sub_f32_e32 v16, v98, v40
	v_sub_f32_e32 v67, v101, v40
	v_sub_f32_e32 v66, v100, v40
	v_pk_mul_f32 v[66:67], v[40:41], v[66:67] op_sel:[1,0]
	v_pk_mul_f32 v[16:17], v[40:41], v[16:17] op_sel:[1,0]
	v_pk_fma_f32 v[40:41], v[124:125], v[66:67], v[128:129]
	v_pk_fma_f32 v[16:17], v[122:123], v[16:17], v[126:127]
	v_cndmask_b32_e32 v40, v1, v40, vcc
	v_cndmask_b32_e32 v41, v1, v41, vcc
	v_cndmask_b32_e32 v16, v1, v16, vcc
	v_cndmask_b32_e32 v17, v1, v17, vcc
	v_cvt_pk_bf16_f32 v246, v16, v17
	v_cvt_pk_bf16_f32 v247, v40, v41
	ds_read_b64 v[40:41], v146 offset:9344
	v_mov_b32_e32 v244, v234
	v_mov_b32_e32 v245, v235
	s_nop 1
	v_permlane16_swap_b32_e32 v244, v246
	v_permlane16_swap_b32_e32 v245, v247
	global_store_dwordx4 v[102:103], v[244:247], off
	s_waitcnt lgkmcnt(0)
; __device__ __forceinline__ unsigned cvt_pk_bf16(float lo, float hi) { unsigned r; asm volatile("v_cvt_pk_bf16_f32 %0, %1, %2" : "=v"(r) : "v"(lo), "v"(hi)); return r; }
;     __device__ __forceinline__ void fused(f32x4 (&acc)[2][2][4][2], const Unit& u, int wr, int wc, int fr, int fq, PG8_LAS unsigned char* lds, int wid, int lane) const {
;     ...
;         const float qnan = __builtin_nanf("");
; #pragma unroll
;         for (int bj = 0; bj < 2; ++bj)
; #pragma unroll
;             for (int n = 0; n < 2; ++n) { const f32x4 gv = *(const f32x4*)(g + col0 + bj * HALF + n * 16), bv = *(const f32x4*)(b + col0 + bj * HALF + n * 16);
; #pragma unroll
;                 for (int ai = 0; ai < 2; ++ai)
; #pragma unroll
;                     for (int m = 0; m < 4; ++m) { const int r = ai * HALF + wr * 64 + m * 16 + fr; const f32x2v sr = S[r]; const size_t o = (size_t)(rowoff + u.pm * BM + r) * ldc + col0 + bj * HALF + n * 16;
;                         f32x4 v = (acc[ai][bj][m][n] - sr.x) * sr.y * gv + bv; if (bad) v = (f32x4){qnan, qnan, qnan, qnan};
;                         if (outf) *(f32x4*)(outf + o) = v; else { u32x2 w; w.x = cvt_pk_bf16(v[0], v[1]); w.y = cvt_pk_bf16(v[2], v[3]); *(u32x2*)(outb + o) = w; } } }
	v_sub_f32_e32 v17, v75, v40
	v_sub_f32_e32 v16, v74, v40
	v_sub_f32_e32 v67, v77, v40
	v_sub_f32_e32 v66, v76, v40
	v_pk_mul_f32 v[66:67], v[40:41], v[66:67] op_sel:[1,0]
	v_pk_mul_f32 v[16:17], v[40:41], v[16:17] op_sel:[1,0]
	v_pk_fma_f32 v[40:41], v[124:125], v[66:67], v[128:129]
	v_pk_fma_f32 v[16:17], v[122:123], v[16:17], v[126:127]
	v_cndmask_b32_e32 v40, v1, v40, vcc
	v_cndmask_b32_e32 v41, v1, v41, vcc
	v_cndmask_b32_e32 v16, v1, v16, vcc
	v_cndmask_b32_e32 v17, v1, v17, vcc
	v_cvt_pk_bf16_f32 v250, v16, v17
	v_cvt_pk_bf16_f32 v251, v40, v41
	ds_read_b64 v[40:41], v146 offset:9472
	v_mov_b32_e32 v248, v236
	v_mov_b32_e32 v249, v237
	s_nop 1
	v_permlane16_swap_b32_e32 v248, v250
	v_permlane16_swap_b32_e32 v249, v251
	global_store_dwordx4 v[78:79], v[248:251], off
	s_waitcnt lgkmcnt(0)
	v_sub_f32_e32 v17, v35, v40
	v_sub_f32_e32 v16, v34, v40
	v_sub_f32_e32 v35, v37, v40
	v_sub_f32_e32 v34, v36, v40
	v_pk_mul_f32 v[34:35], v[40:41], v[34:35] op_sel:[1,0]
	v_pk_mul_f32 v[16:17], v[40:41], v[16:17] op_sel:[1,0]
	v_pk_fma_f32 v[34:35], v[124:125], v[34:35], v[128:129]
	v_pk_fma_f32 v[16:17], v[122:123], v[16:17], v[126:127]
	v_cndmask_b32_e32 v34, v1, v34, vcc
	v_cndmask_b32_e32 v35, v1, v35, vcc
	v_cndmask_b32_e32 v16, v1, v16, vcc
	v_cndmask_b32_e32 v17, v1, v17, vcc
	v_cvt_pk_bf16_f32 v246, v16, v17
	v_cvt_pk_bf16_f32 v247, v34, v35
	ds_read_b64 v[34:35], v146 offset:9600
	v_mov_b32_e32 v244, v238
	v_mov_b32_e32 v245, v239
	s_nop 1
	v_permlane16_swap_b32_e32 v244, v246
	v_permlane16_swap_b32_e32 v245, v247
	global_store_dwordx4 v[38:39], v[244:247], off
	s_waitcnt lgkmcnt(0)
	v_sub_f32_e32 v11, v11, v34
	v_sub_f32_e32 v10, v10, v34
	v_sub_f32_e32 v13, v13, v34
	v_sub_f32_e32 v12, v12, v34
	v_pk_mul_f32 v[10:11], v[34:35], v[10:11] op_sel:[1,0]
	v_pk_mul_f32 v[12:13], v[34:35], v[12:13] op_sel:[1,0]
	v_pk_fma_f32 v[10:11], v[122:123], v[10:11], v[126:127]
	v_pk_fma_f32 v[12:13], v[124:125], v[12:13], v[128:129]
	v_cndmask_b32_e32 v10, v1, v10, vcc
	v_cndmask_b32_e32 v11, v1, v11, vcc
	v_cndmask_b32_e32 v12, v1, v12, vcc
	v_cndmask_b32_e32 v13, v1, v13, vcc
	v_cvt_pk_bf16_f32 v250, v10, v11
	v_cvt_pk_bf16_f32 v251, v12, v13
	v_mov_b32_e32 v248, v240
	v_mov_b32_e32 v249, v241
	s_nop 1
	v_permlane16_swap_b32_e32 v248, v250
	v_permlane16_swap_b32_e32 v249, v251
	global_store_dwordx4 v[14:15], v[248:251], off
	global_load_dwordx4 v[10:13], v[140:141], off offset:512
	s_nop 0
	global_load_dwordx4 v[34:37], v[142:143], off offset:512
	ds_read_b64 v[16:17], v146 offset:8192
	s_waitcnt lgkmcnt(0)
	v_sub_f32_e32 v41, v43, v16
	v_sub_f32_e32 v40, v42, v16
	v_sub_f32_e32 v43, v45, v16
	v_sub_f32_e32 v42, v44, v16
	v_pk_mul_f32 v[42:43], v[16:17], v[42:43] op_sel:[1,0]
	v_pk_mul_f32 v[16:17], v[16:17], v[40:41] op_sel:[1,0]
	s_waitcnt vmcnt(0)
	v_pk_fma_f32 v[40:41], v[12:13], v[42:43], v[36:37]
	v_pk_fma_f32 v[16:17], v[10:11], v[16:17], v[34:35]
	v_cndmask_b32_e32 v40, v1, v40, vcc
	v_cndmask_b32_e32 v41, v1, v41, vcc
	v_cndmask_b32_e32 v16, v1, v16, vcc
	v_cndmask_b32_e32 v17, v1, v17, vcc
	v_cvt_pk_bf16_f32 v226, v16, v17
	v_cvt_pk_bf16_f32 v227, v40, v41
	ds_read_b64 v[40:41], v146 offset:8320
	s_waitcnt lgkmcnt(0)
	v_sub_f32_e32 v17, v51, v40
	v_sub_f32_e32 v16, v50, v40
	v_sub_f32_e32 v43, v53, v40
	v_sub_f32_e32 v42, v52, v40
	v_pk_mul_f32 v[42:43], v[40:41], v[42:43] op_sel:[1,0]
	v_pk_mul_f32 v[16:17], v[40:41], v[16:17] op_sel:[1,0]
	v_pk_fma_f32 v[40:41], v[12:13], v[42:43], v[36:37]
	v_pk_fma_f32 v[16:17], v[10:11], v[16:17], v[34:35]
	v_cndmask_b32_e32 v40, v1, v40, vcc
	v_cndmask_b32_e32 v41, v1, v41, vcc
	v_cndmask_b32_e32 v16, v1, v16, vcc
	v_cndmask_b32_e32 v17, v1, v17, vcc
	v_cvt_pk_bf16_f32 v228, v16, v17
	v_cvt_pk_bf16_f32 v229, v40, v41
	ds_read_b64 v[40:41], v146 offset:8448
	s_waitcnt lgkmcnt(0)
	v_sub_f32_e32 v17, v71, v40
	v_sub_f32_e32 v16, v70, v40
	v_sub_f32_e32 v43, v73, v40
	v_sub_f32_e32 v42, v72, v40
	v_pk_mul_f32 v[42:43], v[40:41], v[42:43] op_sel:[1,0]
	v_pk_mul_f32 v[16:17], v[40:41], v[16:17] op_sel:[1,0]
	v_pk_fma_f32 v[40:41], v[12:13], v[42:43], v[36:37]
	v_pk_fma_f32 v[16:17], v[10:11], v[16:17], v[34:35]
	v_cndmask_b32_e32 v40, v1, v40, vcc
	v_cndmask_b32_e32 v41, v1, v41, vcc
	v_cndmask_b32_e32 v16, v1, v16, vcc
	v_cndmask_b32_e32 v17, v1, v17, vcc
	v_cvt_pk_bf16_f32 v230, v16, v17
	v_cvt_pk_bf16_f32 v231, v40, v41
	ds_read_b64 v[40:41], v146 offset:8576
	s_waitcnt lgkmcnt(0)
	v_sub_f32_e32 v17, v95, v40
	v_sub_f32_e32 v16, v94, v40
	v_sub_f32_e32 v43, v97, v40
	v_sub_f32_e32 v42, v96, v40
	v_pk_mul_f32 v[42:43], v[40:41], v[42:43] op_sel:[1,0]
	v_pk_mul_f32 v[16:17], v[40:41], v[16:17] op_sel:[1,0]
	v_pk_fma_f32 v[40:41], v[12:13], v[42:43], v[36:37]
	v_pk_fma_f32 v[16:17], v[10:11], v[16:17], v[34:35]
	v_cndmask_b32_e32 v40, v1, v40, vcc
	v_cndmask_b32_e32 v41, v1, v41, vcc
	v_cndmask_b32_e32 v16, v1, v16, vcc
	v_cndmask_b32_e32 v17, v1, v17, vcc
	v_cvt_pk_bf16_f32 v232, v16, v17
	v_cvt_pk_bf16_f32 v233, v40, v41
	ds_read_b64 v[40:41], v146 offset:9216
	s_waitcnt lgkmcnt(0)
	v_sub_f32_e32 v17, v91, v40
	v_sub_f32_e32 v16, v90, v40
	v_sub_f32_e32 v43, v93, v40
	v_sub_f32_e32 v42, v92, v40
	v_pk_mul_f32 v[42:43], v[40:41], v[42:43] op_sel:[1,0]
	v_pk_mul_f32 v[16:17], v[40:41], v[16:17] op_sel:[1,0]
	v_pk_fma_f32 v[40:41], v[12:13], v[42:43], v[36:37]
	v_pk_fma_f32 v[16:17], v[10:11], v[16:17], v[34:35]
	v_cndmask_b32_e32 v40, v1, v40, vcc
	v_cndmask_b32_e32 v41, v1, v41, vcc
	v_cndmask_b32_e32 v16, v1, v16, vcc
	v_cndmask_b32_e32 v17, v1, v17, vcc
	v_cvt_pk_bf16_f32 v234, v16, v17
	v_cvt_pk_bf16_f32 v235, v40, v41
	ds_read_b64 v[40:41], v146 offset:9344
	s_waitcnt lgkmcnt(0)
; __device__ __forceinline__ unsigned cvt_pk_bf16(float lo, float hi) { unsigned r; asm volatile("v_cvt_pk_bf16_f32 %0, %1, %2" : "=v"(r) : "v"(lo), "v"(hi)); return r; }
;     __device__ __forceinline__ void fused(f32x4 (&acc)[2][2][4][2], const Unit& u, int wr, int wc, int fr, int fq, PG8_LAS unsigned char* lds, int wid, int lane) const {
;     ...
;         const float qnan = __builtin_nanf("");
; #pragma unroll
;         for (int bj = 0; bj < 2; ++bj)
; #pragma unroll
;             for (int n = 0; n < 2; ++n) { const f32x4 gv = *(const f32x4*)(g + col0 + bj * HALF + n * 16), bv = *(const f32x4*)(b + col0 + bj * HALF + n * 16);
; #pragma unroll
;                 for (int ai = 0; ai < 2; ++ai)
; #pragma unroll
;                     for (int m = 0; m < 4; ++m) { const int r = ai * HALF + wr * 64 + m * 16 + fr; const f32x2v sr = S[r]; const size_t o = (size_t)(rowoff + u.pm * BM + r) * ldc + col0 + bj * HALF + n * 16;
;                         f32x4 v = (acc[ai][bj][m][n] - sr.x) * sr.y * gv + bv; if (bad) v = (f32x4){qnan, qnan, qnan, qnan};
;                         if (outf) *(f32x4*)(outf + o) = v; else { u32x2 w; w.x = cvt_pk_bf16(v[0], v[1]); w.y = cvt_pk_bf16(v[2], v[3]); *(u32x2*)(outb + o) = w; } } }
	v_sub_f32_e32 v17, v63, v40
	v_sub_f32_e32 v16, v62, v40
	v_sub_f32_e32 v43, v65, v40
	v_sub_f32_e32 v42, v64, v40
	v_pk_mul_f32 v[42:43], v[40:41], v[42:43] op_sel:[1,0]
	v_pk_mul_f32 v[16:17], v[40:41], v[16:17] op_sel:[1,0]
	v_pk_fma_f32 v[40:41], v[12:13], v[42:43], v[36:37]
	v_pk_fma_f32 v[16:17], v[10:11], v[16:17], v[34:35]
	v_cndmask_b32_e32 v40, v1, v40, vcc
	v_cndmask_b32_e32 v41, v1, v41, vcc
	v_cndmask_b32_e32 v16, v1, v16, vcc
	v_cndmask_b32_e32 v17, v1, v17, vcc
	v_cvt_pk_bf16_f32 v236, v16, v17
	v_cvt_pk_bf16_f32 v237, v40, v41
	ds_read_b64 v[40:41], v146 offset:9472
	s_waitcnt lgkmcnt(0)
	v_sub_f32_e32 v17, v27, v40
	v_sub_f32_e32 v16, v26, v40
	v_sub_f32_e32 v27, v29, v40
	v_sub_f32_e32 v26, v28, v40
	v_pk_mul_f32 v[26:27], v[40:41], v[26:27] op_sel:[1,0]
	v_pk_mul_f32 v[16:17], v[40:41], v[16:17] op_sel:[1,0]
	v_pk_fma_f32 v[26:27], v[12:13], v[26:27], v[36:37]
	v_pk_fma_f32 v[16:17], v[10:11], v[16:17], v[34:35]
	v_cndmask_b32_e32 v26, v1, v26, vcc
	v_cndmask_b32_e32 v27, v1, v27, vcc
	v_cndmask_b32_e32 v16, v1, v16, vcc
	v_cndmask_b32_e32 v17, v1, v17, vcc
	v_cvt_pk_bf16_f32 v238, v16, v17
	v_cvt_pk_bf16_f32 v239, v26, v27
	ds_read_b64 v[26:27], v146 offset:9600
	s_waitcnt lgkmcnt(0)
	v_sub_f32_e32 v7, v7, v26
	v_sub_f32_e32 v6, v6, v26
	v_sub_f32_e32 v9, v9, v26
	v_sub_f32_e32 v8, v8, v26
	v_pk_mul_f32 v[6:7], v[26:27], v[6:7] op_sel:[1,0]
	v_pk_mul_f32 v[8:9], v[26:27], v[8:9] op_sel:[1,0]
	v_pk_fma_f32 v[6:7], v[10:11], v[6:7], v[34:35]
	v_pk_fma_f32 v[8:9], v[12:13], v[8:9], v[36:37]
	v_cndmask_b32_e32 v6, v1, v6, vcc
	v_cndmask_b32_e32 v7, v1, v7, vcc
	v_cndmask_b32_e32 v8, v1, v8, vcc
	v_cndmask_b32_e32 v9, v1, v9, vcc
	v_cvt_pk_bf16_f32 v240, v6, v7
	v_cvt_pk_bf16_f32 v241, v8, v9
	global_load_dwordx4 v[6:9], v[140:141], off offset:576
	s_nop 0
	global_load_dwordx4 v[10:13], v[142:143], off offset:576
	ds_read_b64 v[16:17], v146 offset:8192
	s_waitcnt lgkmcnt(0)
	v_sub_f32_e32 v19, v19, v16
	v_sub_f32_e32 v18, v18, v16
	v_sub_f32_e32 v21, v21, v16
	v_sub_f32_e32 v20, v20, v16
	v_pk_mul_f32 v[20:21], v[16:17], v[20:21] op_sel:[1,0]
	v_pk_mul_f32 v[16:17], v[16:17], v[18:19] op_sel:[1,0]
	s_waitcnt vmcnt(0)
	v_pk_fma_f32 v[18:19], v[8:9], v[20:21], v[12:13]
	v_pk_fma_f32 v[16:17], v[6:7], v[16:17], v[10:11]
	v_cndmask_b32_e32 v18, v1, v18, vcc
	v_cndmask_b32_e32 v19, v1, v19, vcc
	v_cndmask_b32_e32 v16, v1, v16, vcc
	v_cndmask_b32_e32 v17, v1, v17, vcc
	v_cvt_pk_bf16_f32 v246, v16, v17
	v_cvt_pk_bf16_f32 v247, v18, v19
	ds_read_b64 v[18:19], v146 offset:8320
	v_mov_b32_e32 v244, v226
	v_mov_b32_e32 v245, v227
	s_nop 1
	v_permlane16_swap_b32_e32 v244, v246
	v_permlane16_swap_b32_e32 v245, v247
	global_store_dwordx4 v[144:145], v[244:247], off offset:256
	s_waitcnt lgkmcnt(0)
	v_sub_f32_e32 v17, v31, v18
	v_sub_f32_e32 v16, v30, v18
	v_sub_f32_e32 v21, v33, v18
	v_sub_f32_e32 v20, v32, v18
	v_pk_mul_f32 v[20:21], v[18:19], v[20:21] op_sel:[1,0]
	v_pk_mul_f32 v[16:17], v[18:19], v[16:17] op_sel:[1,0]
	v_pk_fma_f32 v[18:19], v[8:9], v[20:21], v[12:13]
	v_pk_fma_f32 v[16:17], v[6:7], v[16:17], v[10:11]
	v_cndmask_b32_e32 v18, v1, v18, vcc
	v_cndmask_b32_e32 v19, v1, v19, vcc
	v_cndmask_b32_e32 v16, v1, v16, vcc
	v_cndmask_b32_e32 v17, v1, v17, vcc
	v_cvt_pk_bf16_f32 v250, v16, v17
	v_cvt_pk_bf16_f32 v251, v18, v19
	ds_read_b64 v[18:19], v146 offset:8448
	v_mov_b32_e32 v248, v228
	v_mov_b32_e32 v249, v229
	s_nop 1
	v_permlane16_swap_b32_e32 v248, v250
	v_permlane16_swap_b32_e32 v249, v251
	global_store_dwordx4 v[114:115], v[248:251], off offset:256
	s_waitcnt lgkmcnt(0)
	v_sub_f32_e32 v17, v47, v18
	v_sub_f32_e32 v16, v46, v18
	v_sub_f32_e32 v21, v49, v18
	v_sub_f32_e32 v20, v48, v18
	v_pk_mul_f32 v[20:21], v[18:19], v[20:21] op_sel:[1,0]
	v_pk_mul_f32 v[16:17], v[18:19], v[16:17] op_sel:[1,0]
	v_pk_fma_f32 v[18:19], v[8:9], v[20:21], v[12:13]
	v_pk_fma_f32 v[16:17], v[6:7], v[16:17], v[10:11]
	v_cndmask_b32_e32 v18, v1, v18, vcc
	v_cndmask_b32_e32 v19, v1, v19, vcc
	v_cndmask_b32_e32 v16, v1, v16, vcc
	v_cndmask_b32_e32 v17, v1, v17, vcc
	v_cvt_pk_bf16_f32 v246, v16, v17
	v_cvt_pk_bf16_f32 v247, v18, v19
	ds_read_b64 v[18:19], v146 offset:8576
	v_mov_b32_e32 v244, v230
	v_mov_b32_e32 v245, v231
	s_nop 1
	v_permlane16_swap_b32_e32 v244, v246
	v_permlane16_swap_b32_e32 v245, v247
	global_store_dwordx4 v[108:109], v[244:247], off offset:256
	s_waitcnt lgkmcnt(0)
; __device__ __forceinline__ unsigned cvt_pk_bf16(float lo, float hi) { unsigned r; asm volatile("v_cvt_pk_bf16_f32 %0, %1, %2" : "=v"(r) : "v"(lo), "v"(hi)); return r; }
;     __device__ __forceinline__ void fused(f32x4 (&acc)[2][2][4][2], const Unit& u, int wr, int wc, int fr, int fq, PG8_LAS unsigned char* lds, int wid, int lane) const {
;     ...
;         const float qnan = __builtin_nanf("");
; #pragma unroll
;         for (int bj = 0; bj < 2; ++bj)
; #pragma unroll
;             for (int n = 0; n < 2; ++n) { const f32x4 gv = *(const f32x4*)(g + col0 + bj * HALF + n * 16), bv = *(const f32x4*)(b + col0 + bj * HALF + n * 16);
; #pragma unroll
;                 for (int ai = 0; ai < 2; ++ai)
; #pragma unroll
;                     for (int m = 0; m < 4; ++m) { const int r = ai * HALF + wr * 64 + m * 16 + fr; const f32x2v sr = S[r]; const size_t o = (size_t)(rowoff + u.pm * BM + r) * ldc + col0 + bj * HALF + n * 16;
;                         f32x4 v = (acc[ai][bj][m][n] - sr.x) * sr.y * gv + bv; if (bad) v = (f32x4){qnan, qnan, qnan, qnan};
;                         if (outf) *(f32x4*)(outf + o) = v; else { u32x2 w; w.x = cvt_pk_bf16(v[0], v[1]); w.y = cvt_pk_bf16(v[2], v[3]); *(u32x2*)(outb + o) = w; } } }
	v_sub_f32_e32 v17, v55, v18
	v_sub_f32_e32 v16, v54, v18
	v_sub_f32_e32 v21, v57, v18
	v_sub_f32_e32 v20, v56, v18
	v_pk_mul_f32 v[20:21], v[18:19], v[20:21] op_sel:[1,0]
	v_pk_mul_f32 v[16:17], v[18:19], v[16:17] op_sel:[1,0]
	v_pk_fma_f32 v[18:19], v[8:9], v[20:21], v[12:13]
	v_pk_fma_f32 v[16:17], v[6:7], v[16:17], v[10:11]
	v_cndmask_b32_e32 v18, v1, v18, vcc
	v_cndmask_b32_e32 v19, v1, v19, vcc
	v_cndmask_b32_e32 v16, v1, v16, vcc
	v_cndmask_b32_e32 v17, v1, v17, vcc
	v_cvt_pk_bf16_f32 v250, v16, v17
	v_cvt_pk_bf16_f32 v251, v18, v19
	ds_read_b64 v[18:19], v146 offset:9216
	v_mov_b32_e32 v248, v232
	v_mov_b32_e32 v249, v233
	s_nop 1
	v_permlane16_swap_b32_e32 v248, v250
	v_permlane16_swap_b32_e32 v249, v251
	global_store_dwordx4 v[106:107], v[248:251], off offset:256
	s_waitcnt lgkmcnt(0)
	v_sub_f32_e32 v17, v83, v18
	v_sub_f32_e32 v16, v82, v18
	v_sub_f32_e32 v21, v85, v18
	v_sub_f32_e32 v20, v84, v18
	v_pk_mul_f32 v[20:21], v[18:19], v[20:21] op_sel:[1,0]
	v_pk_mul_f32 v[16:17], v[18:19], v[16:17] op_sel:[1,0]
	v_pk_fma_f32 v[18:19], v[8:9], v[20:21], v[12:13]
	v_pk_fma_f32 v[16:17], v[6:7], v[16:17], v[10:11]
	v_cndmask_b32_e32 v18, v1, v18, vcc
	v_cndmask_b32_e32 v19, v1, v19, vcc
	v_cndmask_b32_e32 v16, v1, v16, vcc
	v_cndmask_b32_e32 v17, v1, v17, vcc
	v_cvt_pk_bf16_f32 v246, v16, v17
	v_cvt_pk_bf16_f32 v247, v18, v19
	ds_read_b64 v[18:19], v146 offset:9344
	v_mov_b32_e32 v244, v234
	v_mov_b32_e32 v245, v235
	s_nop 1
	v_permlane16_swap_b32_e32 v244, v246
	v_permlane16_swap_b32_e32 v245, v247
	global_store_dwordx4 v[102:103], v[244:247], off offset:256
	s_waitcnt lgkmcnt(0)
	v_sub_f32_e32 v17, v59, v18
	v_sub_f32_e32 v16, v58, v18
	v_sub_f32_e32 v21, v61, v18
	v_sub_f32_e32 v20, v60, v18
	v_pk_mul_f32 v[20:21], v[18:19], v[20:21] op_sel:[1,0]
	v_pk_mul_f32 v[16:17], v[18:19], v[16:17] op_sel:[1,0]
	v_pk_fma_f32 v[18:19], v[8:9], v[20:21], v[12:13]
	v_pk_fma_f32 v[16:17], v[6:7], v[16:17], v[10:11]
	v_cndmask_b32_e32 v18, v1, v18, vcc
	v_cndmask_b32_e32 v19, v1, v19, vcc
	v_cndmask_b32_e32 v16, v1, v16, vcc
	v_cndmask_b32_e32 v17, v1, v17, vcc
	v_cvt_pk_bf16_f32 v250, v16, v17
	v_cvt_pk_bf16_f32 v251, v18, v19
	ds_read_b64 v[18:19], v146 offset:9472
	v_mov_b32_e32 v248, v236
	v_mov_b32_e32 v249, v237
	s_nop 1
	v_permlane16_swap_b32_e32 v248, v250
	v_permlane16_swap_b32_e32 v249, v251
	global_store_dwordx4 v[78:79], v[248:251], off offset:256
	s_waitcnt lgkmcnt(0)
	v_sub_f32_e32 v17, v23, v18
	v_sub_f32_e32 v16, v22, v18
	v_sub_f32_e32 v21, v25, v18
	v_sub_f32_e32 v20, v24, v18
	v_pk_mul_f32 v[20:21], v[18:19], v[20:21] op_sel:[1,0]
	v_pk_mul_f32 v[16:17], v[18:19], v[16:17] op_sel:[1,0]
	v_pk_fma_f32 v[18:19], v[8:9], v[20:21], v[12:13]
	v_pk_fma_f32 v[16:17], v[6:7], v[16:17], v[10:11]
	v_cndmask_b32_e32 v18, v1, v18, vcc
	v_cndmask_b32_e32 v19, v1, v19, vcc
	v_cndmask_b32_e32 v16, v1, v16, vcc
	v_cndmask_b32_e32 v17, v1, v17, vcc
	v_cvt_pk_bf16_f32 v246, v16, v17
	v_cvt_pk_bf16_f32 v247, v18, v19
	ds_read_b64 v[18:19], v146 offset:9600
	v_mov_b32_e32 v244, v238
	v_mov_b32_e32 v245, v239
	s_nop 1
	v_permlane16_swap_b32_e32 v244, v246
	v_permlane16_swap_b32_e32 v245, v247
	global_store_dwordx4 v[38:39], v[244:247], off offset:256
	s_waitcnt lgkmcnt(0)
	v_sub_f32_e32 v3, v3, v18
	v_sub_f32_e32 v2, v2, v18
	v_sub_f32_e32 v5, v5, v18
	v_sub_f32_e32 v4, v4, v18
	v_pk_mul_f32 v[2:3], v[18:19], v[2:3] op_sel:[1,0]
	v_pk_mul_f32 v[4:5], v[18:19], v[4:5] op_sel:[1,0]
	v_pk_fma_f32 v[2:3], v[6:7], v[2:3], v[10:11]
	v_pk_fma_f32 v[4:5], v[8:9], v[4:5], v[12:13]
	v_cndmask_b32_e32 v2, v1, v2, vcc
	v_cndmask_b32_e32 v4, v1, v4, vcc
	v_cndmask_b32_e32 v5, v1, v5, vcc
	v_cndmask_b32_e32 v1, v1, v3, vcc
	v_cvt_pk_bf16_f32 v250, v2, v1
	v_cvt_pk_bf16_f32 v251, v4, v5
	v_mov_b32_e32 v248, v240
	v_mov_b32_e32 v249, v241
	s_nop 1
	v_permlane16_swap_b32_e32 v248, v250
	v_permlane16_swap_b32_e32 v249, v251
	global_store_dwordx4 v[14:15], v[248:251], off offset:256
	v_sub_u32_e32 v138, v138, v252

; template <class Epi, class Sched, bool ALIGN_EPI = false, bool SP2 = false>
; __device__ __forceinline__ void gemm_phase(PG8_LAS unsigned char* lds, const Gemm g, const Sched& S, const Epi& E) {
;     ...
;     const int K = g.K, LD = g.ld ? g.ld : g.K, nt = K / BK;
;     unsigned voffA[2], voffB[2];
; #pragma unroll
;     for (int i = 0; i < 2; ++i) { int R, C; stage_rc(tid * 16 + i * 8192, R, C); const int Rb = Epi::PERM ? ((R & ~31) + perm32(R & 31)) : R;
;         voffA[i] = (unsigned)(R * LD + C) * 2u; voffB[i] = (unsigned)(Rb * LD + C) * 2u; }
;     const size_t kstep = (size_t)(BK * 2);
;     const size_t hstep = (size_t)HALF * LD * 2;
;     const size_t tstep = 2 * hstep;
;     const unsigned ldsw = (unsigned)wid * 1024u;
;     const int aoff = lds_byte(wr * 64 + fr, fq * 8), boff = lds_byte(wc * 32 + fr, fq * 8);
;     ...
;     Unit cur, nxt; int ui = 0;
;     if (!S.next(0, cur)) return;
;     f32x4 acc[2][2][4][2];
; #pragma unroll
;     for (int a = 0; a < 2; ++a)
; #pragma unroll
;         for (int b = 0; b < 2; ++b)
; #pragma unroll
;             for (int m = 0; m < 4; ++m)
; #pragma unroll
;                 for (int n = 0; n < 2; ++n) acc[a][b][m][n] = (f32x4){0.f, 0.f, 0.f, 0.f};
;     bf16x8 At[4][2], B0[2][2], B1[2][2];
;     const size_t sstep = (size_t)K * 2;
;     const char* cA = (const char*)g.A + (size_t)cur.pm * tstep + (size_t)cur.pk * sstep; const char* cB = (const char*)g.Bt + (size_t)cur.pn * tstep + (size_t)cur.pk * sstep;
;     S.a_ready(cur);
;     if constexpr (SP2) {
;         PG8_STAGE(PG8_SB(0, 0), cB, voffB); PG8_STAGE(PG8_SB(0, 1), cB + hstep, voffB); PG8_STAGE(PG8_SA(0, 0), cA, voffA); PG8_STAGE(PG8_SA(0, 1), cA + hstep, voffA);
;         if (wr == 1) PG8_BAR;
;         PG8_WAIT_V(2); PG8_BAR;
;         PG8_STAGE(PG8_SB(1, 0), cB + kstep, voffB); PG8_STAGE(PG8_SA(1, 0), cA + kstep, voffA); PG8_STAGE(PG8_SB(1, 1), cB + hstep + kstep, voffB);
;         PG8_WAIT_V(6); PG8_BAR;
;     } else {
;         PG8_STAGE(PG8_SB(0, 0), cB, voffB); PG8_STAGE(PG8_SA(0, 0), cA, voffA); PG8_STAGE(PG8_SB(0, 1), cB + hstep, voffB); PG8_STAGE(PG8_SA(0, 1), cA + hstep, voffA);
;         if (wr == 1) PG8_BAR;
;         PG8_WAIT_V(4); PG8_BAR;
;         PG8_STAGE(PG8_SB(1, 0), cB + kstep, voffB); PG8_STAGE(PG8_SA(1, 0), cA + kstep, voffA); PG8_STAGE(PG8_SB(1, 1), cB + hstep + kstep, voffB);
;         PG8_WAIT_V(6); PG8_BAR;
;     }
.LBB0_778:
	v_mov_b32_e32 v14, v0
	s_add_u32 s1, s44, 0x51300000
	v_bfe_i32 v3, v14, 27, 1
	v_lshlrev_b32_e32 v1, 4, v14
	v_lshrrev_b32_e32 v3, 22, v3
	v_add_u32_e32 v3, v1, v3
	v_and_b32_e32 v3, 0xfffffc00, v3
	v_sub_u32_e32 v3, v1, v3
	v_lshrrev_b32_e32 v4, 4, v3
	v_ashrrev_i32_e32 v2, 31, v14
	v_bitop3_b32 v3, v4, v3, 32 bitop3:0x6c
	v_lshrrev_b32_e32 v2, 26, v2
	v_ashrrev_i32_e32 v5, 31, v3
	v_add_u32_e32 v2, v14, v2
	v_lshrrev_b32_e32 v5, 26, v5
	v_ashrrev_i32_e32 v2, 6, v2
	v_add_u32_e32 v5, v3, v5
	v_lshlrev_b32_e32 v4, 3, v2
	v_ashrrev_i32_e32 v6, 6, v5
	v_and_b32_e32 v5, 0xc0, v5
	v_and_b32_e32 v4, 0x7ffffff0, v4
	v_lshlrev_b32_e32 v2, 5, v2
	v_sub_u32_e32 v3, v3, v5
	v_mov_b32_e32 v5, 1
	v_add_u32_e32 v4, v6, v4
	v_and_b32_e32 v2, 32, v2
	v_ashrrev_i16_sdwa v3, v5, sext(v3) dst_sel:DWORD dst_unused:UNUSED_PAD src0_sel:DWORD src1_sel:BYTE_0
	v_bfe_i32 v6, v3, 0, 16
	v_mad_u64_u32 v[2:3], s[12:13], v4, s10, v[2:3]
	v_add_u32_e32 v1, 0x2000, v1
	v_add_lshl_u32 v130, v2, v6, 1
	v_ashrrev_i32_e32 v2, 31, v1
	v_lshrrev_b32_e32 v2, 22, v2
	v_add_u32_e32 v2, v1, v2
	v_ashrrev_i32_e32 v2, 10, v2
	v_mul_i32_i24_e32 v3, 0x400, v2
	v_sub_u32_e32 v1, v1, v3
	v_lshrrev_b32_e32 v3, 4, v1
	v_bitop3_b32 v1, v3, v1, 32 bitop3:0x6c
	v_ashrrev_i32_e32 v4, 31, v1
	v_lshrrev_b32_e32 v4, 26, v4
	v_lshlrev_b32_e32 v3, 3, v2
	v_add_u32_e32 v4, v1, v4
	s_addc_u32 s26, s45, 0
	v_and_b32_e32 v3, 0x7ffffff0, v3
	v_ashrrev_i32_e32 v6, 6, v4
	v_lshlrev_b32_e32 v2, 5, v2
	s_add_u32 s27, s44, 0x2d00000
	v_add_u32_e32 v3, v6, v3
	v_and_b32_e32 v2, 32, v2
	s_addc_u32 s28, s45, 0
	s_add_i32 s4, s33, 0x98
	v_mad_u64_u32 v[2:3], s[12:13], v3, s10, v[2:3]
	s_and_b32 s11, s33, 7
	s_bfe_u32 s12, s4, 0x50003
	s_mulk_i32 s11, 0x63
	s_add_i32 s11, s12, s11
	s_mul_i32 s12, s11, 0x556
	s_lshr_b32 s12, s12, 16
	s_lshl_b32 s13, s12, 3
	s_mul_i32 s12, s12, 48
	s_sub_i32 s12, s11, s12
	s_and_b32 s11, s12, 7
	s_or_b32 s11, s11, s13
	s_bfe_u32 s18, s12, 0xd0003
	s_and_b32 s12, s11, 0x7fff
	v_readfirstlane_b32 s2, v14
	s_mul_i32 s13, s9, s12
	s_mul_hi_u32 s14, s8, s12
	s_ashr_i32 s5, s2, 6
	s_add_i32 s14, s14, s13
	s_mul_i32 s15, s8, s12
	s_mul_i32 s12, s9, s18
	s_mul_hi_u32 s13, s8, s18
	s_ashr_i32 s3, s2, 8
	s_lshl_b32 s29, s5, 10
	s_add_i32 s13, s13, s12
	s_mul_i32 s12, s8, s18
	v_and_b32_e32 v4, 0xc0, v4
	s_add_u32 s24, s27, s12
	v_sub_u32_e32 v1, v1, v4
	s_addc_u32 s25, s28, s13
	s_cmp_gt_u32 s18, 3
	s_cselect_b32 s98, 0x100, 0
	s_add_u32 s24, s24, s98
	s_addc_u32 s25, s25, 0
	s_add_i32 s30, s29, 0
	v_ashrrev_i16_sdwa v1, v5, sext(v1) dst_sel:DWORD dst_unused:UNUSED_PAD src0_sel:DWORD src1_sel:BYTE_0
	s_add_i32 m0, s30, 0x10000
	v_bfe_i32 v1, v1, 0, 16
	global_load_lds_dwordx4 v130, s[24:25]
	s_add_i32 m0, s30, 0x12000
	v_add_lshl_u32 v132, v2, v1, 1
	s_add_u32 s12, s24, s6
	global_load_lds_dwordx4 v132, s[24:25]
	s_addc_u32 s13, s25, s7
	s_add_i32 m0, s30, 0x14000
	v_mov_b32_e32 v131, 0
	global_load_lds_dwordx4 v130, s[12:13]
	s_add_i32 m0, s30, 0x16000
	s_add_u32 s22, s1, s15
	s_addc_u32 s23, s26, s14
	s_cmp_gt_u32 s18, 3
	s_cselect_b32 s98, 0x100, 0
	s_add_u32 s22, s22, s98
	s_addc_u32 s23, s23, 0
	s_add_i32 s31, s30, 0x2000
	global_load_lds_dwordx4 v132, s[12:13]
	s_mov_b32 m0, s30
	s_add_u32 s14, s22, s6
	global_load_lds_dwordx4 v130, s[22:23]
	s_mov_b32 m0, s31
	s_addc_u32 s15, s23, s7
	s_add_i32 s34, s30, 0x4000
	global_load_lds_dwordx4 v132, s[22:23]
	s_mov_b32 m0, s34
	s_add_i32 s35, s30, 0x6000
	global_load_lds_dwordx4 v130, s[14:15]
	s_mov_b32 m0, s35
	v_mov_b32_e32 v133, v131
	global_load_lds_dwordx4 v132, s[14:15]
	s_cmp_eq_u32 s3, 1
	s_mov_b32 s36, 0
	v_lshl_add_u64 v[12:13], s[24:25], 0, v[130:131]
	v_lshl_add_u64 v[10:11], s[24:25], 0, v[132:133]
	v_lshl_add_u64 v[4:5], s[12:13], 0, v[130:131]
	v_lshl_add_u64 v[2:3], s[12:13], 0, v[132:133]
	v_lshl_add_u64 v[6:7], s[22:23], 0, v[130:131]
	s_cselect_b64 s[12:13], -1, 0
	s_cmp_lg_u32 s3, 1
	v_lshl_add_u64 v[8:9], s[22:23], 0, v[132:133]
	s_cbranch_scc1 .LBB0_780
	s_barrier
.LBB0_780:
	s_and_b32 s37, s4, 0xff
	s_add_u32 s14, s44, 0x52400000
	s_mov_b64 s[16:17], 0x80
	s_addc_u32 s15, s45, 0
	s_add_i32 m0, s30, 0x18000
	v_lshl_add_u64 v[12:13], v[12:13], 0, s[16:17]
	s_waitcnt vmcnt(2)
	s_barrier
	global_load_lds_dwordx4 v[12:13], off
	v_lshl_add_u64 v[10:11], v[10:11], 0, s[16:17]
	s_add_i32 m0, s30, 0x1a000
	s_add_i32 s38, s30, 0x8000
	global_load_lds_dwordx4 v[10:11], off
	v_lshl_add_u64 v[6:7], v[6:7], 0, s[16:17]
	s_mov_b32 m0, s38
	s_add_i32 s39, s30, 0xa000
	global_load_lds_dwordx4 v[6:7], off
	v_lshl_add_u64 v[6:7], v[8:9], 0, s[16:17]
	s_mov_b32 m0, s39
	v_lshl_add_u64 v[4:5], v[4:5], 0, s[16:17]
	global_load_lds_dwordx4 v[6:7], off
	s_add_i32 m0, s30, 0x1c000
	v_lshl_add_u64 v[2:3], v[2:3], 0, s[16:17]
	global_load_lds_dwordx4 v[4:5], off
	s_add_i32 m0, s30, 0x1e000
	s_and_b32 s53, 0xffff, s11
	global_load_lds_dwordx4 v[2:3], off
	v_bfe_u32 v2, v14, 4, 2
	v_and_b32_e32 v3, 15, v14
	v_lshlrev_b32_e32 v4, 4, v2
	v_lshl_or_b32 v1, s3, 6, v3
	v_lshl_or_b32 v3, v3, 6, v4
	v_lshlrev_b32_e32 v4, 2, v14
	s_lshl_b32 s3, s3, 13
	v_and_b32_e32 v4, 32, v4
	v_bitop3_b32 v5, v3, s3, v4 bitop3:0xde
	s_lshl_b32 s3, s5, 5
	s_and_b32 s3, s3, 0x60
	s_lshl_b32 s4, s3, 7
	s_and_b32 s52, 0xffff, s18
	s_cmp_gt_i32 s10, 63
	s_cselect_b64 s[10:11], -1, 0
	s_mov_b32 s40, 0
	s_waitcnt vmcnt(6)
	s_cmpk_lt_u32 s2, 0x100
	v_bitop3_b32 v142, v3, s4, v4 bitop3:0xde
	s_cselect_b64 s[18:19], -1, 0
	s_add_i32 s43, 0, 0x10000
	s_add_i32 s48, 0, 0x14000
	s_ashr_i32 s41, s64, 31
	v_lshl_or_b32 v143, v2, 2, s3
	v_lshl_add_u64 v[134:135], s[6:7], 0, v[130:131]
	v_lshl_add_u64 v[136:137], s[6:7], 0, v[132:133]
	v_mov_b64_e32 v[138:139], 0x318
	v_mov_b64_e32 v[140:141], 0x317
	s_movk_i32 s42, 0x64
	v_add_u32_e32 v144, s43, v142
	v_add_u32_e32 v145, s48, v142
	v_add_u32_e32 v146, 0, v5
	s_movk_i32 s49, 0xc00
	s_barrier
	s_branch .LBB0_783

; template <class Epi, class Sched, bool ALIGN_EPI = false, bool SP2 = false>
; __device__ __forceinline__ void gemm_phase(PG8_LAS unsigned char* lds, const Gemm g, const Sched& S, const Epi& E) {
;     ...
;         const bool has_next = S.next(ui + 1, nxt);
;         const char* nA = has_next ? (const char*)g.A + (size_t)nxt.pm * tstep + (size_t)nxt.pk * sstep : cA; const char* nB = has_next ? (const char*)g.Bt + (size_t)nxt.pn * tstep + (size_t)nxt.pk * sstep : cB;
.LBB0_785:
	s_nop 0
	v_cndmask_b32_e64 v2, 0, 1, s[4:5]
	v_cmp_ne_u32_e64 s[2:3], 1, v2
	s_andn2_b64 vcc, exec, s[4:5]
	s_mov_b64 s[4:5], s[22:23]
	s_cbranch_vccnz .LBB0_787
	s_ashr_i32 s4, s51, 31
	s_mul_hi_u32 s5, s8, s51
	s_mul_i32 s4, s8, s4
	s_add_i32 s4, s5, s4
	s_mul_i32 s5, s9, s51
	s_add_i32 s5, s4, s5
	s_mul_i32 s4, s8, s51
	s_add_u32 s4, s1, s4
	s_addc_u32 s5, s26, s5
	s_cmp_gt_u32 s50, 3
	s_cselect_b32 s98, 0x100, 0
	s_add_u32 s4, s4, s98
	s_addc_u32 s5, s5, 0
.LBB0_787:
	s_and_b64 vcc, exec, s[2:3]
	s_mov_b64 s[20:21], s[24:25]
	s_cbranch_vccnz .LBB0_789
	s_ashr_i32 s20, s50, 31
	s_mul_hi_u32 s21, s8, s50
	s_mul_i32 s20, s8, s20
	s_add_i32 s20, s21, s20
	s_mul_i32 s21, s9, s50
	s_add_i32 s21, s20, s21
	s_mul_i32 s20, s8, s50
	s_add_u32 s20, s27, s20
	s_addc_u32 s21, s28, s21
	s_cmp_gt_u32 s50, 3
	s_cselect_b32 s98, 0x100, 0
	s_add_u32 s20, s20, s98
	s_addc_u32 s21, s21, 0

; #define PG8_STAGE(bufoff, gbase, voff) do { _Pragma("unroll") for (int _i = 0; _i < 2; ++_i) \
;         __builtin_amdgcn_global_load_lds((const unsigned*)((const char*)(gbase) + (voff)[_i]), (PG8_LAS unsigned*)(lds + (bufoff) + ldsw + _i * 8192), 16, 0, 0); } while (0)
; #define PG8_LDA(dst, b, h) do { _Pragma("unroll") for (int m = 0; m < 4; ++m) _Pragma("unroll") for (int k = 0; k < 2; ++k) dst[m][k] = *(const PG8_LAS bf16x8*)(lds + PG8_SA(b, h) + aoff + m * 2048 + k * 1024); } while (0)
; #define PG8_LDB(dst, b, h) do { _Pragma("unroll") for (int n = 0; n < 2; ++n) _Pragma("unroll") for (int k = 0; k < 2; ++k) dst[n][k] = *(const PG8_LAS bf16x8*)(lds + PG8_SB(b, h) + boff + n * 2048 + k * 1024); } while (0)
; #define PG8_MMA(ai, bj, At, Bt) do { __builtin_amdgcn_s_setprio(1); _Pragma("unroll") for (int m = 0; m < 4; ++m) _Pragma("unroll") for (int n = 0; n < 2; ++n) _Pragma("unroll") for (int k = 0; k < 2; ++k) \
;         acc[ai][bj][m][n] = __builtin_amdgcn_mfma_f32_16x16x32_bf16(Bt[n][k], At[m][k], acc[ai][bj][m][n], 0, 0, 0); __builtin_amdgcn_s_setprio(0); } while (0)
; #define PG8_WAIT_V(n) asm volatile("s_waitcnt vmcnt(" #n ")" ::: "memory")
; #define PG8_WAIT_L(n) asm volatile("s_waitcnt lgkmcnt(" #n ")" ::: "memory")
; #define PG8_BAR __builtin_amdgcn_s_barrier()
; #define PG8_SCHED __builtin_amdgcn_sched_barrier(0)
; template <class Epi, class Sched, bool ALIGN_EPI = false, bool SP2 = false>
; __device__ __forceinline__ void gemm_phase(PG8_LAS unsigned char* lds, const Gemm g, const Sched& S, const Epi& E) {
;     ...
;             if constexpr (SP2) {
;             PG8_LDB(B0, 0, 0); PG8_LDB(B1, 0, 1); PG8_SCHED; PG8_LDA(At, 0, 0); PG8_STAGE(PG8_SA(1, 1), a1 + hstep, voffA);
;             PG8_WAIT_V(8); PG8_WAIT_L(0); PG8_BAR; PG8_MMA(0, 0, At, B0); PG8_MMA(0, 1, At, B1); PG8_BAR; PG8_SCHED;
;             PG8_LDA(At, 0, 1); PG8_STAGE(PG8_SB(0, 0), b2, voffB); PG8_STAGE(PG8_SB(0, 1), b2 + hstep, voffB); PG8_STAGE(PG8_SA(0, 0), a2, voffA);
;             PG8_WAIT_V(8); PG8_WAIT_L(0); PG8_BAR; PG8_MMA(1, 0, At, B0); PG8_MMA(1, 1, At, B1); PG8_BAR; PG8_SCHED;
.LBB0_791:
	ds_read_b128 v[148:151], v144
	ds_read_b128 v[152:155], v144 offset:1024
	ds_read_b128 v[156:159], v144 offset:2048
	ds_read_b128 v[160:163], v144 offset:3072
	ds_read_b128 v[164:167], v145
	ds_read_b128 v[168:171], v145 offset:1024
	ds_read_b128 v[172:175], v145 offset:2048
	ds_read_b128 v[176:179], v145 offset:3072
	s_add_i32 s56, s24, 2
	s_add_u32 s57, s22, 0x80
	s_addc_u32 s25, s23, 0
	s_cmp_eq_u32 s40, s24
	s_cselect_b32 s24, s4, s57
	s_cselect_b32 s25, s5, s25
	s_cselect_b32 s59, s21, s55
	s_cselect_b32 s58, s20, s54
	v_lshl_add_u64 v[184:185], s[22:23], 0, v[134:135]
	s_add_i32 m0, s30, 0xc000
	ds_read_b128 v[180:183], v146
	ds_read_b128 v[188:191], v146 offset:1024
	ds_read_b128 v[192:195], v146 offset:2048
	ds_read_b128 v[196:199], v146 offset:3072
	ds_read_b128 v[200:203], v146 offset:4096
	ds_read_b128 v[204:207], v146 offset:5120
	ds_read_b128 v[208:211], v146 offset:6144
	ds_read_b128 v[212:215], v146 offset:7168
	global_load_lds_dwordx4 v[184:185], off
	v_lshl_add_u64 v[184:185], s[22:23], 0, v[136:137]
	s_add_i32 m0, s30, 0xe000
	s_nop 0
	global_load_lds_dwordx4 v[184:185], off
	s_waitcnt vmcnt(8)
	s_waitcnt lgkmcnt(0)
	s_barrier
	s_setprio 1
	s_waitcnt lgkmcnt(0)
	v_mfma_f32_16x16x32_bf16 v[126:129], v[148:151], v[180:183], v[126:129]
	v_mfma_f32_16x16x32_bf16 v[122:125], v[156:159], v[180:183], v[122:125]
	v_mfma_f32_16x16x32_bf16 v[110:113], v[148:151], v[192:195], v[110:113]
	v_mfma_f32_16x16x32_bf16 v[106:109], v[156:159], v[192:195], v[106:109]
	v_mfma_f32_16x16x32_bf16 v[94:97], v[148:151], v[200:203], v[94:97]
	v_mfma_f32_16x16x32_bf16 v[90:93], v[156:159], v[200:203], v[90:93]
	v_mfma_f32_16x16x32_bf16 v[78:81], v[148:151], v[208:211], v[78:81]
	v_mfma_f32_16x16x32_bf16 v[74:77], v[156:159], v[208:211], v[74:77]
	v_mfma_f32_16x16x32_bf16 v[126:129], v[152:155], v[188:191], v[126:129]
	v_mfma_f32_16x16x32_bf16 v[122:125], v[160:163], v[188:191], v[122:125]
	v_mfma_f32_16x16x32_bf16 v[110:113], v[152:155], v[196:199], v[110:113]
	v_mfma_f32_16x16x32_bf16 v[106:109], v[160:163], v[196:199], v[106:109]
	v_mfma_f32_16x16x32_bf16 v[94:97], v[152:155], v[204:207], v[94:97]
	v_mfma_f32_16x16x32_bf16 v[90:93], v[160:163], v[204:207], v[90:93]
	v_mfma_f32_16x16x32_bf16 v[78:81], v[152:155], v[212:215], v[78:81]
	v_mfma_f32_16x16x32_bf16 v[74:77], v[160:163], v[212:215], v[74:77]
	s_setprio 0
	s_setprio 1
	v_mfma_f32_16x16x32_bf16 v[118:121], v[164:167], v[180:183], v[118:121]
	v_mfma_f32_16x16x32_bf16 v[114:117], v[172:175], v[180:183], v[114:117]
	v_mfma_f32_16x16x32_bf16 v[102:105], v[164:167], v[192:195], v[102:105]
	v_mfma_f32_16x16x32_bf16 v[98:101], v[172:175], v[192:195], v[98:101]
	v_mfma_f32_16x16x32_bf16 v[86:89], v[164:167], v[200:203], v[86:89]
	v_mfma_f32_16x16x32_bf16 v[82:85], v[172:175], v[200:203], v[82:85]
	v_mfma_f32_16x16x32_bf16 v[70:73], v[164:167], v[208:211], v[70:73]
	v_mfma_f32_16x16x32_bf16 v[66:69], v[172:175], v[208:211], v[66:69]
	v_mfma_f32_16x16x32_bf16 v[118:121], v[168:171], v[188:191], v[118:121]
	v_mfma_f32_16x16x32_bf16 v[114:117], v[176:179], v[188:191], v[114:117]
	v_mfma_f32_16x16x32_bf16 v[102:105], v[168:171], v[196:199], v[102:105]
	v_mfma_f32_16x16x32_bf16 v[98:101], v[176:179], v[196:199], v[98:101]
	v_mfma_f32_16x16x32_bf16 v[86:89], v[168:171], v[204:207], v[86:89]
	v_mfma_f32_16x16x32_bf16 v[82:85], v[176:179], v[204:207], v[82:85]
	v_mfma_f32_16x16x32_bf16 v[70:73], v[168:171], v[212:215], v[70:73]
	v_mfma_f32_16x16x32_bf16 v[66:69], v[176:179], v[212:215], v[66:69]
	s_setprio 0
	s_barrier
	s_add_i32 s57, s43, s29
	v_lshl_add_u64 v[184:185], s[58:59], 0, v[130:131]
	s_mov_b32 m0, s57
	ds_read_b128 v[180:183], v146 offset:16384
	ds_read_b128 v[188:191], v146 offset:17408
	ds_read_b128 v[192:195], v146 offset:18432
	ds_read_b128 v[196:199], v146 offset:19456
	ds_read_b128 v[200:203], v146 offset:20480
	ds_read_b128 v[204:207], v146 offset:21504
	ds_read_b128 v[208:211], v146 offset:22528
	ds_read_b128 v[212:215], v146 offset:23552
	global_load_lds_dwordx4 v[184:185], off
	s_add_i32 m0, s57, 0x2000
	v_lshl_add_u64 v[216:217], s[58:59], 0, v[132:133]
	s_add_u32 s58, s58, s6
	s_addc_u32 s59, s59, s7
	s_add_i32 s57, s48, s29
	global_load_lds_dwordx4 v[216:217], off
	v_lshl_add_u64 v[218:219], s[58:59], 0, v[130:131]
	s_mov_b32 m0, s57
	v_lshl_add_u64 v[220:221], s[58:59], 0, v[132:133]
	global_load_lds_dwordx4 v[218:219], off
	s_add_i32 m0, s57, 0x2000
	v_lshl_add_u64 v[222:223], s[24:25], 0, v[130:131]
	global_load_lds_dwordx4 v[220:221], off
	s_mov_b32 m0, s30
	v_lshl_add_u64 v[224:225], s[24:25], 0, v[132:133]
	global_load_lds_dwordx4 v[222:223], off
	s_mov_b32 m0, s31
	s_nop 0
	global_load_lds_dwordx4 v[224:225], off
	s_waitcnt vmcnt(8)
	s_waitcnt lgkmcnt(0)
	s_barrier
; #define PG8_STAGE(bufoff, gbase, voff) do { _Pragma("unroll") for (int _i = 0; _i < 2; ++_i) \
;         __builtin_amdgcn_global_load_lds((const unsigned*)((const char*)(gbase) + (voff)[_i]), (PG8_LAS unsigned*)(lds + (bufoff) + ldsw + _i * 8192), 16, 0, 0); } while (0)
; #define PG8_LDA(dst, b, h) do { _Pragma("unroll") for (int m = 0; m < 4; ++m) _Pragma("unroll") for (int k = 0; k < 2; ++k) dst[m][k] = *(const PG8_LAS bf16x8*)(lds + PG8_SA(b, h) + aoff + m * 2048 + k * 1024); } while (0)
; #define PG8_LDB(dst, b, h) do { _Pragma("unroll") for (int n = 0; n < 2; ++n) _Pragma("unroll") for (int k = 0; k < 2; ++k) dst[n][k] = *(const PG8_LAS bf16x8*)(lds + PG8_SB(b, h) + boff + n * 2048 + k * 1024); } while (0)
; #define PG8_MMA(ai, bj, At, Bt) do { __builtin_amdgcn_s_setprio(1); _Pragma("unroll") for (int m = 0; m < 4; ++m) _Pragma("unroll") for (int n = 0; n < 2; ++n) _Pragma("unroll") for (int k = 0; k < 2; ++k) \
;         acc[ai][bj][m][n] = __builtin_amdgcn_mfma_f32_16x16x32_bf16(Bt[n][k], At[m][k], acc[ai][bj][m][n], 0, 0, 0); __builtin_amdgcn_s_setprio(0); } while (0)
; #define PG8_WAIT_V(n) asm volatile("s_waitcnt vmcnt(" #n ")" ::: "memory")
; #define PG8_WAIT_L(n) asm volatile("s_waitcnt lgkmcnt(" #n ")" ::: "memory")
; #define PG8_BAR __builtin_amdgcn_s_barrier()
; #define PG8_SCHED __builtin_amdgcn_sched_barrier(0)
; template <class Epi, class Sched, bool ALIGN_EPI = false, bool SP2 = false>
; __device__ __forceinline__ void gemm_phase(PG8_LAS unsigned char* lds, const Gemm g, const Sched& S, const Epi& E) {
;     ...
;             PG8_WAIT_V(8); PG8_WAIT_L(0); PG8_BAR; PG8_MMA(1, 0, At, B0); PG8_MMA(1, 1, At, B1); PG8_BAR; PG8_SCHED;
;             PG8_LDB(B0, 1, 0); PG8_LDB(B1, 1, 1); PG8_SCHED; PG8_LDA(At, 1, 0); PG8_STAGE(PG8_SA(0, 1), a2 + hstep, voffA);
;             PG8_WAIT_V(8); PG8_WAIT_L(0); PG8_BAR; PG8_MMA(0, 0, At, B0); PG8_MMA(0, 1, At, B1); PG8_BAR; PG8_SCHED;
	s_setprio 1
	s_waitcnt lgkmcnt(0)
	v_mfma_f32_16x16x32_bf16 v[62:65], v[148:151], v[180:183], v[62:65]
	v_mfma_f32_16x16x32_bf16 v[58:61], v[156:159], v[180:183], v[58:61]
	v_mfma_f32_16x16x32_bf16 v[46:49], v[148:151], v[192:195], v[46:49]
	v_mfma_f32_16x16x32_bf16 v[42:45], v[156:159], v[192:195], v[42:45]
	v_mfma_f32_16x16x32_bf16 v[30:33], v[148:151], v[200:203], v[30:33]
	v_mfma_f32_16x16x32_bf16 v[26:29], v[156:159], v[200:203], v[26:29]
	v_mfma_f32_16x16x32_bf16 v[14:17], v[148:151], v[208:211], v[14:17]
	v_mfma_f32_16x16x32_bf16 v[10:13], v[156:159], v[208:211], v[10:13]
	v_mfma_f32_16x16x32_bf16 v[62:65], v[152:155], v[188:191], v[62:65]
	v_mfma_f32_16x16x32_bf16 v[58:61], v[160:163], v[188:191], v[58:61]
	v_mfma_f32_16x16x32_bf16 v[46:49], v[152:155], v[196:199], v[46:49]
	v_mfma_f32_16x16x32_bf16 v[42:45], v[160:163], v[196:199], v[42:45]
	v_mfma_f32_16x16x32_bf16 v[30:33], v[152:155], v[204:207], v[30:33]
	v_mfma_f32_16x16x32_bf16 v[26:29], v[160:163], v[204:207], v[26:29]
	v_mfma_f32_16x16x32_bf16 v[14:17], v[152:155], v[212:215], v[14:17]
	v_mfma_f32_16x16x32_bf16 v[10:13], v[160:163], v[212:215], v[10:13]
	s_setprio 0
	s_setprio 1
	v_mfma_f32_16x16x32_bf16 v[54:57], v[164:167], v[180:183], v[54:57]
	v_mfma_f32_16x16x32_bf16 v[50:53], v[172:175], v[180:183], v[50:53]
	v_mfma_f32_16x16x32_bf16 v[38:41], v[164:167], v[192:195], v[38:41]
	v_mfma_f32_16x16x32_bf16 v[34:37], v[172:175], v[192:195], v[34:37]
	v_mfma_f32_16x16x32_bf16 v[22:25], v[164:167], v[200:203], v[22:25]
	v_mfma_f32_16x16x32_bf16 v[18:21], v[172:175], v[200:203], v[18:21]
	v_mfma_f32_16x16x32_bf16 v[6:9], v[164:167], v[208:211], v[6:9]
	v_mfma_f32_16x16x32_bf16 v[2:5], v[172:175], v[208:211], v[2:5]
	v_mfma_f32_16x16x32_bf16 v[54:57], v[168:171], v[188:191], v[54:57]
	v_mfma_f32_16x16x32_bf16 v[50:53], v[176:179], v[188:191], v[50:53]
	v_mfma_f32_16x16x32_bf16 v[38:41], v[168:171], v[196:199], v[38:41]
	v_mfma_f32_16x16x32_bf16 v[34:37], v[176:179], v[196:199], v[34:37]
	v_mfma_f32_16x16x32_bf16 v[22:25], v[168:171], v[204:207], v[22:25]
	v_mfma_f32_16x16x32_bf16 v[18:21], v[176:179], v[204:207], v[18:21]
	v_mfma_f32_16x16x32_bf16 v[6:9], v[168:171], v[212:215], v[6:9]
	v_mfma_f32_16x16x32_bf16 v[2:5], v[176:179], v[212:215], v[2:5]
	s_setprio 0
	s_barrier
	s_add_i32 s57, 0, 0x18000
	v_add_u32_e32 v147, s57, v142
	s_add_i32 s58, 0, 0x1c000
	ds_read_b128 v[148:151], v147
	ds_read_b128 v[152:155], v147 offset:1024
	ds_read_b128 v[156:159], v147 offset:2048
	ds_read_b128 v[160:163], v147 offset:3072
	v_add_u32_e32 v147, s58, v142
	ds_read_b128 v[164:167], v147
	ds_read_b128 v[168:171], v147 offset:1024
	ds_read_b128 v[172:175], v147 offset:2048
	ds_read_b128 v[176:179], v147 offset:3072
	s_add_u32 s24, s24, s6
	s_addc_u32 s25, s25, s7
	s_mov_b32 m0, s34
	v_lshl_add_u64 v[226:227], s[24:25], 0, v[130:131]
	ds_read_b128 v[180:183], v146 offset:32768
	ds_read_b128 v[188:191], v146 offset:33792
	ds_read_b128 v[192:195], v146 offset:34816
	ds_read_b128 v[196:199], v146 offset:35840
	ds_read_b128 v[200:203], v146 offset:36864
	ds_read_b128 v[204:207], v146 offset:37888
	ds_read_b128 v[208:211], v146 offset:38912
	ds_read_b128 v[212:215], v146 offset:39936
	global_load_lds_dwordx4 v[226:227], off
	v_lshl_add_u64 v[226:227], s[24:25], 0, v[132:133]
	s_mov_b32 m0, s35
	s_nop 0
	global_load_lds_dwordx4 v[226:227], off
	s_waitcnt vmcnt(8)
	s_waitcnt lgkmcnt(0)
	s_barrier
	s_setprio 1
	s_waitcnt lgkmcnt(0)
	v_mfma_f32_16x16x32_bf16 v[126:129], v[148:151], v[180:183], v[126:129]
	v_mfma_f32_16x16x32_bf16 v[122:125], v[156:159], v[180:183], v[122:125]
	v_mfma_f32_16x16x32_bf16 v[110:113], v[148:151], v[192:195], v[110:113]
	v_mfma_f32_16x16x32_bf16 v[106:109], v[156:159], v[192:195], v[106:109]
	v_mfma_f32_16x16x32_bf16 v[94:97], v[148:151], v[200:203], v[94:97]
	v_mfma_f32_16x16x32_bf16 v[90:93], v[156:159], v[200:203], v[90:93]
	v_mfma_f32_16x16x32_bf16 v[78:81], v[148:151], v[208:211], v[78:81]
	v_mfma_f32_16x16x32_bf16 v[74:77], v[156:159], v[208:211], v[74:77]
	v_mfma_f32_16x16x32_bf16 v[126:129], v[152:155], v[188:191], v[126:129]
	v_mfma_f32_16x16x32_bf16 v[122:125], v[160:163], v[188:191], v[122:125]
	v_mfma_f32_16x16x32_bf16 v[110:113], v[152:155], v[196:199], v[110:113]
	v_mfma_f32_16x16x32_bf16 v[106:109], v[160:163], v[196:199], v[106:109]
	v_mfma_f32_16x16x32_bf16 v[94:97], v[152:155], v[204:207], v[94:97]
	v_mfma_f32_16x16x32_bf16 v[90:93], v[160:163], v[204:207], v[90:93]
	v_mfma_f32_16x16x32_bf16 v[78:81], v[152:155], v[212:215], v[78:81]
	v_mfma_f32_16x16x32_bf16 v[74:77], v[160:163], v[212:215], v[74:77]
	s_setprio 0
	s_setprio 1
	v_mfma_f32_16x16x32_bf16 v[118:121], v[164:167], v[180:183], v[118:121]
	v_mfma_f32_16x16x32_bf16 v[114:117], v[172:175], v[180:183], v[114:117]
	v_mfma_f32_16x16x32_bf16 v[102:105], v[164:167], v[192:195], v[102:105]
	v_mfma_f32_16x16x32_bf16 v[98:101], v[172:175], v[192:195], v[98:101]
	v_mfma_f32_16x16x32_bf16 v[86:89], v[164:167], v[200:203], v[86:89]
	v_mfma_f32_16x16x32_bf16 v[82:85], v[172:175], v[200:203], v[82:85]
	v_mfma_f32_16x16x32_bf16 v[70:73], v[164:167], v[208:211], v[70:73]
	v_mfma_f32_16x16x32_bf16 v[66:69], v[172:175], v[208:211], v[66:69]
	v_mfma_f32_16x16x32_bf16 v[118:121], v[168:171], v[188:191], v[118:121]
	v_mfma_f32_16x16x32_bf16 v[114:117], v[176:179], v[188:191], v[114:117]
	v_mfma_f32_16x16x32_bf16 v[102:105], v[168:171], v[196:199], v[102:105]
	v_mfma_f32_16x16x32_bf16 v[98:101], v[176:179], v[196:199], v[98:101]
	v_mfma_f32_16x16x32_bf16 v[86:89], v[168:171], v[204:207], v[86:89]
	v_mfma_f32_16x16x32_bf16 v[82:85], v[176:179], v[204:207], v[82:85]
	v_mfma_f32_16x16x32_bf16 v[70:73], v[168:171], v[212:215], v[70:73]
	v_mfma_f32_16x16x32_bf16 v[66:69], v[176:179], v[212:215], v[66:69]
	s_setprio 0
	s_barrier
; #define PG8_STAGE(bufoff, gbase, voff) do { _Pragma("unroll") for (int _i = 0; _i < 2; ++_i) \
;         __builtin_amdgcn_global_load_lds((const unsigned*)((const char*)(gbase) + (voff)[_i]), (PG8_LAS unsigned*)(lds + (bufoff) + ldsw + _i * 8192), 16, 0, 0); } while (0)
; #define PG8_LDA(dst, b, h) do { _Pragma("unroll") for (int m = 0; m < 4; ++m) _Pragma("unroll") for (int k = 0; k < 2; ++k) dst[m][k] = *(const PG8_LAS bf16x8*)(lds + PG8_SA(b, h) + aoff + m * 2048 + k * 1024); } while (0)
; #define PG8_LDB(dst, b, h) do { _Pragma("unroll") for (int n = 0; n < 2; ++n) _Pragma("unroll") for (int k = 0; k < 2; ++k) dst[n][k] = *(const PG8_LAS bf16x8*)(lds + PG8_SB(b, h) + boff + n * 2048 + k * 1024); } while (0)
; template <class Epi, class Sched, bool ALIGN_EPI = false, bool SP2 = false>
; __device__ __forceinline__ void gemm_phase(PG8_LAS unsigned char* lds, const Gemm g, const Sched& S, const Epi& E) {
;     ...
;         for (int t = 0; t < nt; t += 2) {
;             const bool last = (t == nt - 2);
;             const char* a1 = cA + (size_t)(t + 1) * kstep;
;             const char* a2 = last ? nA : cA + (size_t)(t + 2) * kstep; const char* b2 = last ? nB : cB + (size_t)(t + 2) * kstep;
;             const char* a3 = a2 + kstep; const char* b3 = b2 + kstep;
;             if (last && has_next) S.a_ready(nxt);
;             if constexpr (SP2) {
;             PG8_LDB(B0, 0, 0); PG8_LDB(B1, 0, 1); PG8_SCHED; PG8_LDA(At, 0, 0); PG8_STAGE(PG8_SA(1, 1), a1 + hstep, voffA);
;             PG8_WAIT_V(8); PG8_WAIT_L(0); PG8_BAR; PG8_MMA(0, 0, At, B0); PG8_MMA(0, 1, At, B1); PG8_BAR; PG8_SCHED;
;             PG8_LDA(At, 0, 1); PG8_STAGE(PG8_SB(0, 0), b2, voffB); PG8_STAGE(PG8_SB(0, 1), b2 + hstep, voffB); PG8_STAGE(PG8_SA(0, 0), a2, voffA);
;             PG8_WAIT_V(8); PG8_WAIT_L(0); PG8_BAR; PG8_MMA(1, 0, At, B0); PG8_MMA(1, 1, At, B1); PG8_BAR; PG8_SCHED;
;             PG8_LDB(B0, 1, 0); PG8_LDB(B1, 1, 1); PG8_SCHED; PG8_LDA(At, 1, 0); PG8_STAGE(PG8_SA(0, 1), a2 + hstep, voffA);
;             PG8_WAIT_V(8); PG8_WAIT_L(0); PG8_BAR; PG8_MMA(0, 0, At, B0); PG8_MMA(0, 1, At, B1); PG8_BAR; PG8_SCHED;
;             PG8_LDA(At, 1, 1); PG8_STAGE(PG8_SB(1, 0), b3, voffB); PG8_STAGE(PG8_SB(1, 1), b3 + hstep, voffB); PG8_STAGE(PG8_SA(1, 0), a3, voffA);
;             PG8_WAIT_V(8); PG8_WAIT_L(0); PG8_BAR; PG8_MMA(1, 0, At, B0); PG8_MMA(1, 1, At, B1); PG8_BAR; PG8_SCHED;
	s_add_i32 s24, s57, s29
	v_lshl_add_u64 v[184:185], v[184:185], 0, s[16:17]
	s_mov_b32 m0, s24
	ds_read_b128 v[180:183], v146 offset:49152
	ds_read_b128 v[188:191], v146 offset:50176
	ds_read_b128 v[192:195], v146 offset:51200
	ds_read_b128 v[196:199], v146 offset:52224
	ds_read_b128 v[200:203], v146 offset:53248
	ds_read_b128 v[204:207], v146 offset:54272
	ds_read_b128 v[208:211], v146 offset:55296
	ds_read_b128 v[212:215], v146 offset:56320
	global_load_lds_dwordx4 v[184:185], off
	v_lshl_add_u64 v[184:185], v[216:217], 0, s[16:17]
	s_add_i32 m0, s24, 0x2000
	s_add_i32 s24, s58, s29
	global_load_lds_dwordx4 v[184:185], off
	v_lshl_add_u64 v[184:185], v[218:219], 0, s[16:17]
	s_mov_b32 m0, s24
	s_nop 0
	global_load_lds_dwordx4 v[184:185], off
	v_lshl_add_u64 v[184:185], v[220:221], 0, s[16:17]
	s_add_i32 m0, s24, 0x2000
	s_nop 0
	global_load_lds_dwordx4 v[184:185], off
	v_lshl_add_u64 v[184:185], v[222:223], 0, s[16:17]
	s_mov_b32 m0, s38
	s_nop 0
	global_load_lds_dwordx4 v[184:185], off
	v_lshl_add_u64 v[184:185], v[224:225], 0, s[16:17]
	s_mov_b32 m0, s39
	s_nop 0
	global_load_lds_dwordx4 v[184:185], off
	s_waitcnt vmcnt(8)
	s_waitcnt lgkmcnt(0)
	s_barrier
	s_setprio 1
	s_waitcnt lgkmcnt(0)
	v_mfma_f32_16x16x32_bf16 v[62:65], v[148:151], v[180:183], v[62:65]
	v_mfma_f32_16x16x32_bf16 v[58:61], v[156:159], v[180:183], v[58:61]
	v_mfma_f32_16x16x32_bf16 v[46:49], v[148:151], v[192:195], v[46:49]
	v_mfma_f32_16x16x32_bf16 v[42:45], v[156:159], v[192:195], v[42:45]
	v_mfma_f32_16x16x32_bf16 v[30:33], v[148:151], v[200:203], v[30:33]
	v_mfma_f32_16x16x32_bf16 v[26:29], v[156:159], v[200:203], v[26:29]
	v_mfma_f32_16x16x32_bf16 v[14:17], v[148:151], v[208:211], v[14:17]
	v_mfma_f32_16x16x32_bf16 v[10:13], v[156:159], v[208:211], v[10:13]
	v_mfma_f32_16x16x32_bf16 v[62:65], v[152:155], v[188:191], v[62:65]
	v_mfma_f32_16x16x32_bf16 v[58:61], v[160:163], v[188:191], v[58:61]
	v_mfma_f32_16x16x32_bf16 v[46:49], v[152:155], v[196:199], v[46:49]
	v_mfma_f32_16x16x32_bf16 v[42:45], v[160:163], v[196:199], v[42:45]
	v_mfma_f32_16x16x32_bf16 v[30:33], v[152:155], v[204:207], v[30:33]
	v_mfma_f32_16x16x32_bf16 v[26:29], v[160:163], v[204:207], v[26:29]
	v_mfma_f32_16x16x32_bf16 v[14:17], v[152:155], v[212:215], v[14:17]
	v_mfma_f32_16x16x32_bf16 v[10:13], v[160:163], v[212:215], v[10:13]
	s_setprio 0
	s_setprio 1
	v_mfma_f32_16x16x32_bf16 v[54:57], v[164:167], v[180:183], v[54:57]
	v_mfma_f32_16x16x32_bf16 v[50:53], v[172:175], v[180:183], v[50:53]
	v_mfma_f32_16x16x32_bf16 v[38:41], v[164:167], v[192:195], v[38:41]
	v_mfma_f32_16x16x32_bf16 v[34:37], v[172:175], v[192:195], v[34:37]
	v_mfma_f32_16x16x32_bf16 v[22:25], v[164:167], v[200:203], v[22:25]
	v_mfma_f32_16x16x32_bf16 v[18:21], v[172:175], v[200:203], v[18:21]
	v_mfma_f32_16x16x32_bf16 v[6:9], v[164:167], v[208:211], v[6:9]
	v_mfma_f32_16x16x32_bf16 v[2:5], v[172:175], v[208:211], v[2:5]
	v_mfma_f32_16x16x32_bf16 v[54:57], v[168:171], v[188:191], v[54:57]
	v_mfma_f32_16x16x32_bf16 v[50:53], v[176:179], v[188:191], v[50:53]
	v_mfma_f32_16x16x32_bf16 v[38:41], v[168:171], v[196:199], v[38:41]
	v_mfma_f32_16x16x32_bf16 v[34:37], v[176:179], v[196:199], v[34:37]
	v_mfma_f32_16x16x32_bf16 v[22:25], v[168:171], v[204:207], v[22:25]
	v_mfma_f32_16x16x32_bf16 v[18:21], v[176:179], v[204:207], v[18:21]
	v_mfma_f32_16x16x32_bf16 v[6:9], v[168:171], v[212:215], v[6:9]
	v_mfma_f32_16x16x32_bf16 v[2:5], v[176:179], v[212:215], v[2:5]
	s_setprio 0
	s_barrier
	s_add_u32 s22, s22, 0x100
	s_addc_u32 s23, s23, 0
	s_add_u32 s54, s54, 0x100
	s_addc_u32 s55, s55, 0
	s_cmp_ge_i32 s56, 2
	s_mov_b32 s24, s56
	s_cbranch_scc0 .LBB0_791

; __device__ __forceinline__ unsigned cvt_pk_bf16(float lo, float hi) { unsigned r; asm volatile("v_cvt_pk_bf16_f32 %0, %1, %2" : "=v"(r) : "v"(lo), "v"(hi)); return r; }
;     __device__ __forceinline__ void fused(f32x4 (&acc)[2][2][4][2], const Unit& u, int wr, int wc, int fr, int fq, PG8_LAS unsigned char* lds, int wid, int lane) const {
;     ...
;         const float qnan = __builtin_nanf("");
; #pragma unroll
;         for (int bj = 0; bj < 2; ++bj)
; #pragma unroll
;             for (int n = 0; n < 2; ++n) { const f32x4 gv = *(const f32x4*)(g + col0 + bj * HALF + n * 16), bv = *(const f32x4*)(b + col0 + bj * HALF + n * 16);
; #pragma unroll
;                 for (int ai = 0; ai < 2; ++ai)
; #pragma unroll
;                     for (int m = 0; m < 4; ++m) { const int r = ai * HALF + wr * 64 + m * 16 + fr; const f32x2v sr = S[r]; const size_t o = (size_t)(rowoff + u.pm * BM + r) * ldc + col0 + bj * HALF + n * 16;
;                         f32x4 v = (acc[ai][bj][m][n] - sr.x) * sr.y * gv + bv; if (bad) v = (f32x4){qnan, qnan, qnan, qnan};
;                         if (outf) *(f32x4*)(outf + o) = v; else { u32x2 w; w.x = cvt_pk_bf16(v[0], v[1]); w.y = cvt_pk_bf16(v[2], v[3]); *(u32x2*)(outb + o) = w; } } }
.LBB0_1452:
	s_or_b64 exec, exec, s[6:7]
	v_and_b32_e32 v252, 16, v186
	v_lshrrev_b32_e32 v253, 1, v252
	v_add_u32_e32 v252, v252, v253
	v_add_u32_e32 v138, v138, v252
	v_lshlrev_b64 v[134:135], 2, v[130:131]
	s_waitcnt lgkmcnt(0)
	s_barrier
	v_lshl_add_u64 v[140:141], s[14:15], 0, v[134:135]
	v_lshl_add_u64 v[142:143], s[10:11], 0, v[134:135]
	global_load_dwordx4 v[130:133], v[140:141], off
	global_load_dwordx4 v[134:137], v[142:143], off
	v_lshl_add_u32 v148, v1, 3, 0
	ds_read_b64 v[150:151], v148 offset:8192
	v_add_u32_e32 v146, s28, v1
	v_mov_b32_e32 v1, 0x7fc00000
	s_waitcnt lgkmcnt(1)
	v_cmp_eq_u32_e32 vcc, 0, v144
	v_ashrrev_i32_e32 v147, 31, v146
	s_waitcnt lgkmcnt(0)
	v_sub_f32_e32 v111, v111, v150
	v_sub_f32_e32 v110, v110, v150
	v_sub_f32_e32 v113, v113, v150
	v_sub_f32_e32 v112, v112, v150
	v_pk_mul_f32 v[112:113], v[150:151], v[112:113] op_sel:[1,0]
	v_pk_mul_f32 v[110:111], v[150:151], v[110:111] op_sel:[1,0]
	v_readlane_b32 s4, v254, 13
	v_lshlrev_b64 v[162:163], 11, v[146:147]
	v_readlane_b32 s5, v254, 14
	v_add_u32_e32 v152, 16, v146
	v_ashrrev_i32_e32 v153, 31, v152
	v_lshl_add_u64 v[144:145], s[4:5], 0, v[162:163]
	v_lshl_add_u64 v[144:145], v[144:145], 0, v[138:139]
	v_add_u32_e32 v154, 32, v146
	v_ashrrev_i32_e32 v155, 31, v154
	v_add_u32_e32 v156, 48, v146
	v_ashrrev_i32_e32 v157, 31, v156
	v_add_u32_e32 v158, 0x80, v146
	v_ashrrev_i32_e32 v159, 31, v158
	v_add_u32_e32 v160, 0x90, v146
	v_ashrrev_i32_e32 v161, 31, v160
	s_waitcnt vmcnt(0)
	v_pk_fma_f32 v[110:111], v[130:131], v[110:111], v[134:135]
	v_pk_fma_f32 v[112:113], v[132:133], v[112:113], v[136:137]
	v_cndmask_b32_e32 v110, v1, v110, vcc
	v_cndmask_b32_e32 v112, v1, v112, vcc
	v_cndmask_b32_e32 v113, v1, v113, vcc
	v_cndmask_b32_e32 v111, v1, v111, vcc
	v_cvt_pk_bf16_f32 v226, v110, v111
	v_cvt_pk_bf16_f32 v227, v112, v113
	ds_read_b64 v[112:113], v148 offset:8320
	s_waitcnt lgkmcnt(0)
	v_sub_f32_e32 v111, v119, v112
	v_sub_f32_e32 v110, v118, v112
	v_sub_f32_e32 v119, v121, v112
	v_sub_f32_e32 v118, v120, v112
	v_pk_mul_f32 v[118:119], v[112:113], v[118:119] op_sel:[1,0]
	v_pk_mul_f32 v[110:111], v[112:113], v[110:111] op_sel:[1,0]
	v_pk_fma_f32 v[112:113], v[132:133], v[118:119], v[136:137]
	v_pk_fma_f32 v[110:111], v[130:131], v[110:111], v[134:135]
	v_cndmask_b32_e32 v112, v1, v112, vcc
	v_cndmask_b32_e32 v113, v1, v113, vcc
	v_cndmask_b32_e32 v110, v1, v110, vcc
	v_cndmask_b32_e32 v111, v1, v111, vcc
	v_cvt_pk_bf16_f32 v228, v110, v111
	v_cvt_pk_bf16_f32 v229, v112, v113
	ds_read_b64 v[112:113], v148 offset:8448
	v_lshlrev_b64 v[118:119], 11, v[152:153]
	v_lshl_add_u64 v[118:119], s[4:5], 0, v[118:119]
	v_lshl_add_u64 v[118:119], v[118:119], 0, v[138:139]
	s_waitcnt lgkmcnt(0)
	v_sub_f32_e32 v111, v127, v112
	v_sub_f32_e32 v110, v126, v112
	v_sub_f32_e32 v121, v129, v112
	v_sub_f32_e32 v120, v128, v112
	v_pk_mul_f32 v[110:111], v[112:113], v[110:111] op_sel:[1,0]
	v_pk_mul_f32 v[120:121], v[112:113], v[120:121] op_sel:[1,0]
	v_pk_fma_f32 v[110:111], v[130:131], v[110:111], v[134:135]
	v_pk_fma_f32 v[112:113], v[132:133], v[120:121], v[136:137]
	v_cndmask_b32_e32 v110, v1, v110, vcc
	v_cndmask_b32_e32 v111, v1, v111, vcc
	v_cndmask_b32_e32 v112, v1, v112, vcc
	v_cndmask_b32_e32 v113, v1, v113, vcc
	v_cvt_pk_bf16_f32 v230, v110, v111
	v_cvt_pk_bf16_f32 v231, v112, v113
	ds_read_b64 v[120:121], v148 offset:8576
	v_lshlrev_b64 v[112:113], 11, v[154:155]
	v_lshl_add_u64 v[112:113], s[4:5], 0, v[112:113]
	v_lshl_add_u64 v[112:113], v[112:113], 0, v[138:139]
	s_waitcnt lgkmcnt(0)
	v_sub_f32_e32 v111, v123, v120
	v_sub_f32_e32 v110, v122, v120
	v_sub_f32_e32 v123, v125, v120
	v_sub_f32_e32 v122, v124, v120
	v_pk_mul_f32 v[122:123], v[120:121], v[122:123] op_sel:[1,0]
	v_pk_mul_f32 v[110:111], v[120:121], v[110:111] op_sel:[1,0]
	v_pk_fma_f32 v[120:121], v[132:133], v[122:123], v[136:137]
	v_pk_fma_f32 v[110:111], v[130:131], v[110:111], v[134:135]
	v_cndmask_b32_e32 v122, v1, v120, vcc
	v_cndmask_b32_e32 v121, v1, v121, vcc
	v_cndmask_b32_e32 v110, v1, v110, vcc
	v_cndmask_b32_e32 v111, v1, v111, vcc
	v_cvt_pk_bf16_f32 v232, v110, v111
	v_cvt_pk_bf16_f32 v233, v122, v121
	ds_read_b64 v[122:123], v148 offset:9216
	v_lshlrev_b64 v[110:111], 11, v[156:157]
	v_lshl_add_u64 v[110:111], s[4:5], 0, v[110:111]
	v_lshl_add_u64 v[110:111], v[110:111], 0, v[138:139]
	s_waitcnt lgkmcnt(0)
	v_sub_f32_e32 v105, v105, v122
	v_sub_f32_e32 v104, v104, v122
	v_sub_f32_e32 v103, v103, v122
	v_sub_f32_e32 v102, v102, v122
	v_pk_mul_f32 v[104:105], v[122:123], v[104:105] op_sel:[1,0]
	v_pk_mul_f32 v[102:103], v[122:123], v[102:103] op_sel:[1,0]
	v_pk_fma_f32 v[104:105], v[132:133], v[104:105], v[136:137]
	v_pk_fma_f32 v[102:103], v[130:131], v[102:103], v[134:135]
	v_cndmask_b32_e32 v120, v1, v104, vcc
	v_cndmask_b32_e32 v105, v1, v105, vcc
	v_cndmask_b32_e32 v102, v1, v102, vcc
	v_cndmask_b32_e32 v103, v1, v103, vcc
	v_cvt_pk_bf16_f32 v234, v102, v103
	v_cvt_pk_bf16_f32 v235, v120, v105
	ds_read_b64 v[120:121], v148 offset:9344
	v_lshlrev_b64 v[102:103], 11, v[158:159]
	v_lshl_add_u64 v[102:103], s[4:5], 0, v[102:103]
	v_lshl_add_u64 v[102:103], v[102:103], 0, v[138:139]
	s_waitcnt lgkmcnt(0)
	v_sub_f32_e32 v85, v85, v120
	v_sub_f32_e32 v84, v84, v120
	v_sub_f32_e32 v83, v83, v120
	v_sub_f32_e32 v82, v82, v120
	v_pk_mul_f32 v[84:85], v[120:121], v[84:85] op_sel:[1,0]
	v_pk_mul_f32 v[82:83], v[120:121], v[82:83] op_sel:[1,0]
	v_pk_fma_f32 v[84:85], v[132:133], v[84:85], v[136:137]
	v_pk_fma_f32 v[82:83], v[130:131], v[82:83], v[134:135]
	v_cndmask_b32_e32 v104, v1, v84, vcc
	v_cndmask_b32_e32 v85, v1, v85, vcc
	v_cndmask_b32_e32 v82, v1, v82, vcc
	v_cndmask_b32_e32 v83, v1, v83, vcc
	v_cvt_pk_bf16_f32 v236, v82, v83
	v_cvt_pk_bf16_f32 v237, v104, v85
	ds_read_b64 v[104:105], v148 offset:9472
	v_lshlrev_b64 v[82:83], 11, v[160:161]
	v_lshl_add_u64 v[82:83], s[4:5], 0, v[82:83]
	v_lshl_add_u64 v[82:83], v[82:83], 0, v[138:139]
	s_waitcnt lgkmcnt(0)
; __device__ __forceinline__ unsigned cvt_pk_bf16(float lo, float hi) { unsigned r; asm volatile("v_cvt_pk_bf16_f32 %0, %1, %2" : "=v"(r) : "v"(lo), "v"(hi)); return r; }
;     __device__ __forceinline__ void fused(f32x4 (&acc)[2][2][4][2], const Unit& u, int wr, int wc, int fr, int fq, PG8_LAS unsigned char* lds, int wid, int lane) const {
;     ...
;         const float qnan = __builtin_nanf("");
; #pragma unroll
;         for (int bj = 0; bj < 2; ++bj)
; #pragma unroll
;             for (int n = 0; n < 2; ++n) { const f32x4 gv = *(const f32x4*)(g + col0 + bj * HALF + n * 16), bv = *(const f32x4*)(b + col0 + bj * HALF + n * 16);
; #pragma unroll
;                 for (int ai = 0; ai < 2; ++ai)
; #pragma unroll
;                     for (int m = 0; m < 4; ++m) { const int r = ai * HALF + wr * 64 + m * 16 + fr; const f32x2v sr = S[r]; const size_t o = (size_t)(rowoff + u.pm * BM + r) * ldc + col0 + bj * HALF + n * 16;
;                         f32x4 v = (acc[ai][bj][m][n] - sr.x) * sr.y * gv + bv; if (bad) v = (f32x4){qnan, qnan, qnan, qnan};
;                         if (outf) *(f32x4*)(outf + o) = v; else { u32x2 w; w.x = cvt_pk_bf16(v[0], v[1]); w.y = cvt_pk_bf16(v[2], v[3]); *(u32x2*)(outb + o) = w; } } }
	v_sub_f32_e32 v39, v39, v104
	v_sub_f32_e32 v38, v38, v104
	v_sub_f32_e32 v41, v41, v104
	v_sub_f32_e32 v40, v40, v104
	v_pk_mul_f32 v[40:41], v[104:105], v[40:41] op_sel:[1,0]
	v_pk_mul_f32 v[38:39], v[104:105], v[38:39] op_sel:[1,0]
	v_add_u32_e32 v84, 0xa0, v146
	v_pk_fma_f32 v[38:39], v[130:131], v[38:39], v[134:135]
	v_pk_fma_f32 v[40:41], v[132:133], v[40:41], v[136:137]
	v_ashrrev_i32_e32 v85, 31, v84
	v_cndmask_b32_e32 v41, v1, v41, vcc
	v_cndmask_b32_e32 v38, v1, v38, vcc
	v_cndmask_b32_e32 v39, v1, v39, vcc
	v_cndmask_b32_e32 v104, v1, v40, vcc
	v_cvt_pk_bf16_f32 v238, v38, v39
	v_cvt_pk_bf16_f32 v239, v104, v41
	v_lshlrev_b64 v[38:39], 11, v[84:85]
	ds_read_b64 v[84:85], v148 offset:9600
	v_lshl_add_u64 v[38:39], s[4:5], 0, v[38:39]
	v_lshl_add_u64 v[38:39], v[38:39], 0, v[138:139]
	v_add_u32_e32 v40, 0xb0, v146
	s_waitcnt lgkmcnt(0)
	v_sub_f32_e32 v19, v19, v84
	v_sub_f32_e32 v18, v18, v84
	v_sub_f32_e32 v21, v21, v84
	v_sub_f32_e32 v20, v20, v84
	v_pk_mul_f32 v[18:19], v[84:85], v[18:19] op_sel:[1,0]
	v_pk_mul_f32 v[20:21], v[84:85], v[20:21] op_sel:[1,0]
	v_pk_fma_f32 v[18:19], v[130:131], v[18:19], v[134:135]
	v_ashrrev_i32_e32 v41, 31, v40
	v_pk_fma_f32 v[20:21], v[132:133], v[20:21], v[136:137]
	v_cndmask_b32_e32 v18, v1, v18, vcc
	v_cndmask_b32_e32 v19, v1, v19, vcc
	v_cndmask_b32_e32 v84, v1, v20, vcc
	v_cvt_pk_bf16_f32 v240, v18, v19
	v_lshlrev_b64 v[18:19], 11, v[40:41]
	v_lshl_add_u64 v[18:19], s[4:5], 0, v[18:19]
	v_cndmask_b32_e32 v21, v1, v21, vcc
	v_lshl_add_u64 v[18:19], v[18:19], 0, v[138:139]
	v_cvt_pk_bf16_f32 v241, v84, v21
	global_load_dwordx4 v[120:123], v[140:141], off offset:64
	global_load_dwordx4 v[124:127], v[142:143], off offset:64
	ds_read_b64 v[20:21], v148 offset:8192
	s_waitcnt lgkmcnt(0)
	v_sub_f32_e32 v41, v75, v20
	v_sub_f32_e32 v40, v74, v20
	v_sub_f32_e32 v75, v77, v20
	v_sub_f32_e32 v74, v76, v20
	v_pk_mul_f32 v[74:75], v[20:21], v[74:75] op_sel:[1,0]
	v_pk_mul_f32 v[20:21], v[20:21], v[40:41] op_sel:[1,0]
	s_waitcnt vmcnt(0)
	v_pk_fma_f32 v[40:41], v[122:123], v[74:75], v[126:127]
	v_pk_fma_f32 v[20:21], v[120:121], v[20:21], v[124:125]
	v_cndmask_b32_e32 v40, v1, v40, vcc
	v_cndmask_b32_e32 v41, v1, v41, vcc
	v_cndmask_b32_e32 v20, v1, v20, vcc
	v_cndmask_b32_e32 v21, v1, v21, vcc
	v_cvt_pk_bf16_f32 v246, v20, v21
	v_cvt_pk_bf16_f32 v247, v40, v41
	ds_read_b64 v[40:41], v148 offset:8320
	v_mov_b32_e32 v244, v226
	v_mov_b32_e32 v245, v227
	s_nop 1
	v_permlane16_swap_b32_e32 v244, v246
	v_permlane16_swap_b32_e32 v245, v247
	global_store_dwordx4 v[144:145], v[244:247], off
	s_waitcnt lgkmcnt(0)
	v_sub_f32_e32 v21, v95, v40
	v_sub_f32_e32 v20, v94, v40
	v_sub_f32_e32 v75, v97, v40
	v_sub_f32_e32 v74, v96, v40
	v_pk_mul_f32 v[74:75], v[40:41], v[74:75] op_sel:[1,0]
	v_pk_mul_f32 v[20:21], v[40:41], v[20:21] op_sel:[1,0]
	v_pk_fma_f32 v[40:41], v[122:123], v[74:75], v[126:127]
	v_pk_fma_f32 v[20:21], v[120:121], v[20:21], v[124:125]
	v_cndmask_b32_e32 v40, v1, v40, vcc
	v_cndmask_b32_e32 v41, v1, v41, vcc
	v_cndmask_b32_e32 v20, v1, v20, vcc
	v_cndmask_b32_e32 v21, v1, v21, vcc
	v_cvt_pk_bf16_f32 v250, v20, v21
	v_cvt_pk_bf16_f32 v251, v40, v41
	ds_read_b64 v[40:41], v148 offset:8448
	v_mov_b32_e32 v248, v228
	v_mov_b32_e32 v249, v229
	s_nop 1
	v_permlane16_swap_b32_e32 v248, v250
	v_permlane16_swap_b32_e32 v249, v251
	global_store_dwordx4 v[118:119], v[248:251], off
	s_waitcnt lgkmcnt(0)
	v_sub_f32_e32 v21, v107, v40
	v_sub_f32_e32 v20, v106, v40
	v_sub_f32_e32 v75, v109, v40
	v_sub_f32_e32 v74, v108, v40
	v_pk_mul_f32 v[74:75], v[40:41], v[74:75] op_sel:[1,0]
	v_pk_mul_f32 v[20:21], v[40:41], v[20:21] op_sel:[1,0]
	v_pk_fma_f32 v[40:41], v[122:123], v[74:75], v[126:127]
	v_pk_fma_f32 v[20:21], v[120:121], v[20:21], v[124:125]
	v_cndmask_b32_e32 v40, v1, v40, vcc
	v_cndmask_b32_e32 v41, v1, v41, vcc
	v_cndmask_b32_e32 v20, v1, v20, vcc
	v_cndmask_b32_e32 v21, v1, v21, vcc
	v_cvt_pk_bf16_f32 v246, v20, v21
	v_cvt_pk_bf16_f32 v247, v40, v41
	ds_read_b64 v[40:41], v148 offset:8576
	v_mov_b32_e32 v244, v230
	v_mov_b32_e32 v245, v231
	s_nop 1
	v_permlane16_swap_b32_e32 v244, v246
	v_permlane16_swap_b32_e32 v245, v247
	global_store_dwordx4 v[112:113], v[244:247], off
	s_waitcnt lgkmcnt(0)
	v_sub_f32_e32 v21, v115, v40
	v_sub_f32_e32 v20, v114, v40
	v_sub_f32_e32 v75, v117, v40
	v_sub_f32_e32 v74, v116, v40
	v_pk_mul_f32 v[74:75], v[40:41], v[74:75] op_sel:[1,0]
	v_pk_mul_f32 v[20:21], v[40:41], v[20:21] op_sel:[1,0]
	v_pk_fma_f32 v[40:41], v[122:123], v[74:75], v[126:127]
	v_pk_fma_f32 v[20:21], v[120:121], v[20:21], v[124:125]
	v_cndmask_b32_e32 v40, v1, v40, vcc
	v_cndmask_b32_e32 v41, v1, v41, vcc
	v_cndmask_b32_e32 v20, v1, v20, vcc
	v_cndmask_b32_e32 v21, v1, v21, vcc
	v_cvt_pk_bf16_f32 v250, v20, v21
	v_cvt_pk_bf16_f32 v251, v40, v41
	ds_read_b64 v[40:41], v148 offset:9216
	v_mov_b32_e32 v248, v232
	v_mov_b32_e32 v249, v233
	s_nop 1
	v_permlane16_swap_b32_e32 v248, v250
	v_permlane16_swap_b32_e32 v249, v251
	global_store_dwordx4 v[110:111], v[248:251], off
	s_waitcnt lgkmcnt(0)
	v_sub_f32_e32 v21, v99, v40
	v_sub_f32_e32 v20, v98, v40
	v_sub_f32_e32 v75, v101, v40
	v_sub_f32_e32 v74, v100, v40
	v_pk_mul_f32 v[74:75], v[40:41], v[74:75] op_sel:[1,0]
	v_pk_mul_f32 v[20:21], v[40:41], v[20:21] op_sel:[1,0]
	v_pk_fma_f32 v[40:41], v[122:123], v[74:75], v[126:127]
	v_pk_fma_f32 v[20:21], v[120:121], v[20:21], v[124:125]
	v_cndmask_b32_e32 v40, v1, v40, vcc
	v_cndmask_b32_e32 v41, v1, v41, vcc
	v_cndmask_b32_e32 v20, v1, v20, vcc
	v_cndmask_b32_e32 v21, v1, v21, vcc
	v_cvt_pk_bf16_f32 v246, v20, v21
	v_cvt_pk_bf16_f32 v247, v40, v41
	ds_read_b64 v[40:41], v148 offset:9344
	v_mov_b32_e32 v244, v234
	v_mov_b32_e32 v245, v235
	s_nop 1
	v_permlane16_swap_b32_e32 v244, v246
	v_permlane16_swap_b32_e32 v245, v247
	global_store_dwordx4 v[102:103], v[244:247], off
	s_waitcnt lgkmcnt(0)
; __device__ __forceinline__ unsigned cvt_pk_bf16(float lo, float hi) { unsigned r; asm volatile("v_cvt_pk_bf16_f32 %0, %1, %2" : "=v"(r) : "v"(lo), "v"(hi)); return r; }
;     __device__ __forceinline__ void fused(f32x4 (&acc)[2][2][4][2], const Unit& u, int wr, int wc, int fr, int fq, PG8_LAS unsigned char* lds, int wid, int lane) const {
;     ...
;         const float qnan = __builtin_nanf("");
; #pragma unroll
;         for (int bj = 0; bj < 2; ++bj)
; #pragma unroll
;             for (int n = 0; n < 2; ++n) { const f32x4 gv = *(const f32x4*)(g + col0 + bj * HALF + n * 16), bv = *(const f32x4*)(b + col0 + bj * HALF + n * 16);
; #pragma unroll
;                 for (int ai = 0; ai < 2; ++ai)
; #pragma unroll
;                     for (int m = 0; m < 4; ++m) { const int r = ai * HALF + wr * 64 + m * 16 + fr; const f32x2v sr = S[r]; const size_t o = (size_t)(rowoff + u.pm * BM + r) * ldc + col0 + bj * HALF + n * 16;
;                         f32x4 v = (acc[ai][bj][m][n] - sr.x) * sr.y * gv + bv; if (bad) v = (f32x4){qnan, qnan, qnan, qnan};
;                         if (outf) *(f32x4*)(outf + o) = v; else { u32x2 w; w.x = cvt_pk_bf16(v[0], v[1]); w.y = cvt_pk_bf16(v[2], v[3]); *(u32x2*)(outb + o) = w; } } }
	v_sub_f32_e32 v21, v79, v40
	v_sub_f32_e32 v20, v78, v40
	v_sub_f32_e32 v75, v81, v40
	v_sub_f32_e32 v74, v80, v40
	v_pk_mul_f32 v[74:75], v[40:41], v[74:75] op_sel:[1,0]
	v_pk_mul_f32 v[20:21], v[40:41], v[20:21] op_sel:[1,0]
	v_pk_fma_f32 v[40:41], v[122:123], v[74:75], v[126:127]
	v_pk_fma_f32 v[20:21], v[120:121], v[20:21], v[124:125]
	v_cndmask_b32_e32 v40, v1, v40, vcc
	v_cndmask_b32_e32 v41, v1, v41, vcc
	v_cndmask_b32_e32 v20, v1, v20, vcc
	v_cndmask_b32_e32 v21, v1, v21, vcc
	v_cvt_pk_bf16_f32 v250, v20, v21
	v_cvt_pk_bf16_f32 v251, v40, v41
	ds_read_b64 v[40:41], v148 offset:9472
	v_mov_b32_e32 v248, v236
	v_mov_b32_e32 v249, v237
	s_nop 1
	v_permlane16_swap_b32_e32 v248, v250
	v_permlane16_swap_b32_e32 v249, v251
	global_store_dwordx4 v[82:83], v[248:251], off
	s_waitcnt lgkmcnt(0)
	v_sub_f32_e32 v21, v35, v40
	v_sub_f32_e32 v20, v34, v40
	v_sub_f32_e32 v35, v37, v40
	v_sub_f32_e32 v34, v36, v40
	v_pk_mul_f32 v[34:35], v[40:41], v[34:35] op_sel:[1,0]
	v_pk_mul_f32 v[20:21], v[40:41], v[20:21] op_sel:[1,0]
	v_pk_fma_f32 v[34:35], v[122:123], v[34:35], v[126:127]
	v_pk_fma_f32 v[20:21], v[120:121], v[20:21], v[124:125]
	v_cndmask_b32_e32 v34, v1, v34, vcc
	v_cndmask_b32_e32 v35, v1, v35, vcc
	v_cndmask_b32_e32 v20, v1, v20, vcc
	v_cndmask_b32_e32 v21, v1, v21, vcc
	v_cvt_pk_bf16_f32 v246, v20, v21
	v_cvt_pk_bf16_f32 v247, v34, v35
	ds_read_b64 v[34:35], v148 offset:9600
	v_mov_b32_e32 v244, v238
	v_mov_b32_e32 v245, v239
	s_nop 1
	v_permlane16_swap_b32_e32 v244, v246
	v_permlane16_swap_b32_e32 v245, v247
	global_store_dwordx4 v[38:39], v[244:247], off
	s_waitcnt lgkmcnt(0)
	v_sub_f32_e32 v11, v11, v34
	v_sub_f32_e32 v10, v10, v34
	v_sub_f32_e32 v13, v13, v34
	v_sub_f32_e32 v12, v12, v34
	v_pk_mul_f32 v[10:11], v[34:35], v[10:11] op_sel:[1,0]
	v_pk_mul_f32 v[12:13], v[34:35], v[12:13] op_sel:[1,0]
	v_pk_fma_f32 v[10:11], v[120:121], v[10:11], v[124:125]
	v_pk_fma_f32 v[12:13], v[122:123], v[12:13], v[126:127]
	v_cndmask_b32_e32 v10, v1, v10, vcc
	v_cndmask_b32_e32 v11, v1, v11, vcc
	v_cndmask_b32_e32 v12, v1, v12, vcc
	v_cndmask_b32_e32 v13, v1, v13, vcc
	v_cvt_pk_bf16_f32 v250, v10, v11
	v_cvt_pk_bf16_f32 v251, v12, v13
	v_mov_b32_e32 v248, v240
	v_mov_b32_e32 v249, v241
	s_nop 1
	v_permlane16_swap_b32_e32 v248, v250
	v_permlane16_swap_b32_e32 v249, v251
	global_store_dwordx4 v[18:19], v[248:251], off
	global_load_dwordx4 v[10:13], v[140:141], off offset:512
	s_nop 0
	global_load_dwordx4 v[34:37], v[142:143], off offset:512
	ds_read_b64 v[20:21], v148 offset:8192
	s_waitcnt lgkmcnt(0)
	v_sub_f32_e32 v41, v47, v20
	v_sub_f32_e32 v40, v46, v20
	v_sub_f32_e32 v47, v49, v20
	v_sub_f32_e32 v46, v48, v20
	v_pk_mul_f32 v[46:47], v[20:21], v[46:47] op_sel:[1,0]
	v_pk_mul_f32 v[20:21], v[20:21], v[40:41] op_sel:[1,0]
	s_waitcnt vmcnt(0)
	v_pk_fma_f32 v[40:41], v[12:13], v[46:47], v[36:37]
	v_pk_fma_f32 v[20:21], v[10:11], v[20:21], v[34:35]
	v_cndmask_b32_e32 v40, v1, v40, vcc
	v_cndmask_b32_e32 v41, v1, v41, vcc
	v_cndmask_b32_e32 v20, v1, v20, vcc
	v_cndmask_b32_e32 v21, v1, v21, vcc
	v_cvt_pk_bf16_f32 v226, v20, v21
	v_cvt_pk_bf16_f32 v227, v40, v41
	ds_read_b64 v[40:41], v148 offset:8320
	s_waitcnt lgkmcnt(0)
	v_sub_f32_e32 v21, v55, v40
	v_sub_f32_e32 v20, v54, v40
	v_sub_f32_e32 v47, v57, v40
	v_sub_f32_e32 v46, v56, v40
	v_pk_mul_f32 v[46:47], v[40:41], v[46:47] op_sel:[1,0]
	v_pk_mul_f32 v[20:21], v[40:41], v[20:21] op_sel:[1,0]
	v_pk_fma_f32 v[40:41], v[12:13], v[46:47], v[36:37]
	v_pk_fma_f32 v[20:21], v[10:11], v[20:21], v[34:35]
	v_cndmask_b32_e32 v40, v1, v40, vcc
	v_cndmask_b32_e32 v41, v1, v41, vcc
	v_cndmask_b32_e32 v20, v1, v20, vcc
	v_cndmask_b32_e32 v21, v1, v21, vcc
	v_cvt_pk_bf16_f32 v228, v20, v21
	v_cvt_pk_bf16_f32 v229, v40, v41
	ds_read_b64 v[40:41], v148 offset:8448
	s_waitcnt lgkmcnt(0)
	v_sub_f32_e32 v21, v71, v40
	v_sub_f32_e32 v20, v70, v40
	v_sub_f32_e32 v47, v73, v40
	v_sub_f32_e32 v46, v72, v40
	v_pk_mul_f32 v[46:47], v[40:41], v[46:47] op_sel:[1,0]
	v_pk_mul_f32 v[20:21], v[40:41], v[20:21] op_sel:[1,0]
	v_pk_fma_f32 v[40:41], v[12:13], v[46:47], v[36:37]
	v_pk_fma_f32 v[20:21], v[10:11], v[20:21], v[34:35]
	v_cndmask_b32_e32 v40, v1, v40, vcc
	v_cndmask_b32_e32 v41, v1, v41, vcc
	v_cndmask_b32_e32 v20, v1, v20, vcc
	v_cndmask_b32_e32 v21, v1, v21, vcc
	v_cvt_pk_bf16_f32 v230, v20, v21
	v_cvt_pk_bf16_f32 v231, v40, v41
	ds_read_b64 v[40:41], v148 offset:8576
	s_waitcnt lgkmcnt(0)
	v_sub_f32_e32 v21, v87, v40
	v_sub_f32_e32 v20, v86, v40
	v_sub_f32_e32 v47, v89, v40
	v_sub_f32_e32 v46, v88, v40
	v_pk_mul_f32 v[46:47], v[40:41], v[46:47] op_sel:[1,0]
	v_pk_mul_f32 v[20:21], v[40:41], v[20:21] op_sel:[1,0]
	v_pk_fma_f32 v[40:41], v[12:13], v[46:47], v[36:37]
	v_pk_fma_f32 v[20:21], v[10:11], v[20:21], v[34:35]
	v_cndmask_b32_e32 v40, v1, v40, vcc
	v_cndmask_b32_e32 v41, v1, v41, vcc
	v_cndmask_b32_e32 v20, v1, v20, vcc
	v_cndmask_b32_e32 v21, v1, v21, vcc
	v_cvt_pk_bf16_f32 v232, v20, v21
	v_cvt_pk_bf16_f32 v233, v40, v41
	ds_read_b64 v[40:41], v148 offset:9216
	s_waitcnt lgkmcnt(0)
	v_sub_f32_e32 v21, v91, v40
	v_sub_f32_e32 v20, v90, v40
	v_sub_f32_e32 v47, v93, v40
	v_sub_f32_e32 v46, v92, v40
	v_pk_mul_f32 v[46:47], v[40:41], v[46:47] op_sel:[1,0]
	v_pk_mul_f32 v[20:21], v[40:41], v[20:21] op_sel:[1,0]
	v_pk_fma_f32 v[40:41], v[12:13], v[46:47], v[36:37]
	v_pk_fma_f32 v[20:21], v[10:11], v[20:21], v[34:35]
	v_cndmask_b32_e32 v40, v1, v40, vcc
	v_cndmask_b32_e32 v41, v1, v41, vcc
	v_cndmask_b32_e32 v20, v1, v20, vcc
	v_cndmask_b32_e32 v21, v1, v21, vcc
	v_cvt_pk_bf16_f32 v234, v20, v21
	v_cvt_pk_bf16_f32 v235, v40, v41
	ds_read_b64 v[40:41], v148 offset:9344
	s_waitcnt lgkmcnt(0)
; __device__ __forceinline__ unsigned cvt_pk_bf16(float lo, float hi) { unsigned r; asm volatile("v_cvt_pk_bf16_f32 %0, %1, %2" : "=v"(r) : "v"(lo), "v"(hi)); return r; }
;     __device__ __forceinline__ void fused(f32x4 (&acc)[2][2][4][2], const Unit& u, int wr, int wc, int fr, int fq, PG8_LAS unsigned char* lds, int wid, int lane) const {
;     ...
;         const float qnan = __builtin_nanf("");
; #pragma unroll
;         for (int bj = 0; bj < 2; ++bj)
; #pragma unroll
;             for (int n = 0; n < 2; ++n) { const f32x4 gv = *(const f32x4*)(g + col0 + bj * HALF + n * 16), bv = *(const f32x4*)(b + col0 + bj * HALF + n * 16);
; #pragma unroll
;                 for (int ai = 0; ai < 2; ++ai)
; #pragma unroll
;                     for (int m = 0; m < 4; ++m) { const int r = ai * HALF + wr * 64 + m * 16 + fr; const f32x2v sr = S[r]; const size_t o = (size_t)(rowoff + u.pm * BM + r) * ldc + col0 + bj * HALF + n * 16;
;                         f32x4 v = (acc[ai][bj][m][n] - sr.x) * sr.y * gv + bv; if (bad) v = (f32x4){qnan, qnan, qnan, qnan};
;                         if (outf) *(f32x4*)(outf + o) = v; else { u32x2 w; w.x = cvt_pk_bf16(v[0], v[1]); w.y = cvt_pk_bf16(v[2], v[3]); *(u32x2*)(outb + o) = w; } } }
	v_sub_f32_e32 v21, v63, v40
	v_sub_f32_e32 v20, v62, v40
	v_sub_f32_e32 v47, v65, v40
	v_sub_f32_e32 v46, v64, v40
	v_pk_mul_f32 v[46:47], v[40:41], v[46:47] op_sel:[1,0]
	v_pk_mul_f32 v[20:21], v[40:41], v[20:21] op_sel:[1,0]
	v_pk_fma_f32 v[40:41], v[12:13], v[46:47], v[36:37]
	v_pk_fma_f32 v[20:21], v[10:11], v[20:21], v[34:35]
	v_cndmask_b32_e32 v40, v1, v40, vcc
	v_cndmask_b32_e32 v41, v1, v41, vcc
	v_cndmask_b32_e32 v20, v1, v20, vcc
	v_cndmask_b32_e32 v21, v1, v21, vcc
	v_cvt_pk_bf16_f32 v236, v20, v21
	v_cvt_pk_bf16_f32 v237, v40, v41
	ds_read_b64 v[40:41], v148 offset:9472
	s_waitcnt lgkmcnt(0)
	v_sub_f32_e32 v21, v27, v40
	v_sub_f32_e32 v20, v26, v40
	v_sub_f32_e32 v27, v29, v40
	v_sub_f32_e32 v26, v28, v40
	v_pk_mul_f32 v[26:27], v[40:41], v[26:27] op_sel:[1,0]
	v_pk_mul_f32 v[20:21], v[40:41], v[20:21] op_sel:[1,0]
	v_pk_fma_f32 v[26:27], v[12:13], v[26:27], v[36:37]
	v_pk_fma_f32 v[20:21], v[10:11], v[20:21], v[34:35]
	v_cndmask_b32_e32 v26, v1, v26, vcc
	v_cndmask_b32_e32 v27, v1, v27, vcc
	v_cndmask_b32_e32 v20, v1, v20, vcc
	v_cndmask_b32_e32 v21, v1, v21, vcc
	v_cvt_pk_bf16_f32 v238, v20, v21
	v_cvt_pk_bf16_f32 v239, v26, v27
	ds_read_b64 v[26:27], v148 offset:9600
	s_waitcnt lgkmcnt(0)
	v_sub_f32_e32 v7, v7, v26
	v_sub_f32_e32 v6, v6, v26
	v_sub_f32_e32 v9, v9, v26
	v_sub_f32_e32 v8, v8, v26
	v_pk_mul_f32 v[6:7], v[26:27], v[6:7] op_sel:[1,0]
	v_pk_mul_f32 v[8:9], v[26:27], v[8:9] op_sel:[1,0]
	v_pk_fma_f32 v[6:7], v[10:11], v[6:7], v[34:35]
	v_pk_fma_f32 v[8:9], v[12:13], v[8:9], v[36:37]
	v_cndmask_b32_e32 v6, v1, v6, vcc
	v_cndmask_b32_e32 v7, v1, v7, vcc
	v_cndmask_b32_e32 v8, v1, v8, vcc
	v_cndmask_b32_e32 v9, v1, v9, vcc
	v_cvt_pk_bf16_f32 v240, v6, v7
	v_cvt_pk_bf16_f32 v241, v8, v9
	global_load_dwordx4 v[6:9], v[140:141], off offset:576
	s_nop 0
	global_load_dwordx4 v[10:13], v[142:143], off offset:576
	ds_read_b64 v[20:21], v148 offset:8192
	s_waitcnt lgkmcnt(0)
	v_sub_f32_e32 v15, v15, v20
	v_sub_f32_e32 v14, v14, v20
	v_sub_f32_e32 v17, v17, v20
	v_sub_f32_e32 v16, v16, v20
	v_pk_mul_f32 v[16:17], v[20:21], v[16:17] op_sel:[1,0]
	v_pk_mul_f32 v[14:15], v[20:21], v[14:15] op_sel:[1,0]
	s_waitcnt vmcnt(0)
	v_pk_fma_f32 v[16:17], v[8:9], v[16:17], v[12:13]
	v_pk_fma_f32 v[14:15], v[6:7], v[14:15], v[10:11]
	v_cndmask_b32_e32 v16, v1, v16, vcc
	v_cndmask_b32_e32 v17, v1, v17, vcc
	v_cndmask_b32_e32 v14, v1, v14, vcc
	v_cndmask_b32_e32 v15, v1, v15, vcc
	v_cvt_pk_bf16_f32 v246, v14, v15
	v_cvt_pk_bf16_f32 v247, v16, v17
	ds_read_b64 v[16:17], v148 offset:8320
	v_mov_b32_e32 v244, v226
	v_mov_b32_e32 v245, v227
	s_nop 1
	v_permlane16_swap_b32_e32 v244, v246
	v_permlane16_swap_b32_e32 v245, v247
	global_store_dwordx4 v[144:145], v[244:247], off offset:256
	s_waitcnt lgkmcnt(0)
	v_sub_f32_e32 v15, v31, v16
	v_sub_f32_e32 v14, v30, v16
	v_sub_f32_e32 v21, v33, v16
	v_sub_f32_e32 v20, v32, v16
	v_pk_mul_f32 v[20:21], v[16:17], v[20:21] op_sel:[1,0]
	v_pk_mul_f32 v[14:15], v[16:17], v[14:15] op_sel:[1,0]
	v_pk_fma_f32 v[16:17], v[8:9], v[20:21], v[12:13]
	v_pk_fma_f32 v[14:15], v[6:7], v[14:15], v[10:11]
	v_cndmask_b32_e32 v16, v1, v16, vcc
	v_cndmask_b32_e32 v17, v1, v17, vcc
	v_cndmask_b32_e32 v14, v1, v14, vcc
	v_cndmask_b32_e32 v15, v1, v15, vcc
	v_cvt_pk_bf16_f32 v250, v14, v15
	v_cvt_pk_bf16_f32 v251, v16, v17
	ds_read_b64 v[16:17], v148 offset:8448
	v_mov_b32_e32 v248, v228
	v_mov_b32_e32 v249, v229
	s_nop 1
	v_permlane16_swap_b32_e32 v248, v250
	v_permlane16_swap_b32_e32 v249, v251
	global_store_dwordx4 v[118:119], v[248:251], off offset:256
	s_waitcnt lgkmcnt(0)
	v_sub_f32_e32 v15, v43, v16
	v_sub_f32_e32 v14, v42, v16
	v_sub_f32_e32 v21, v45, v16
	v_sub_f32_e32 v20, v44, v16
	v_pk_mul_f32 v[20:21], v[16:17], v[20:21] op_sel:[1,0]
	v_pk_mul_f32 v[14:15], v[16:17], v[14:15] op_sel:[1,0]
	v_pk_fma_f32 v[16:17], v[8:9], v[20:21], v[12:13]
	v_pk_fma_f32 v[14:15], v[6:7], v[14:15], v[10:11]
	v_cndmask_b32_e32 v16, v1, v16, vcc
	v_cndmask_b32_e32 v17, v1, v17, vcc
	v_cndmask_b32_e32 v14, v1, v14, vcc
	v_cndmask_b32_e32 v15, v1, v15, vcc
	v_cvt_pk_bf16_f32 v246, v14, v15
	v_cvt_pk_bf16_f32 v247, v16, v17
	ds_read_b64 v[16:17], v148 offset:8576
	v_mov_b32_e32 v244, v230
	v_mov_b32_e32 v245, v231
	s_nop 1
	v_permlane16_swap_b32_e32 v244, v246
	v_permlane16_swap_b32_e32 v245, v247
	global_store_dwordx4 v[112:113], v[244:247], off offset:256
	s_waitcnt lgkmcnt(0)
; __device__ __forceinline__ unsigned cvt_pk_bf16(float lo, float hi) { unsigned r; asm volatile("v_cvt_pk_bf16_f32 %0, %1, %2" : "=v"(r) : "v"(lo), "v"(hi)); return r; }
;     __device__ __forceinline__ void fused(f32x4 (&acc)[2][2][4][2], const Unit& u, int wr, int wc, int fr, int fq, PG8_LAS unsigned char* lds, int wid, int lane) const {
;     ...
;         const float qnan = __builtin_nanf("");
; #pragma unroll
;         for (int bj = 0; bj < 2; ++bj)
; #pragma unroll
;             for (int n = 0; n < 2; ++n) { const f32x4 gv = *(const f32x4*)(g + col0 + bj * HALF + n * 16), bv = *(const f32x4*)(b + col0 + bj * HALF + n * 16);
; #pragma unroll
;                 for (int ai = 0; ai < 2; ++ai)
; #pragma unroll
;                     for (int m = 0; m < 4; ++m) { const int r = ai * HALF + wr * 64 + m * 16 + fr; const f32x2v sr = S[r]; const size_t o = (size_t)(rowoff + u.pm * BM + r) * ldc + col0 + bj * HALF + n * 16;
;                         f32x4 v = (acc[ai][bj][m][n] - sr.x) * sr.y * gv + bv; if (bad) v = (f32x4){qnan, qnan, qnan, qnan};
;                         if (outf) *(f32x4*)(outf + o) = v; else { u32x2 w; w.x = cvt_pk_bf16(v[0], v[1]); w.y = cvt_pk_bf16(v[2], v[3]); *(u32x2*)(outb + o) = w; } } }
	v_sub_f32_e32 v15, v51, v16
	v_sub_f32_e32 v14, v50, v16
	v_sub_f32_e32 v21, v53, v16
	v_sub_f32_e32 v20, v52, v16
	v_pk_mul_f32 v[20:21], v[16:17], v[20:21] op_sel:[1,0]
	v_pk_mul_f32 v[14:15], v[16:17], v[14:15] op_sel:[1,0]
	v_pk_fma_f32 v[16:17], v[8:9], v[20:21], v[12:13]
	v_pk_fma_f32 v[14:15], v[6:7], v[14:15], v[10:11]
	v_cndmask_b32_e32 v16, v1, v16, vcc
	v_cndmask_b32_e32 v17, v1, v17, vcc
	v_cndmask_b32_e32 v14, v1, v14, vcc
	v_cndmask_b32_e32 v15, v1, v15, vcc
	v_cvt_pk_bf16_f32 v250, v14, v15
	v_cvt_pk_bf16_f32 v251, v16, v17
	ds_read_b64 v[16:17], v148 offset:9216
	v_mov_b32_e32 v248, v232
	v_mov_b32_e32 v249, v233
	s_nop 1
	v_permlane16_swap_b32_e32 v248, v250
	v_permlane16_swap_b32_e32 v249, v251
	global_store_dwordx4 v[110:111], v[248:251], off offset:256
	s_waitcnt lgkmcnt(0)
	v_sub_f32_e32 v15, v67, v16
	v_sub_f32_e32 v14, v66, v16
	v_sub_f32_e32 v21, v69, v16
	v_sub_f32_e32 v20, v68, v16
	v_pk_mul_f32 v[20:21], v[16:17], v[20:21] op_sel:[1,0]
	v_pk_mul_f32 v[14:15], v[16:17], v[14:15] op_sel:[1,0]
	v_pk_fma_f32 v[16:17], v[8:9], v[20:21], v[12:13]
	v_pk_fma_f32 v[14:15], v[6:7], v[14:15], v[10:11]
	v_cndmask_b32_e32 v16, v1, v16, vcc
	v_cndmask_b32_e32 v17, v1, v17, vcc
	v_cndmask_b32_e32 v14, v1, v14, vcc
	v_cndmask_b32_e32 v15, v1, v15, vcc
	v_cvt_pk_bf16_f32 v246, v14, v15
	v_cvt_pk_bf16_f32 v247, v16, v17
	ds_read_b64 v[16:17], v148 offset:9344
	v_mov_b32_e32 v244, v234
	v_mov_b32_e32 v245, v235
	s_nop 1
	v_permlane16_swap_b32_e32 v244, v246
	v_permlane16_swap_b32_e32 v245, v247
	global_store_dwordx4 v[102:103], v[244:247], off offset:256
	s_waitcnt lgkmcnt(0)
	v_sub_f32_e32 v15, v59, v16
	v_sub_f32_e32 v14, v58, v16
	v_sub_f32_e32 v21, v61, v16
	v_sub_f32_e32 v20, v60, v16
	v_pk_mul_f32 v[20:21], v[16:17], v[20:21] op_sel:[1,0]
	v_pk_mul_f32 v[14:15], v[16:17], v[14:15] op_sel:[1,0]
	v_pk_fma_f32 v[16:17], v[8:9], v[20:21], v[12:13]
	v_pk_fma_f32 v[14:15], v[6:7], v[14:15], v[10:11]
	v_cndmask_b32_e32 v16, v1, v16, vcc
	v_cndmask_b32_e32 v17, v1, v17, vcc
	v_cndmask_b32_e32 v14, v1, v14, vcc
	v_cndmask_b32_e32 v15, v1, v15, vcc
	v_cvt_pk_bf16_f32 v250, v14, v15
	v_cvt_pk_bf16_f32 v251, v16, v17
	ds_read_b64 v[16:17], v148 offset:9472
	v_mov_b32_e32 v248, v236
	v_mov_b32_e32 v249, v237
	s_nop 1
	v_permlane16_swap_b32_e32 v248, v250
	v_permlane16_swap_b32_e32 v249, v251
	global_store_dwordx4 v[82:83], v[248:251], off offset:256
	s_waitcnt lgkmcnt(0)
	v_sub_f32_e32 v15, v23, v16
	v_sub_f32_e32 v14, v22, v16
	v_sub_f32_e32 v21, v25, v16
	v_sub_f32_e32 v20, v24, v16
	v_pk_mul_f32 v[20:21], v[16:17], v[20:21] op_sel:[1,0]
	v_pk_mul_f32 v[14:15], v[16:17], v[14:15] op_sel:[1,0]
	v_pk_fma_f32 v[16:17], v[8:9], v[20:21], v[12:13]
	v_pk_fma_f32 v[14:15], v[6:7], v[14:15], v[10:11]
	v_cndmask_b32_e32 v16, v1, v16, vcc
	v_cndmask_b32_e32 v17, v1, v17, vcc
	v_cndmask_b32_e32 v14, v1, v14, vcc
	v_cndmask_b32_e32 v15, v1, v15, vcc
	v_cvt_pk_bf16_f32 v246, v14, v15
	v_cvt_pk_bf16_f32 v247, v16, v17
	ds_read_b64 v[16:17], v148 offset:9600
	v_mov_b32_e32 v244, v238
	v_mov_b32_e32 v245, v239
	s_nop 1
	v_permlane16_swap_b32_e32 v244, v246
	v_permlane16_swap_b32_e32 v245, v247
	global_store_dwordx4 v[38:39], v[244:247], off offset:256
	s_waitcnt lgkmcnt(0)
	v_sub_f32_e32 v3, v3, v16
	v_sub_f32_e32 v2, v2, v16
	v_sub_f32_e32 v5, v5, v16
	v_sub_f32_e32 v4, v4, v16
	v_pk_mul_f32 v[2:3], v[16:17], v[2:3] op_sel:[1,0]
	v_pk_mul_f32 v[4:5], v[16:17], v[4:5] op_sel:[1,0]
	v_pk_fma_f32 v[2:3], v[6:7], v[2:3], v[10:11]
	v_pk_fma_f32 v[4:5], v[8:9], v[4:5], v[12:13]
	v_cndmask_b32_e32 v2, v1, v2, vcc
	v_cndmask_b32_e32 v4, v1, v4, vcc
	v_cndmask_b32_e32 v5, v1, v5, vcc
	v_cndmask_b32_e32 v1, v1, v3, vcc
	v_cvt_pk_bf16_f32 v250, v2, v1
	v_cvt_pk_bf16_f32 v251, v4, v5
	v_mov_b32_e32 v248, v240
	v_mov_b32_e32 v249, v241
	s_nop 1
	v_permlane16_swap_b32_e32 v248, v250
	v_permlane16_swap_b32_e32 v249, v251
	global_store_dwordx4 v[18:19], v[248:251], off offset:256
	v_sub_u32_e32 v138, v138, v252

; __device__ __forceinline__ unsigned cvt_pk_bf16(float lo, float hi) { unsigned r; asm volatile("v_cvt_pk_bf16_f32 %0, %1, %2" : "=v"(r) : "v"(lo), "v"(hi)); return r; }
;     __device__ __forceinline__ void fused(f32x4 (&acc)[2][2][4][2], const Unit& u, int wr, int wc, int fr, int fq, PG8_LAS unsigned char* lds, int wid, int lane) const {
;     ...
;         const float qnan = __builtin_nanf("");
; #pragma unroll
;         for (int bj = 0; bj < 2; ++bj)
; #pragma unroll
;             for (int n = 0; n < 2; ++n) { const f32x4 gv = *(const f32x4*)(g + col0 + bj * HALF + n * 16), bv = *(const f32x4*)(b + col0 + bj * HALF + n * 16);
; #pragma unroll
;                 for (int ai = 0; ai < 2; ++ai)
; #pragma unroll
;                     for (int m = 0; m < 4; ++m) { const int r = ai * HALF + wr * 64 + m * 16 + fr; const f32x2v sr = S[r]; const size_t o = (size_t)(rowoff + u.pm * BM + r) * ldc + col0 + bj * HALF + n * 16;
;                         f32x4 v = (acc[ai][bj][m][n] - sr.x) * sr.y * gv + bv; if (bad) v = (f32x4){qnan, qnan, qnan, qnan};
;                         if (outf) *(f32x4*)(outf + o) = v; else { u32x2 w; w.x = cvt_pk_bf16(v[0], v[1]); w.y = cvt_pk_bf16(v[2], v[3]); *(u32x2*)(outb + o) = w; } } }
.LBB0_1570:
	s_or_b64 exec, exec, s[6:7]
	v_and_b32_e32 v252, 16, v186
	v_lshrrev_b32_e32 v253, 1, v252
	v_add_u32_e32 v252, v252, v253
	v_add_u32_e32 v138, v138, v252
	v_lshlrev_b64 v[134:135], 2, v[130:131]
	s_waitcnt lgkmcnt(0)
	s_barrier
	v_lshl_add_u64 v[140:141], s[14:15], 0, v[134:135]
	v_lshl_add_u64 v[142:143], s[12:13], 0, v[134:135]
	global_load_dwordx4 v[130:133], v[140:141], off
	global_load_dwordx4 v[134:137], v[142:143], off
	v_lshl_add_u32 v146, v1, 3, 0
	ds_read_b64 v[148:149], v146 offset:8192
	v_add_u32_e32 v147, s0, v1
	v_mov_b32_e32 v1, 0x7fc00000
	s_waitcnt lgkmcnt(1)
	v_cmp_eq_u32_e32 vcc, 0, v144
	v_add_u32_e32 v150, 0x4000, v147
	s_waitcnt lgkmcnt(0)
	v_sub_f32_e32 v111, v111, v148
	v_sub_f32_e32 v110, v110, v148
	v_sub_f32_e32 v113, v113, v148
	v_sub_f32_e32 v112, v112, v148
	v_pk_mul_f32 v[112:113], v[148:149], v[112:113] op_sel:[1,0]
	v_pk_mul_f32 v[110:111], v[148:149], v[110:111] op_sel:[1,0]
	v_ashrrev_i32_e32 v151, 31, v150
	v_readlane_b32 s0, v254, 13
	v_lshlrev_b64 v[144:145], 11, v[150:151]
	v_readlane_b32 s1, v254, 14
	v_add_u32_e32 v152, 0x4010, v147
	v_ashrrev_i32_e32 v153, 31, v152
	v_lshl_add_u64 v[144:145], s[0:1], 0, v[144:145]
	v_lshl_add_u64 v[144:145], v[144:145], 0, v[138:139]
	v_add_u32_e32 v154, 0x4020, v147
	v_ashrrev_i32_e32 v155, 31, v154
	v_add_u32_e32 v156, 0x4030, v147
	v_ashrrev_i32_e32 v157, 31, v156
	v_add_u32_e32 v158, 0x4080, v147
	v_ashrrev_i32_e32 v159, 31, v158
	v_add_u32_e32 v160, 0x4090, v147
	v_ashrrev_i32_e32 v161, 31, v160
	s_waitcnt vmcnt(0)
	v_pk_fma_f32 v[110:111], v[130:131], v[110:111], v[134:135]
	v_pk_fma_f32 v[112:113], v[132:133], v[112:113], v[136:137]
	v_cndmask_b32_e32 v110, v1, v110, vcc
	v_cndmask_b32_e32 v112, v1, v112, vcc
	v_cndmask_b32_e32 v113, v1, v113, vcc
	v_cndmask_b32_e32 v111, v1, v111, vcc
	v_cvt_pk_bf16_f32 v226, v110, v111
	v_cvt_pk_bf16_f32 v227, v112, v113
	ds_read_b64 v[112:113], v146 offset:8320
	s_waitcnt lgkmcnt(0)
	v_sub_f32_e32 v111, v119, v112
	v_sub_f32_e32 v110, v118, v112
	v_sub_f32_e32 v119, v121, v112
	v_sub_f32_e32 v118, v120, v112
	v_pk_mul_f32 v[118:119], v[112:113], v[118:119] op_sel:[1,0]
	v_pk_mul_f32 v[110:111], v[112:113], v[110:111] op_sel:[1,0]
	v_pk_fma_f32 v[112:113], v[132:133], v[118:119], v[136:137]
	v_pk_fma_f32 v[110:111], v[130:131], v[110:111], v[134:135]
	v_cndmask_b32_e32 v112, v1, v112, vcc
	v_cndmask_b32_e32 v113, v1, v113, vcc
	v_cndmask_b32_e32 v110, v1, v110, vcc
	v_cndmask_b32_e32 v111, v1, v111, vcc
	v_cvt_pk_bf16_f32 v228, v110, v111
	v_cvt_pk_bf16_f32 v229, v112, v113
	ds_read_b64 v[112:113], v146 offset:8448
	v_lshlrev_b64 v[118:119], 11, v[152:153]
	v_lshl_add_u64 v[118:119], s[0:1], 0, v[118:119]
	v_lshl_add_u64 v[118:119], v[118:119], 0, v[138:139]
	s_waitcnt lgkmcnt(0)
	v_sub_f32_e32 v111, v127, v112
	v_sub_f32_e32 v110, v126, v112
	v_sub_f32_e32 v121, v129, v112
	v_sub_f32_e32 v120, v128, v112
	v_pk_mul_f32 v[110:111], v[112:113], v[110:111] op_sel:[1,0]
	v_pk_mul_f32 v[120:121], v[112:113], v[120:121] op_sel:[1,0]
	v_pk_fma_f32 v[110:111], v[130:131], v[110:111], v[134:135]
	v_pk_fma_f32 v[112:113], v[132:133], v[120:121], v[136:137]
	v_cndmask_b32_e32 v110, v1, v110, vcc
	v_cndmask_b32_e32 v111, v1, v111, vcc
	v_cndmask_b32_e32 v112, v1, v112, vcc
	v_cndmask_b32_e32 v113, v1, v113, vcc
	v_cvt_pk_bf16_f32 v230, v110, v111
	v_cvt_pk_bf16_f32 v231, v112, v113
	ds_read_b64 v[120:121], v146 offset:8576
	v_lshlrev_b64 v[112:113], 11, v[154:155]
	v_lshl_add_u64 v[112:113], s[0:1], 0, v[112:113]
	v_lshl_add_u64 v[112:113], v[112:113], 0, v[138:139]
	s_waitcnt lgkmcnt(0)
	v_sub_f32_e32 v111, v123, v120
	v_sub_f32_e32 v110, v122, v120
	v_sub_f32_e32 v123, v125, v120
	v_sub_f32_e32 v122, v124, v120
	v_pk_mul_f32 v[122:123], v[120:121], v[122:123] op_sel:[1,0]
	v_pk_mul_f32 v[110:111], v[120:121], v[110:111] op_sel:[1,0]
	v_pk_fma_f32 v[120:121], v[132:133], v[122:123], v[136:137]
	v_pk_fma_f32 v[110:111], v[130:131], v[110:111], v[134:135]
	v_cndmask_b32_e32 v122, v1, v120, vcc
	v_cndmask_b32_e32 v121, v1, v121, vcc
	v_cndmask_b32_e32 v110, v1, v110, vcc
	v_cndmask_b32_e32 v111, v1, v111, vcc
	v_cvt_pk_bf16_f32 v232, v110, v111
	v_cvt_pk_bf16_f32 v233, v122, v121
	ds_read_b64 v[122:123], v146 offset:9216
	v_lshlrev_b64 v[110:111], 11, v[156:157]
	v_lshl_add_u64 v[110:111], s[0:1], 0, v[110:111]
	v_lshl_add_u64 v[110:111], v[110:111], 0, v[138:139]
	s_waitcnt lgkmcnt(0)
	v_sub_f32_e32 v105, v105, v122
	v_sub_f32_e32 v104, v104, v122
	v_sub_f32_e32 v103, v103, v122
	v_sub_f32_e32 v102, v102, v122
	v_pk_mul_f32 v[104:105], v[122:123], v[104:105] op_sel:[1,0]
	v_pk_mul_f32 v[102:103], v[122:123], v[102:103] op_sel:[1,0]
	v_pk_fma_f32 v[104:105], v[132:133], v[104:105], v[136:137]
	v_pk_fma_f32 v[102:103], v[130:131], v[102:103], v[134:135]
	v_cndmask_b32_e32 v120, v1, v104, vcc
	v_cndmask_b32_e32 v105, v1, v105, vcc
	v_cndmask_b32_e32 v102, v1, v102, vcc
	v_cndmask_b32_e32 v103, v1, v103, vcc
	v_cvt_pk_bf16_f32 v234, v102, v103
	v_cvt_pk_bf16_f32 v235, v120, v105
	ds_read_b64 v[120:121], v146 offset:9344
	v_lshlrev_b64 v[102:103], 11, v[158:159]
	v_lshl_add_u64 v[102:103], s[0:1], 0, v[102:103]
	v_lshl_add_u64 v[102:103], v[102:103], 0, v[138:139]
	s_waitcnt lgkmcnt(0)
	v_sub_f32_e32 v85, v85, v120
	v_sub_f32_e32 v84, v84, v120
	v_sub_f32_e32 v83, v83, v120
	v_sub_f32_e32 v82, v82, v120
	v_pk_mul_f32 v[84:85], v[120:121], v[84:85] op_sel:[1,0]
	v_pk_mul_f32 v[82:83], v[120:121], v[82:83] op_sel:[1,0]
	v_pk_fma_f32 v[84:85], v[132:133], v[84:85], v[136:137]
	v_pk_fma_f32 v[82:83], v[130:131], v[82:83], v[134:135]
	v_cndmask_b32_e32 v104, v1, v84, vcc
	v_cndmask_b32_e32 v85, v1, v85, vcc
	v_cndmask_b32_e32 v82, v1, v82, vcc
	v_cndmask_b32_e32 v83, v1, v83, vcc
	v_cvt_pk_bf16_f32 v236, v82, v83
	v_cvt_pk_bf16_f32 v237, v104, v85
	ds_read_b64 v[104:105], v146 offset:9472
	v_lshlrev_b64 v[82:83], 11, v[160:161]
	v_lshl_add_u64 v[82:83], s[0:1], 0, v[82:83]
	v_lshl_add_u64 v[82:83], v[82:83], 0, v[138:139]
	s_waitcnt lgkmcnt(0)
; __device__ __forceinline__ unsigned cvt_pk_bf16(float lo, float hi) { unsigned r; asm volatile("v_cvt_pk_bf16_f32 %0, %1, %2" : "=v"(r) : "v"(lo), "v"(hi)); return r; }
;     __device__ __forceinline__ void fused(f32x4 (&acc)[2][2][4][2], const Unit& u, int wr, int wc, int fr, int fq, PG8_LAS unsigned char* lds, int wid, int lane) const {
;     ...
;         const float qnan = __builtin_nanf("");
; #pragma unroll
;         for (int bj = 0; bj < 2; ++bj)
; #pragma unroll
;             for (int n = 0; n < 2; ++n) { const f32x4 gv = *(const f32x4*)(g + col0 + bj * HALF + n * 16), bv = *(const f32x4*)(b + col0 + bj * HALF + n * 16);
; #pragma unroll
;                 for (int ai = 0; ai < 2; ++ai)
; #pragma unroll
;                     for (int m = 0; m < 4; ++m) { const int r = ai * HALF + wr * 64 + m * 16 + fr; const f32x2v sr = S[r]; const size_t o = (size_t)(rowoff + u.pm * BM + r) * ldc + col0 + bj * HALF + n * 16;
;                         f32x4 v = (acc[ai][bj][m][n] - sr.x) * sr.y * gv + bv; if (bad) v = (f32x4){qnan, qnan, qnan, qnan};
;                         if (outf) *(f32x4*)(outf + o) = v; else { u32x2 w; w.x = cvt_pk_bf16(v[0], v[1]); w.y = cvt_pk_bf16(v[2], v[3]); *(u32x2*)(outb + o) = w; } } }
	v_sub_f32_e32 v39, v39, v104
	v_sub_f32_e32 v38, v38, v104
	v_sub_f32_e32 v41, v41, v104
	v_sub_f32_e32 v40, v40, v104
	v_pk_mul_f32 v[40:41], v[104:105], v[40:41] op_sel:[1,0]
	v_pk_mul_f32 v[38:39], v[104:105], v[38:39] op_sel:[1,0]
	v_add_u32_e32 v84, 0x40a0, v147
	v_pk_fma_f32 v[38:39], v[130:131], v[38:39], v[134:135]
	v_pk_fma_f32 v[40:41], v[132:133], v[40:41], v[136:137]
	v_ashrrev_i32_e32 v85, 31, v84
	v_cndmask_b32_e32 v41, v1, v41, vcc
	v_cndmask_b32_e32 v38, v1, v38, vcc
	v_cndmask_b32_e32 v39, v1, v39, vcc
	v_cndmask_b32_e32 v104, v1, v40, vcc
	v_cvt_pk_bf16_f32 v238, v38, v39
	v_cvt_pk_bf16_f32 v239, v104, v41
	v_lshlrev_b64 v[38:39], 11, v[84:85]
	ds_read_b64 v[84:85], v146 offset:9600
	v_lshl_add_u64 v[38:39], s[0:1], 0, v[38:39]
	v_lshl_add_u64 v[38:39], v[38:39], 0, v[138:139]
	v_add_u32_e32 v40, 0x40b0, v147
	s_waitcnt lgkmcnt(0)
	v_sub_f32_e32 v19, v19, v84
	v_sub_f32_e32 v18, v18, v84
	v_sub_f32_e32 v21, v21, v84
	v_sub_f32_e32 v20, v20, v84
	v_pk_mul_f32 v[18:19], v[84:85], v[18:19] op_sel:[1,0]
	v_pk_mul_f32 v[20:21], v[84:85], v[20:21] op_sel:[1,0]
	v_pk_fma_f32 v[18:19], v[130:131], v[18:19], v[134:135]
	v_ashrrev_i32_e32 v41, 31, v40
	v_pk_fma_f32 v[20:21], v[132:133], v[20:21], v[136:137]
	v_cndmask_b32_e32 v18, v1, v18, vcc
	v_cndmask_b32_e32 v19, v1, v19, vcc
	v_cndmask_b32_e32 v84, v1, v20, vcc
	v_cvt_pk_bf16_f32 v240, v18, v19
	v_lshlrev_b64 v[18:19], 11, v[40:41]
	v_lshl_add_u64 v[18:19], s[0:1], 0, v[18:19]
	v_cndmask_b32_e32 v21, v1, v21, vcc
	v_lshl_add_u64 v[18:19], v[18:19], 0, v[138:139]
	v_cvt_pk_bf16_f32 v241, v84, v21
	global_load_dwordx4 v[120:123], v[140:141], off offset:64
	global_load_dwordx4 v[124:127], v[142:143], off offset:64
	ds_read_b64 v[20:21], v146 offset:8192
	s_waitcnt lgkmcnt(0)
	v_sub_f32_e32 v41, v75, v20
	v_sub_f32_e32 v40, v74, v20
	v_sub_f32_e32 v75, v77, v20
	v_sub_f32_e32 v74, v76, v20
	v_pk_mul_f32 v[74:75], v[20:21], v[74:75] op_sel:[1,0]
	v_pk_mul_f32 v[20:21], v[20:21], v[40:41] op_sel:[1,0]
	s_waitcnt vmcnt(0)
	v_pk_fma_f32 v[40:41], v[122:123], v[74:75], v[126:127]
	v_pk_fma_f32 v[20:21], v[120:121], v[20:21], v[124:125]
	v_cndmask_b32_e32 v40, v1, v40, vcc
	v_cndmask_b32_e32 v41, v1, v41, vcc
	v_cndmask_b32_e32 v20, v1, v20, vcc
	v_cndmask_b32_e32 v21, v1, v21, vcc
	v_cvt_pk_bf16_f32 v246, v20, v21
	v_cvt_pk_bf16_f32 v247, v40, v41
	ds_read_b64 v[40:41], v146 offset:8320
	v_mov_b32_e32 v244, v226
	v_mov_b32_e32 v245, v227
	s_nop 1
	v_permlane16_swap_b32_e32 v244, v246
	v_permlane16_swap_b32_e32 v245, v247
	global_store_dwordx4 v[144:145], v[244:247], off
	s_waitcnt lgkmcnt(0)
	v_sub_f32_e32 v21, v95, v40
	v_sub_f32_e32 v20, v94, v40
	v_sub_f32_e32 v75, v97, v40
	v_sub_f32_e32 v74, v96, v40
	v_pk_mul_f32 v[74:75], v[40:41], v[74:75] op_sel:[1,0]
	v_pk_mul_f32 v[20:21], v[40:41], v[20:21] op_sel:[1,0]
	v_pk_fma_f32 v[40:41], v[122:123], v[74:75], v[126:127]
	v_pk_fma_f32 v[20:21], v[120:121], v[20:21], v[124:125]
	v_cndmask_b32_e32 v40, v1, v40, vcc
	v_cndmask_b32_e32 v41, v1, v41, vcc
	v_cndmask_b32_e32 v20, v1, v20, vcc
	v_cndmask_b32_e32 v21, v1, v21, vcc
	v_cvt_pk_bf16_f32 v250, v20, v21
	v_cvt_pk_bf16_f32 v251, v40, v41
	ds_read_b64 v[40:41], v146 offset:8448
	v_mov_b32_e32 v248, v228
	v_mov_b32_e32 v249, v229
	s_nop 1
	v_permlane16_swap_b32_e32 v248, v250
	v_permlane16_swap_b32_e32 v249, v251
	global_store_dwordx4 v[118:119], v[248:251], off
	s_waitcnt lgkmcnt(0)
	v_sub_f32_e32 v21, v107, v40
	v_sub_f32_e32 v20, v106, v40
	v_sub_f32_e32 v75, v109, v40
	v_sub_f32_e32 v74, v108, v40
	v_pk_mul_f32 v[74:75], v[40:41], v[74:75] op_sel:[1,0]
	v_pk_mul_f32 v[20:21], v[40:41], v[20:21] op_sel:[1,0]
	v_pk_fma_f32 v[40:41], v[122:123], v[74:75], v[126:127]
	v_pk_fma_f32 v[20:21], v[120:121], v[20:21], v[124:125]
	v_cndmask_b32_e32 v40, v1, v40, vcc
	v_cndmask_b32_e32 v41, v1, v41, vcc
	v_cndmask_b32_e32 v20, v1, v20, vcc
	v_cndmask_b32_e32 v21, v1, v21, vcc
	v_cvt_pk_bf16_f32 v246, v20, v21
	v_cvt_pk_bf16_f32 v247, v40, v41
	ds_read_b64 v[40:41], v146 offset:8576
	v_mov_b32_e32 v244, v230
	v_mov_b32_e32 v245, v231
	s_nop 1
	v_permlane16_swap_b32_e32 v244, v246
	v_permlane16_swap_b32_e32 v245, v247
	global_store_dwordx4 v[112:113], v[244:247], off
	s_waitcnt lgkmcnt(0)
	v_sub_f32_e32 v21, v115, v40
	v_sub_f32_e32 v20, v114, v40
	v_sub_f32_e32 v75, v117, v40
	v_sub_f32_e32 v74, v116, v40
	v_pk_mul_f32 v[74:75], v[40:41], v[74:75] op_sel:[1,0]
	v_pk_mul_f32 v[20:21], v[40:41], v[20:21] op_sel:[1,0]
	v_pk_fma_f32 v[40:41], v[122:123], v[74:75], v[126:127]
	v_pk_fma_f32 v[20:21], v[120:121], v[20:21], v[124:125]
	v_cndmask_b32_e32 v40, v1, v40, vcc
	v_cndmask_b32_e32 v41, v1, v41, vcc
	v_cndmask_b32_e32 v20, v1, v20, vcc
	v_cndmask_b32_e32 v21, v1, v21, vcc
	v_cvt_pk_bf16_f32 v250, v20, v21
	v_cvt_pk_bf16_f32 v251, v40, v41
	ds_read_b64 v[40:41], v146 offset:9216
	v_mov_b32_e32 v248, v232
	v_mov_b32_e32 v249, v233
	s_nop 1
	v_permlane16_swap_b32_e32 v248, v250
	v_permlane16_swap_b32_e32 v249, v251
	global_store_dwordx4 v[110:111], v[248:251], off
	s_waitcnt lgkmcnt(0)
	v_sub_f32_e32 v21, v99, v40
	v_sub_f32_e32 v20, v98, v40
	v_sub_f32_e32 v75, v101, v40
	v_sub_f32_e32 v74, v100, v40
	v_pk_mul_f32 v[74:75], v[40:41], v[74:75] op_sel:[1,0]
	v_pk_mul_f32 v[20:21], v[40:41], v[20:21] op_sel:[1,0]
	v_pk_fma_f32 v[40:41], v[122:123], v[74:75], v[126:127]
	v_pk_fma_f32 v[20:21], v[120:121], v[20:21], v[124:125]
	v_cndmask_b32_e32 v40, v1, v40, vcc
	v_cndmask_b32_e32 v41, v1, v41, vcc
	v_cndmask_b32_e32 v20, v1, v20, vcc
	v_cndmask_b32_e32 v21, v1, v21, vcc
	v_cvt_pk_bf16_f32 v246, v20, v21
	v_cvt_pk_bf16_f32 v247, v40, v41
	ds_read_b64 v[40:41], v146 offset:9344
	v_mov_b32_e32 v244, v234
	v_mov_b32_e32 v245, v235
	s_nop 1
	v_permlane16_swap_b32_e32 v244, v246
	v_permlane16_swap_b32_e32 v245, v247
	global_store_dwordx4 v[102:103], v[244:247], off
	s_waitcnt lgkmcnt(0)
; __device__ __forceinline__ unsigned cvt_pk_bf16(float lo, float hi) { unsigned r; asm volatile("v_cvt_pk_bf16_f32 %0, %1, %2" : "=v"(r) : "v"(lo), "v"(hi)); return r; }
;     __device__ __forceinline__ void fused(f32x4 (&acc)[2][2][4][2], const Unit& u, int wr, int wc, int fr, int fq, PG8_LAS unsigned char* lds, int wid, int lane) const {
;     ...
;         const float qnan = __builtin_nanf("");
; #pragma unroll
;         for (int bj = 0; bj < 2; ++bj)
; #pragma unroll
;             for (int n = 0; n < 2; ++n) { const f32x4 gv = *(const f32x4*)(g + col0 + bj * HALF + n * 16), bv = *(const f32x4*)(b + col0 + bj * HALF + n * 16);
; #pragma unroll
;                 for (int ai = 0; ai < 2; ++ai)
; #pragma unroll
;                     for (int m = 0; m < 4; ++m) { const int r = ai * HALF + wr * 64 + m * 16 + fr; const f32x2v sr = S[r]; const size_t o = (size_t)(rowoff + u.pm * BM + r) * ldc + col0 + bj * HALF + n * 16;
;                         f32x4 v = (acc[ai][bj][m][n] - sr.x) * sr.y * gv + bv; if (bad) v = (f32x4){qnan, qnan, qnan, qnan};
;                         if (outf) *(f32x4*)(outf + o) = v; else { u32x2 w; w.x = cvt_pk_bf16(v[0], v[1]); w.y = cvt_pk_bf16(v[2], v[3]); *(u32x2*)(outb + o) = w; } } }
	v_sub_f32_e32 v21, v79, v40
	v_sub_f32_e32 v20, v78, v40
	v_sub_f32_e32 v75, v81, v40
	v_sub_f32_e32 v74, v80, v40
	v_pk_mul_f32 v[74:75], v[40:41], v[74:75] op_sel:[1,0]
	v_pk_mul_f32 v[20:21], v[40:41], v[20:21] op_sel:[1,0]
	v_pk_fma_f32 v[40:41], v[122:123], v[74:75], v[126:127]
	v_pk_fma_f32 v[20:21], v[120:121], v[20:21], v[124:125]
	v_cndmask_b32_e32 v40, v1, v40, vcc
	v_cndmask_b32_e32 v41, v1, v41, vcc
	v_cndmask_b32_e32 v20, v1, v20, vcc
	v_cndmask_b32_e32 v21, v1, v21, vcc
	v_cvt_pk_bf16_f32 v250, v20, v21
	v_cvt_pk_bf16_f32 v251, v40, v41
	ds_read_b64 v[40:41], v146 offset:9472
	v_mov_b32_e32 v248, v236
	v_mov_b32_e32 v249, v237
	s_nop 1
	v_permlane16_swap_b32_e32 v248, v250
	v_permlane16_swap_b32_e32 v249, v251
	global_store_dwordx4 v[82:83], v[248:251], off
	s_waitcnt lgkmcnt(0)
	v_sub_f32_e32 v21, v35, v40
	v_sub_f32_e32 v20, v34, v40
	v_sub_f32_e32 v35, v37, v40
	v_sub_f32_e32 v34, v36, v40
	v_pk_mul_f32 v[34:35], v[40:41], v[34:35] op_sel:[1,0]
	v_pk_mul_f32 v[20:21], v[40:41], v[20:21] op_sel:[1,0]
	v_pk_fma_f32 v[34:35], v[122:123], v[34:35], v[126:127]
	v_pk_fma_f32 v[20:21], v[120:121], v[20:21], v[124:125]
	v_cndmask_b32_e32 v34, v1, v34, vcc
	v_cndmask_b32_e32 v35, v1, v35, vcc
	v_cndmask_b32_e32 v20, v1, v20, vcc
	v_cndmask_b32_e32 v21, v1, v21, vcc
	v_cvt_pk_bf16_f32 v246, v20, v21
	v_cvt_pk_bf16_f32 v247, v34, v35
	ds_read_b64 v[34:35], v146 offset:9600
	v_mov_b32_e32 v244, v238
	v_mov_b32_e32 v245, v239
	s_nop 1
	v_permlane16_swap_b32_e32 v244, v246
	v_permlane16_swap_b32_e32 v245, v247
	global_store_dwordx4 v[38:39], v[244:247], off
	s_waitcnt lgkmcnt(0)
	v_sub_f32_e32 v11, v11, v34
	v_sub_f32_e32 v10, v10, v34
	v_sub_f32_e32 v13, v13, v34
	v_sub_f32_e32 v12, v12, v34
	v_pk_mul_f32 v[10:11], v[34:35], v[10:11] op_sel:[1,0]
	v_pk_mul_f32 v[12:13], v[34:35], v[12:13] op_sel:[1,0]
	v_pk_fma_f32 v[10:11], v[120:121], v[10:11], v[124:125]
	v_pk_fma_f32 v[12:13], v[122:123], v[12:13], v[126:127]
	v_cndmask_b32_e32 v10, v1, v10, vcc
	v_cndmask_b32_e32 v11, v1, v11, vcc
	v_cndmask_b32_e32 v12, v1, v12, vcc
	v_cndmask_b32_e32 v13, v1, v13, vcc
	v_cvt_pk_bf16_f32 v250, v10, v11
	v_cvt_pk_bf16_f32 v251, v12, v13
	v_mov_b32_e32 v248, v240
	v_mov_b32_e32 v249, v241
	s_nop 1
	v_permlane16_swap_b32_e32 v248, v250
	v_permlane16_swap_b32_e32 v249, v251
	global_store_dwordx4 v[18:19], v[248:251], off
	global_load_dwordx4 v[10:13], v[140:141], off offset:512
	s_nop 0
	global_load_dwordx4 v[34:37], v[142:143], off offset:512
	ds_read_b64 v[20:21], v146 offset:8192
	s_waitcnt lgkmcnt(0)
	v_sub_f32_e32 v41, v47, v20
	v_sub_f32_e32 v40, v46, v20
	v_sub_f32_e32 v47, v49, v20
	v_sub_f32_e32 v46, v48, v20
	v_pk_mul_f32 v[46:47], v[20:21], v[46:47] op_sel:[1,0]
	v_pk_mul_f32 v[20:21], v[20:21], v[40:41] op_sel:[1,0]
	s_waitcnt vmcnt(0)
	v_pk_fma_f32 v[40:41], v[12:13], v[46:47], v[36:37]
	v_pk_fma_f32 v[20:21], v[10:11], v[20:21], v[34:35]
	v_cndmask_b32_e32 v40, v1, v40, vcc
	v_cndmask_b32_e32 v41, v1, v41, vcc
	v_cndmask_b32_e32 v20, v1, v20, vcc
	v_cndmask_b32_e32 v21, v1, v21, vcc
	v_cvt_pk_bf16_f32 v226, v20, v21
	v_cvt_pk_bf16_f32 v227, v40, v41
	ds_read_b64 v[40:41], v146 offset:8320
	s_waitcnt lgkmcnt(0)
	v_sub_f32_e32 v21, v55, v40
	v_sub_f32_e32 v20, v54, v40
	v_sub_f32_e32 v47, v57, v40
	v_sub_f32_e32 v46, v56, v40
	v_pk_mul_f32 v[46:47], v[40:41], v[46:47] op_sel:[1,0]
	v_pk_mul_f32 v[20:21], v[40:41], v[20:21] op_sel:[1,0]
	v_pk_fma_f32 v[40:41], v[12:13], v[46:47], v[36:37]
	v_pk_fma_f32 v[20:21], v[10:11], v[20:21], v[34:35]
	v_cndmask_b32_e32 v40, v1, v40, vcc
	v_cndmask_b32_e32 v41, v1, v41, vcc
	v_cndmask_b32_e32 v20, v1, v20, vcc
	v_cndmask_b32_e32 v21, v1, v21, vcc
	v_cvt_pk_bf16_f32 v228, v20, v21
	v_cvt_pk_bf16_f32 v229, v40, v41
	ds_read_b64 v[40:41], v146 offset:8448
	s_waitcnt lgkmcnt(0)
	v_sub_f32_e32 v21, v71, v40
	v_sub_f32_e32 v20, v70, v40
	v_sub_f32_e32 v47, v73, v40
	v_sub_f32_e32 v46, v72, v40
	v_pk_mul_f32 v[46:47], v[40:41], v[46:47] op_sel:[1,0]
	v_pk_mul_f32 v[20:21], v[40:41], v[20:21] op_sel:[1,0]
	v_pk_fma_f32 v[40:41], v[12:13], v[46:47], v[36:37]
	v_pk_fma_f32 v[20:21], v[10:11], v[20:21], v[34:35]
	v_cndmask_b32_e32 v40, v1, v40, vcc
	v_cndmask_b32_e32 v41, v1, v41, vcc
	v_cndmask_b32_e32 v20, v1, v20, vcc
	v_cndmask_b32_e32 v21, v1, v21, vcc
	v_cvt_pk_bf16_f32 v230, v20, v21
	v_cvt_pk_bf16_f32 v231, v40, v41
	ds_read_b64 v[40:41], v146 offset:8576
	s_waitcnt lgkmcnt(0)
	v_sub_f32_e32 v21, v87, v40
	v_sub_f32_e32 v20, v86, v40
	v_sub_f32_e32 v47, v89, v40
	v_sub_f32_e32 v46, v88, v40
	v_pk_mul_f32 v[46:47], v[40:41], v[46:47] op_sel:[1,0]
	v_pk_mul_f32 v[20:21], v[40:41], v[20:21] op_sel:[1,0]
	v_pk_fma_f32 v[40:41], v[12:13], v[46:47], v[36:37]
	v_pk_fma_f32 v[20:21], v[10:11], v[20:21], v[34:35]
	v_cndmask_b32_e32 v40, v1, v40, vcc
	v_cndmask_b32_e32 v41, v1, v41, vcc
	v_cndmask_b32_e32 v20, v1, v20, vcc
	v_cndmask_b32_e32 v21, v1, v21, vcc
	v_cvt_pk_bf16_f32 v232, v20, v21
	v_cvt_pk_bf16_f32 v233, v40, v41
	ds_read_b64 v[40:41], v146 offset:9216
	s_waitcnt lgkmcnt(0)
	v_sub_f32_e32 v21, v91, v40
	v_sub_f32_e32 v20, v90, v40
	v_sub_f32_e32 v47, v93, v40
	v_sub_f32_e32 v46, v92, v40
	v_pk_mul_f32 v[46:47], v[40:41], v[46:47] op_sel:[1,0]
	v_pk_mul_f32 v[20:21], v[40:41], v[20:21] op_sel:[1,0]
	v_pk_fma_f32 v[40:41], v[12:13], v[46:47], v[36:37]
	v_pk_fma_f32 v[20:21], v[10:11], v[20:21], v[34:35]
	v_cndmask_b32_e32 v40, v1, v40, vcc
	v_cndmask_b32_e32 v41, v1, v41, vcc
	v_cndmask_b32_e32 v20, v1, v20, vcc
	v_cndmask_b32_e32 v21, v1, v21, vcc
	v_cvt_pk_bf16_f32 v234, v20, v21
	v_cvt_pk_bf16_f32 v235, v40, v41
	ds_read_b64 v[40:41], v146 offset:9344
	s_waitcnt lgkmcnt(0)
; __device__ __forceinline__ unsigned cvt_pk_bf16(float lo, float hi) { unsigned r; asm volatile("v_cvt_pk_bf16_f32 %0, %1, %2" : "=v"(r) : "v"(lo), "v"(hi)); return r; }
;     __device__ __forceinline__ void fused(f32x4 (&acc)[2][2][4][2], const Unit& u, int wr, int wc, int fr, int fq, PG8_LAS unsigned char* lds, int wid, int lane) const {
;     ...
;         const float qnan = __builtin_nanf("");
; #pragma unroll
;         for (int bj = 0; bj < 2; ++bj)
; #pragma unroll
;             for (int n = 0; n < 2; ++n) { const f32x4 gv = *(const f32x4*)(g + col0 + bj * HALF + n * 16), bv = *(const f32x4*)(b + col0 + bj * HALF + n * 16);
; #pragma unroll
;                 for (int ai = 0; ai < 2; ++ai)
; #pragma unroll
;                     for (int m = 0; m < 4; ++m) { const int r = ai * HALF + wr * 64 + m * 16 + fr; const f32x2v sr = S[r]; const size_t o = (size_t)(rowoff + u.pm * BM + r) * ldc + col0 + bj * HALF + n * 16;
;                         f32x4 v = (acc[ai][bj][m][n] - sr.x) * sr.y * gv + bv; if (bad) v = (f32x4){qnan, qnan, qnan, qnan};
;                         if (outf) *(f32x4*)(outf + o) = v; else { u32x2 w; w.x = cvt_pk_bf16(v[0], v[1]); w.y = cvt_pk_bf16(v[2], v[3]); *(u32x2*)(outb + o) = w; } } }
	v_sub_f32_e32 v21, v63, v40
	v_sub_f32_e32 v20, v62, v40
	v_sub_f32_e32 v47, v65, v40
	v_sub_f32_e32 v46, v64, v40
	v_pk_mul_f32 v[46:47], v[40:41], v[46:47] op_sel:[1,0]
	v_pk_mul_f32 v[20:21], v[40:41], v[20:21] op_sel:[1,0]
	v_pk_fma_f32 v[40:41], v[12:13], v[46:47], v[36:37]
	v_pk_fma_f32 v[20:21], v[10:11], v[20:21], v[34:35]
	v_cndmask_b32_e32 v40, v1, v40, vcc
	v_cndmask_b32_e32 v41, v1, v41, vcc
	v_cndmask_b32_e32 v20, v1, v20, vcc
	v_cndmask_b32_e32 v21, v1, v21, vcc
	v_cvt_pk_bf16_f32 v236, v20, v21
	v_cvt_pk_bf16_f32 v237, v40, v41
	ds_read_b64 v[40:41], v146 offset:9472
	s_waitcnt lgkmcnt(0)
	v_sub_f32_e32 v21, v27, v40
	v_sub_f32_e32 v20, v26, v40
	v_sub_f32_e32 v27, v29, v40
	v_sub_f32_e32 v26, v28, v40
	v_pk_mul_f32 v[26:27], v[40:41], v[26:27] op_sel:[1,0]
	v_pk_mul_f32 v[20:21], v[40:41], v[20:21] op_sel:[1,0]
	v_pk_fma_f32 v[26:27], v[12:13], v[26:27], v[36:37]
	v_pk_fma_f32 v[20:21], v[10:11], v[20:21], v[34:35]
	v_cndmask_b32_e32 v26, v1, v26, vcc
	v_cndmask_b32_e32 v27, v1, v27, vcc
	v_cndmask_b32_e32 v20, v1, v20, vcc
	v_cndmask_b32_e32 v21, v1, v21, vcc
	v_cvt_pk_bf16_f32 v238, v20, v21
	v_cvt_pk_bf16_f32 v239, v26, v27
	ds_read_b64 v[26:27], v146 offset:9600
	s_waitcnt lgkmcnt(0)
	v_sub_f32_e32 v7, v7, v26
	v_sub_f32_e32 v6, v6, v26
	v_sub_f32_e32 v9, v9, v26
	v_sub_f32_e32 v8, v8, v26
	v_pk_mul_f32 v[6:7], v[26:27], v[6:7] op_sel:[1,0]
	v_pk_mul_f32 v[8:9], v[26:27], v[8:9] op_sel:[1,0]
	v_pk_fma_f32 v[6:7], v[10:11], v[6:7], v[34:35]
	v_pk_fma_f32 v[8:9], v[12:13], v[8:9], v[36:37]
	v_cndmask_b32_e32 v6, v1, v6, vcc
	v_cndmask_b32_e32 v7, v1, v7, vcc
	v_cndmask_b32_e32 v8, v1, v8, vcc
	v_cndmask_b32_e32 v9, v1, v9, vcc
	v_cvt_pk_bf16_f32 v240, v6, v7
	v_cvt_pk_bf16_f32 v241, v8, v9
	global_load_dwordx4 v[6:9], v[140:141], off offset:576
	s_nop 0
	global_load_dwordx4 v[10:13], v[142:143], off offset:576
	ds_read_b64 v[20:21], v146 offset:8192
	s_waitcnt lgkmcnt(0)
	v_sub_f32_e32 v15, v15, v20
	v_sub_f32_e32 v14, v14, v20
	v_sub_f32_e32 v17, v17, v20
	v_sub_f32_e32 v16, v16, v20
	v_pk_mul_f32 v[16:17], v[20:21], v[16:17] op_sel:[1,0]
	v_pk_mul_f32 v[14:15], v[20:21], v[14:15] op_sel:[1,0]
	s_waitcnt vmcnt(0)
	v_pk_fma_f32 v[16:17], v[8:9], v[16:17], v[12:13]
	v_pk_fma_f32 v[14:15], v[6:7], v[14:15], v[10:11]
	v_cndmask_b32_e32 v16, v1, v16, vcc
	v_cndmask_b32_e32 v17, v1, v17, vcc
	v_cndmask_b32_e32 v14, v1, v14, vcc
	v_cndmask_b32_e32 v15, v1, v15, vcc
	v_cvt_pk_bf16_f32 v246, v14, v15
	v_cvt_pk_bf16_f32 v247, v16, v17
	ds_read_b64 v[16:17], v146 offset:8320
	v_mov_b32_e32 v244, v226
	v_mov_b32_e32 v245, v227
	s_nop 1
	v_permlane16_swap_b32_e32 v244, v246
	v_permlane16_swap_b32_e32 v245, v247
	global_store_dwordx4 v[144:145], v[244:247], off offset:256
	s_waitcnt lgkmcnt(0)
	v_sub_f32_e32 v15, v31, v16
	v_sub_f32_e32 v14, v30, v16
	v_sub_f32_e32 v21, v33, v16
	v_sub_f32_e32 v20, v32, v16
	v_pk_mul_f32 v[20:21], v[16:17], v[20:21] op_sel:[1,0]
	v_pk_mul_f32 v[14:15], v[16:17], v[14:15] op_sel:[1,0]
	v_pk_fma_f32 v[16:17], v[8:9], v[20:21], v[12:13]
	v_pk_fma_f32 v[14:15], v[6:7], v[14:15], v[10:11]
	v_cndmask_b32_e32 v16, v1, v16, vcc
	v_cndmask_b32_e32 v17, v1, v17, vcc
	v_cndmask_b32_e32 v14, v1, v14, vcc
	v_cndmask_b32_e32 v15, v1, v15, vcc
	v_cvt_pk_bf16_f32 v250, v14, v15
	v_cvt_pk_bf16_f32 v251, v16, v17
	ds_read_b64 v[16:17], v146 offset:8448
	v_mov_b32_e32 v248, v228
	v_mov_b32_e32 v249, v229
	s_nop 1
	v_permlane16_swap_b32_e32 v248, v250
	v_permlane16_swap_b32_e32 v249, v251
	global_store_dwordx4 v[118:119], v[248:251], off offset:256
	s_waitcnt lgkmcnt(0)
	v_sub_f32_e32 v15, v43, v16
	v_sub_f32_e32 v14, v42, v16
	v_sub_f32_e32 v21, v45, v16
	v_sub_f32_e32 v20, v44, v16
	v_pk_mul_f32 v[20:21], v[16:17], v[20:21] op_sel:[1,0]
	v_pk_mul_f32 v[14:15], v[16:17], v[14:15] op_sel:[1,0]
	v_pk_fma_f32 v[16:17], v[8:9], v[20:21], v[12:13]
	v_pk_fma_f32 v[14:15], v[6:7], v[14:15], v[10:11]
	v_cndmask_b32_e32 v16, v1, v16, vcc
	v_cndmask_b32_e32 v17, v1, v17, vcc
	v_cndmask_b32_e32 v14, v1, v14, vcc
	v_cndmask_b32_e32 v15, v1, v15, vcc
	v_cvt_pk_bf16_f32 v246, v14, v15
	v_cvt_pk_bf16_f32 v247, v16, v17
	ds_read_b64 v[16:17], v146 offset:8576
	v_mov_b32_e32 v244, v230
	v_mov_b32_e32 v245, v231
	s_nop 1
	v_permlane16_swap_b32_e32 v244, v246
	v_permlane16_swap_b32_e32 v245, v247
	global_store_dwordx4 v[112:113], v[244:247], off offset:256
	s_waitcnt lgkmcnt(0)
; __device__ __forceinline__ unsigned cvt_pk_bf16(float lo, float hi) { unsigned r; asm volatile("v_cvt_pk_bf16_f32 %0, %1, %2" : "=v"(r) : "v"(lo), "v"(hi)); return r; }
;     __device__ __forceinline__ void fused(f32x4 (&acc)[2][2][4][2], const Unit& u, int wr, int wc, int fr, int fq, PG8_LAS unsigned char* lds, int wid, int lane) const {
;     ...
;         const float qnan = __builtin_nanf("");
; #pragma unroll
;         for (int bj = 0; bj < 2; ++bj)
; #pragma unroll
;             for (int n = 0; n < 2; ++n) { const f32x4 gv = *(const f32x4*)(g + col0 + bj * HALF + n * 16), bv = *(const f32x4*)(b + col0 + bj * HALF + n * 16);
; #pragma unroll
;                 for (int ai = 0; ai < 2; ++ai)
; #pragma unroll
;                     for (int m = 0; m < 4; ++m) { const int r = ai * HALF + wr * 64 + m * 16 + fr; const f32x2v sr = S[r]; const size_t o = (size_t)(rowoff + u.pm * BM + r) * ldc + col0 + bj * HALF + n * 16;
;                         f32x4 v = (acc[ai][bj][m][n] - sr.x) * sr.y * gv + bv; if (bad) v = (f32x4){qnan, qnan, qnan, qnan};
;                         if (outf) *(f32x4*)(outf + o) = v; else { u32x2 w; w.x = cvt_pk_bf16(v[0], v[1]); w.y = cvt_pk_bf16(v[2], v[3]); *(u32x2*)(outb + o) = w; } } }
	v_sub_f32_e32 v15, v51, v16
	v_sub_f32_e32 v14, v50, v16
	v_sub_f32_e32 v21, v53, v16
	v_sub_f32_e32 v20, v52, v16
	v_pk_mul_f32 v[20:21], v[16:17], v[20:21] op_sel:[1,0]
	v_pk_mul_f32 v[14:15], v[16:17], v[14:15] op_sel:[1,0]
	v_pk_fma_f32 v[16:17], v[8:9], v[20:21], v[12:13]
	v_pk_fma_f32 v[14:15], v[6:7], v[14:15], v[10:11]
	v_cndmask_b32_e32 v16, v1, v16, vcc
	v_cndmask_b32_e32 v17, v1, v17, vcc
	v_cndmask_b32_e32 v14, v1, v14, vcc
	v_cndmask_b32_e32 v15, v1, v15, vcc
	v_cvt_pk_bf16_f32 v250, v14, v15
	v_cvt_pk_bf16_f32 v251, v16, v17
	ds_read_b64 v[16:17], v146 offset:9216
	v_mov_b32_e32 v248, v232
	v_mov_b32_e32 v249, v233
	s_nop 1
	v_permlane16_swap_b32_e32 v248, v250
	v_permlane16_swap_b32_e32 v249, v251
	global_store_dwordx4 v[110:111], v[248:251], off offset:256
	s_waitcnt lgkmcnt(0)
	v_sub_f32_e32 v15, v67, v16
	v_sub_f32_e32 v14, v66, v16
	v_sub_f32_e32 v21, v69, v16
	v_sub_f32_e32 v20, v68, v16
	v_pk_mul_f32 v[20:21], v[16:17], v[20:21] op_sel:[1,0]
	v_pk_mul_f32 v[14:15], v[16:17], v[14:15] op_sel:[1,0]
	v_pk_fma_f32 v[16:17], v[8:9], v[20:21], v[12:13]
	v_pk_fma_f32 v[14:15], v[6:7], v[14:15], v[10:11]
	v_cndmask_b32_e32 v16, v1, v16, vcc
	v_cndmask_b32_e32 v17, v1, v17, vcc
	v_cndmask_b32_e32 v14, v1, v14, vcc
	v_cndmask_b32_e32 v15, v1, v15, vcc
	v_cvt_pk_bf16_f32 v246, v14, v15
	v_cvt_pk_bf16_f32 v247, v16, v17
	ds_read_b64 v[16:17], v146 offset:9344
	v_mov_b32_e32 v244, v234
	v_mov_b32_e32 v245, v235
	s_nop 1
	v_permlane16_swap_b32_e32 v244, v246
	v_permlane16_swap_b32_e32 v245, v247
	global_store_dwordx4 v[102:103], v[244:247], off offset:256
	s_waitcnt lgkmcnt(0)
	v_sub_f32_e32 v15, v59, v16
	v_sub_f32_e32 v14, v58, v16
	v_sub_f32_e32 v21, v61, v16
	v_sub_f32_e32 v20, v60, v16
	v_pk_mul_f32 v[20:21], v[16:17], v[20:21] op_sel:[1,0]
	v_pk_mul_f32 v[14:15], v[16:17], v[14:15] op_sel:[1,0]
	v_pk_fma_f32 v[16:17], v[8:9], v[20:21], v[12:13]
	v_pk_fma_f32 v[14:15], v[6:7], v[14:15], v[10:11]
	v_cndmask_b32_e32 v16, v1, v16, vcc
	v_cndmask_b32_e32 v17, v1, v17, vcc
	v_cndmask_b32_e32 v14, v1, v14, vcc
	v_cndmask_b32_e32 v15, v1, v15, vcc
	v_cvt_pk_bf16_f32 v250, v14, v15
	v_cvt_pk_bf16_f32 v251, v16, v17
	ds_read_b64 v[16:17], v146 offset:9472
	v_mov_b32_e32 v248, v236
	v_mov_b32_e32 v249, v237
	s_nop 1
	v_permlane16_swap_b32_e32 v248, v250
	v_permlane16_swap_b32_e32 v249, v251
	global_store_dwordx4 v[82:83], v[248:251], off offset:256
	s_waitcnt lgkmcnt(0)
	v_sub_f32_e32 v15, v23, v16
	v_sub_f32_e32 v14, v22, v16
	v_sub_f32_e32 v21, v25, v16
	v_sub_f32_e32 v20, v24, v16
	v_pk_mul_f32 v[20:21], v[16:17], v[20:21] op_sel:[1,0]
	v_pk_mul_f32 v[14:15], v[16:17], v[14:15] op_sel:[1,0]
	v_pk_fma_f32 v[16:17], v[8:9], v[20:21], v[12:13]
	v_pk_fma_f32 v[14:15], v[6:7], v[14:15], v[10:11]
	v_cndmask_b32_e32 v16, v1, v16, vcc
	v_cndmask_b32_e32 v17, v1, v17, vcc
	v_cndmask_b32_e32 v14, v1, v14, vcc
	v_cndmask_b32_e32 v15, v1, v15, vcc
	v_cvt_pk_bf16_f32 v246, v14, v15
	v_cvt_pk_bf16_f32 v247, v16, v17
	ds_read_b64 v[16:17], v146 offset:9600
	v_mov_b32_e32 v244, v238
	v_mov_b32_e32 v245, v239
	s_nop 1
	v_permlane16_swap_b32_e32 v244, v246
	v_permlane16_swap_b32_e32 v245, v247
	global_store_dwordx4 v[38:39], v[244:247], off offset:256
	s_waitcnt lgkmcnt(0)
	v_sub_f32_e32 v3, v3, v16
	v_sub_f32_e32 v2, v2, v16
	v_sub_f32_e32 v5, v5, v16
	v_sub_f32_e32 v4, v4, v16
	v_pk_mul_f32 v[2:3], v[16:17], v[2:3] op_sel:[1,0]
	v_pk_mul_f32 v[4:5], v[16:17], v[4:5] op_sel:[1,0]
	v_pk_fma_f32 v[2:3], v[6:7], v[2:3], v[10:11]
	v_pk_fma_f32 v[4:5], v[8:9], v[4:5], v[12:13]
	v_cndmask_b32_e32 v2, v1, v2, vcc
	v_cndmask_b32_e32 v4, v1, v4, vcc
	v_cndmask_b32_e32 v5, v1, v5, vcc
	v_cndmask_b32_e32 v1, v1, v3, vcc
	v_cvt_pk_bf16_f32 v250, v2, v1
	v_cvt_pk_bf16_f32 v251, v4, v5
	v_mov_b32_e32 v248, v240
	v_mov_b32_e32 v249, v241
	s_nop 1
	v_permlane16_swap_b32_e32 v248, v250
	v_permlane16_swap_b32_e32 v249, v251
	global_store_dwordx4 v[18:19], v[248:251], off offset:256
	v_sub_u32_e32 v138, v138, v252
